# generalized snake MFMA order in all 28 GEMM loop phases (symbolically verified), chains elsewhere, P16 warm-up
# speedup vs baseline: 1.0040x; 1.0040x over previous
;     __device__ __forceinline__ bool next(int i, Unit& u) const { if (i >= count) return false; const int L = first + i; u.pm = L / nN; u.pn = L % nN; return true; }
; #define PG8_STAGE(bufoff, gbase, voff) do { if constexpr (ABL & 1) break; glds16s<(bufoff)>((voff)[0], (const void*)(gbase), ldsbw); glds16s<(bufoff) + 8192>((voff)[1], (const void*)(gbase), ldsbw); } while (0)
; #define PG8_LDA(dst, b, h) do { if constexpr (ABL & 4) break; _Pragma("unroll") for (int m = 0; m < 4; ++m) _Pragma("unroll") for (int k = 0; k < 2; ++k) dst[m][k] = *(const LAS f16x8*)(lds + PG8_SA(b, h) + aoff + m * 2048 + k * 1024); } while (0)
; #define PG8_LDB(dst, b, h) do { if constexpr (ABL & 4) break; _Pragma("unroll") for (int n = 0; n < 2; ++n) _Pragma("unroll") for (int k = 0; k < 2; ++k) dst[n][k] = *(const LAS f16x8*)(lds + PG8_SB(b, h) + boff + n * 2048 + k * 1024); } while (0)
; #define PG8_MMAF(ai, bj, At, Bt) do { if (t == 0) PG8_MMA0(ai, bj, At, Bt); else PG8_MMA(ai, bj, At, Bt); } while (0)
; #define PG8_WAIT_V(n) asm volatile("s_waitcnt vmcnt(" #n ")" ::: "memory")
; #define PG8_BAR __builtin_amdgcn_s_barrier()
;     ...
;         const bool has_next = S.next(ui + 1, nxt);
;         const char* nA = has_next ? (const char*)g.A + (size_t)nxt.pm * tstep : cA; const char* nB = has_next ? (const char*)g.Bt + (size_t)nxt.pn * tstep : cB;
;         for (int t = 0; t < nt; t += 2) {
;             const bool last = (t == nt - 2);
;             const char* a1 = cA + (size_t)(t + 1) * kstep;
;             const char* a2 = last ? nA : cA + (size_t)(t + 2) * kstep; const char* b2 = last ? nB : cB + (size_t)(t + 2) * kstep;
;             const char* a3 = a2 + kstep; const char* b3 = b2 + kstep;
;             if (last && has_next) S.a_ready(nxt);
;             if constexpr (SP2) {
;             PG8_LDB(B0, 0, 0); PG8_LDB(B1, 0, 1); PG8_SCHED; PG8_LDA(At, 0, 0); PG8_STAGE(PG8_SA(1, 1), a1 + hstep, voffA);
;             PG8_WAIT_V(8); PG8_WAIT_L(0); PG8_BAR; PG8_MMAF(0, 0, At, B0); PG8_MMAF(0, 1, At, B1); PG8_BAR; PG8_SCHED;
;             const bool fin = last && !has_next;
;             PG8_LDA(At, 0, 1); if (!fin) { PG8_STAGE(PG8_SB(0, 0), b2, voffB); PG8_STAGE(PG8_SB(0, 1), b2 + hstep, voffB); PG8_STAGE(PG8_SA(0, 0), a2, voffA); }
;             if (!fin) PG8_WAIT_V(8); else PG8_WAIT_V(2); PG8_WAIT_L(0); PG8_BAR; PG8_MMAF(1, 0, At, B0); PG8_MMAF(1, 1, At, B1); PG8_BAR; PG8_SCHED;
.LBB0_229:
	s_ashr_i32 s53, s52, 31
	s_lshl_b64 s[8:9], s[52:53], 19
	s_add_u32 s54, s74, s8
	s_addc_u32 s55, s75, s9
	s_and_b64 s[8:9], exec, s[4:5]
	ds_read_b128 v[2:5], v236
	ds_read_b128 v[6:9], v236 offset:1024
	ds_read_b128 v[10:13], v236 offset:2048
	ds_read_b128 v[14:17], v236 offset:3072
	ds_read_b128 v[18:21], v237
	ds_read_b128 v[22:25], v237 offset:1024
	ds_read_b128 v[26:29], v237 offset:2048
	ds_read_b128 v[30:33], v237 offset:3072
	s_cselect_b32 s11, s63, s55
	s_cselect_b32 s35, s62, s54
	s_ashr_i32 s1, s0, 31
	s_lshl_b64 s[8:9], s[0:1], 19
	s_add_u32 s56, s90, s8
	s_addc_u32 s57, s91, s9
	s_and_b64 s[8:9], exec, s[4:5]
	s_cselect_b32 s1, s7, s57
	s_cselect_b32 s46, s6, s56
	s_add_u32 s8, s62, 0x100
	s_addc_u32 s9, s63, 0
	s_add_u32 s64, s6, 0x100
	s_addc_u32 s65, s7, 0
	s_add_u32 s24, s62, 0x180
	s_addc_u32 s25, s63, 0
	ds_read_b128 v[34:37], v238
	ds_read_b128 v[38:41], v238 offset:1024
	ds_read_b128 v[42:45], v238 offset:2048
	ds_read_b128 v[46:49], v238 offset:3072
	ds_read_b128 v[50:53], v238 offset:4096
	ds_read_b128 v[54:57], v238 offset:5120
	ds_read_b128 v[58:61], v238 offset:6144
	ds_read_b128 v[62:65], v238 offset:7168
	s_add_u32 s26, s6, 0x180
	s_addc_u32 s27, s7, 0
	s_add_u32 s76, s62, 0x40080
	s_addc_u32 s77, s63, 0
	s_add_u32 m0, s28, 0xc000
	s_nop 0
	global_load_lds_dwordx4 v232, s[76:77]
	s_nop 0
	s_add_u32 m0, s28, 0xe000
	s_nop 0
	global_load_lds_dwordx4 v234, s[76:77]
	s_waitcnt vmcnt(8)
	s_waitcnt lgkmcnt(0)
	s_barrier
	v_mfma_f32_16x16x32_f16 v[86:89], v[10:13], v[50:53], 0
	s_setprio 1
	v_mfma_f32_16x16x32_f16 v[90:93], v[14:17], v[54:57], v[86:89]
	v_mfma_f32_16x16x32_f16 v[86:89], v[2:5], v[58:61], 0
	v_mfma_f32_16x16x32_f16 v[94:97], v[6:9], v[62:65], v[86:89]
	v_mfma_f32_16x16x32_f16 v[66:69], v[2:5], v[34:37], 0
	v_mfma_f32_16x16x32_f16 v[66:69], v[6:9], v[38:41], v[66:69]
	v_mfma_f32_16x16x32_f16 v[70:73], v[10:13], v[34:37], 0
	v_mfma_f32_16x16x32_f16 v[70:73], v[14:17], v[38:41], v[70:73]
	v_mfma_f32_16x16x32_f16 v[74:77], v[2:5], v[42:45], 0
	v_mfma_f32_16x16x32_f16 v[74:77], v[6:9], v[46:49], v[74:77]
	v_mfma_f32_16x16x32_f16 v[78:81], v[10:13], v[42:45], 0
	v_mfma_f32_16x16x32_f16 v[78:81], v[14:17], v[46:49], v[78:81]
	v_mfma_f32_16x16x32_f16 v[82:85], v[2:5], v[50:53], 0
	v_mfma_f32_16x16x32_f16 v[82:85], v[6:9], v[54:57], v[82:85]
	v_mfma_f32_16x16x32_f16 v[86:89], v[10:13], v[58:61], 0
	v_mfma_f32_16x16x32_f16 v[106:109], v[14:17], v[62:65], v[86:89]
	v_mfma_f32_16x16x32_f16 v[86:89], v[18:21], v[34:37], 0
	v_mfma_f32_16x16x32_f16 v[34:37], v[26:29], v[34:37], 0
	v_mfma_f32_16x16x32_f16 v[110:113], v[22:25], v[38:41], v[86:89]
	v_mfma_f32_16x16x32_f16 v[34:37], v[30:33], v[38:41], v[34:37]
	v_mfma_f32_16x16x32_f16 v[38:41], v[18:21], v[42:45], 0
	v_mfma_f32_16x16x32_f16 v[42:45], v[26:29], v[42:45], 0
	v_mfma_f32_16x16x32_f16 v[38:41], v[22:25], v[46:49], v[38:41]
	v_mfma_f32_16x16x32_f16 v[42:45], v[30:33], v[46:49], v[42:45]
	v_mfma_f32_16x16x32_f16 v[46:49], v[18:21], v[50:53], 0
	v_mfma_f32_16x16x32_f16 v[50:53], v[26:29], v[50:53], 0
	v_mfma_f32_16x16x32_f16 v[46:49], v[22:25], v[54:57], v[46:49]
	v_mfma_f32_16x16x32_f16 v[54:57], v[30:33], v[54:57], v[50:53]
	v_mfma_f32_16x16x32_f16 v[50:53], v[18:21], v[58:61], 0
	v_mfma_f32_16x16x32_f16 v[130:133], v[22:25], v[62:65], v[50:53]
	v_mfma_f32_16x16x32_f16 v[50:53], v[26:29], v[58:61], 0
	v_mfma_f32_16x16x32_f16 v[62:65], v[30:33], v[62:65], v[50:53]
	s_barrier
	s_setprio 0
	s_nop 4
	ds_read_b128 v[50:53], v238 offset:16384
	ds_read_b128 v[58:61], v238 offset:17408
	ds_read_b128 v[86:89], v238 offset:18432
	ds_read_b128 v[98:101], v238 offset:19456
	ds_read_b128 v[102:105], v238 offset:20480
	ds_read_b128 v[114:117], v238 offset:21504
	ds_read_b128 v[118:121], v238 offset:22528
	ds_read_b128 v[122:125], v238 offset:23552
	s_add_u32 m0, s28, 0x10000
	s_nop 0
	global_load_lds_dwordx4 v233, s[64:65]
	s_nop 0
	s_add_u32 m0, s28, 0x12000
	s_nop 0
	global_load_lds_dwordx4 v235, s[64:65]
	s_add_u32 s64, s6, 0x40100
	s_addc_u32 s65, s7, 0
	s_add_u32 m0, s28, 0x14000
	s_nop 0
	global_load_lds_dwordx4 v233, s[64:65]
	s_nop 0
	s_add_u32 m0, s28, 0x16000
	s_nop 0
	global_load_lds_dwordx4 v235, s[64:65]
	s_nop 0
	s_add_u32 m0, s28, 0
	s_nop 0
	global_load_lds_dwordx4 v232, s[8:9]
	s_nop 0
	s_add_u32 m0, s28, 0x2000
	s_nop 0
	global_load_lds_dwordx4 v234, s[8:9]
	s_waitcnt vmcnt(8)
	s_waitcnt lgkmcnt(0)
	s_barrier
	v_mfma_f32_16x16x32_f16 v[126:129], v[2:5], v[50:53], 0
	s_setprio 1
	v_mfma_f32_16x16x32_f16 v[134:137], v[6:9], v[58:61], v[126:129]
	v_mfma_f32_16x16x32_f16 v[126:129], v[10:13], v[50:53], 0
	v_mfma_f32_16x16x32_f16 v[138:141], v[14:17], v[58:61], v[126:129]
	v_mfma_f32_16x16x32_f16 v[126:129], v[2:5], v[86:89], 0
	v_mfma_f32_16x16x32_f16 v[142:145], v[6:9], v[98:101], v[126:129]
	v_mfma_f32_16x16x32_f16 v[126:129], v[10:13], v[86:89], 0
	v_mfma_f32_16x16x32_f16 v[146:149], v[14:17], v[98:101], v[126:129]
	v_mfma_f32_16x16x32_f16 v[126:129], v[2:5], v[102:105], 0
	v_mfma_f32_16x16x32_f16 v[150:153], v[6:9], v[114:117], v[126:129]
	v_mfma_f32_16x16x32_f16 v[2:5], v[2:5], v[118:121], 0
	v_mfma_f32_16x16x32_f16 v[2:5], v[6:9], v[122:125], v[2:5]
	v_mfma_f32_16x16x32_f16 v[6:9], v[10:13], v[118:121], 0
	v_mfma_f32_16x16x32_f16 v[126:129], v[10:13], v[102:105], 0
	v_mfma_f32_16x16x32_f16 v[154:157], v[14:17], v[114:117], v[126:129]
	v_mfma_f32_16x16x32_f16 v[10:13], v[14:17], v[122:125], v[6:9]
	v_mfma_f32_16x16x32_f16 v[6:9], v[18:21], v[50:53], 0
	v_mfma_f32_16x16x32_f16 v[158:161], v[22:25], v[58:61], v[6:9]
	v_mfma_f32_16x16x32_f16 v[6:9], v[26:29], v[50:53], 0
	v_mfma_f32_16x16x32_f16 v[162:165], v[30:33], v[58:61], v[6:9]
	v_mfma_f32_16x16x32_f16 v[6:9], v[18:21], v[86:89], 0
	v_mfma_f32_16x16x32_f16 v[166:169], v[22:25], v[98:101], v[6:9]
	v_mfma_f32_16x16x32_f16 v[6:9], v[26:29], v[86:89], 0
	v_mfma_f32_16x16x32_f16 v[170:173], v[30:33], v[98:101], v[6:9]
	v_mfma_f32_16x16x32_f16 v[6:9], v[18:21], v[102:105], 0
	v_mfma_f32_16x16x32_f16 v[174:177], v[22:25], v[114:117], v[6:9]
	v_mfma_f32_16x16x32_f16 v[6:9], v[26:29], v[102:105], 0
	v_mfma_f32_16x16x32_f16 v[178:181], v[30:33], v[114:117], v[6:9]
	v_mfma_f32_16x16x32_f16 v[6:9], v[18:21], v[118:121], 0
	v_mfma_f32_16x16x32_f16 v[22:25], v[22:25], v[122:125], v[6:9]
	v_mfma_f32_16x16x32_f16 v[6:9], v[26:29], v[118:121], 0
	v_mfma_f32_16x16x32_f16 v[182:185], v[30:33], v[122:125], v[6:9]
	s_barrier
; #define PG8_STAGE(bufoff, gbase, voff) do { if constexpr (ABL & 1) break; glds16s<(bufoff)>((voff)[0], (const void*)(gbase), ldsbw); glds16s<(bufoff) + 8192>((voff)[1], (const void*)(gbase), ldsbw); } while (0)
; #define PG8_LDA(dst, b, h) do { if constexpr (ABL & 4) break; _Pragma("unroll") for (int m = 0; m < 4; ++m) _Pragma("unroll") for (int k = 0; k < 2; ++k) dst[m][k] = *(const LAS f16x8*)(lds + PG8_SA(b, h) + aoff + m * 2048 + k * 1024); } while (0)
; #define PG8_LDB(dst, b, h) do { if constexpr (ABL & 4) break; _Pragma("unroll") for (int n = 0; n < 2; ++n) _Pragma("unroll") for (int k = 0; k < 2; ++k) dst[n][k] = *(const LAS f16x8*)(lds + PG8_SB(b, h) + boff + n * 2048 + k * 1024); } while (0)
; #define PG8_MMA(ai, bj, At, Bt) do { if constexpr (ABL & 2) break; __builtin_amdgcn_s_setprio(1); _Pragma("unroll") for (int m = 0; m < 4; ++m) _Pragma("unroll") for (int n = 0; n < 2; ++n) _Pragma("unroll") for (int k = 0; k < 2; ++k) \
;         acc[ai][bj][m][n] = __builtin_amdgcn_mfma_f32_16x16x32_f16(Bt[n][k], At[m][k], acc[ai][bj][m][n], 0, 0, 0); __builtin_amdgcn_s_setprio(0); } while (0)
; #define PG8_WAIT_V(n) asm volatile("s_waitcnt vmcnt(" #n ")" ::: "memory")
; #define PG8_WAIT_L(n) asm volatile("s_waitcnt lgkmcnt(" #n ")" ::: "memory")
; #define PG8_BAR __builtin_amdgcn_s_barrier()
; #define PG8_SCHED __builtin_amdgcn_sched_barrier(0)
;     ...
;             PG8_LDB(B0, 1, 0); PG8_LDB(B1, 1, 1); PG8_SCHED; PG8_LDA(At, 1, 0); if (!fin) PG8_STAGE(PG8_SA(0, 1), a2 + hstep, voffA);
;             if (!fin) PG8_WAIT_V(8); else PG8_WAIT_V(0); PG8_WAIT_L(0); PG8_BAR; PG8_MMA(0, 0, At, B0); PG8_MMA(0, 1, At, B1); PG8_BAR; PG8_SCHED;
;             PG8_LDA(At, 1, 1); if (!fin) { PG8_STAGE(PG8_SB(1, 0), b3, voffB); PG8_STAGE(PG8_SB(1, 1), b3 + hstep, voffB); PG8_STAGE(PG8_SA(1, 0), a3, voffA); }
;             if (!fin) PG8_WAIT_V(8); PG8_WAIT_L(0); PG8_BAR; PG8_MMA(1, 0, At, B0); PG8_MMA(1, 1, At, B1); PG8_BAR; PG8_SCHED;
	s_setprio 0
	s_nop 4
	ds_read_b128 v[6:9], v239
	ds_read_b128 v[26:29], v239 offset:1024
	ds_read_b128 v[186:189], v239 offset:2048
	ds_read_b128 v[190:193], v239 offset:3072
	ds_read_b128 v[206:209], v240
	ds_read_b128 v[210:213], v240 offset:1024
	ds_read_b128 v[214:217], v240 offset:2048
	ds_read_b128 v[218:221], v240 offset:3072
	ds_read_b128 v[14:17], v238 offset:32768
	ds_read_b128 v[18:21], v238 offset:33792
	ds_read_b128 v[30:33], v238 offset:34816
	ds_read_b128 v[222:225], v238 offset:35840
	ds_read_b128 v[226:229], v238 offset:36864
	ds_read_b128 v[242:245], v238 offset:37888
	ds_read_b128 v[246:249], v238 offset:38912
	ds_read_b128 v[250:253], v238 offset:39936
	s_add_u32 s62, s62, 0x40100
	s_addc_u32 s63, s63, 0
	s_add_u32 m0, s28, 0x4000
	s_nop 0
	global_load_lds_dwordx4 v232, s[62:63]
	s_nop 0
	s_add_u32 m0, s28, 0x6000
	s_nop 0
	global_load_lds_dwordx4 v234, s[62:63]
	s_waitcnt vmcnt(8)
	s_waitcnt lgkmcnt(0)
	s_barrier
	v_mfma_f32_16x16x32_f16 v[50:53], v[6:9], v[14:17], v[66:69]
	s_setprio 1
	v_mfma_f32_16x16x32_f16 v[118:121], v[26:29], v[18:21], v[50:53]
	v_mfma_f32_16x16x32_f16 v[50:53], v[186:189], v[14:17], v[70:73]
	v_mfma_f32_16x16x32_f16 v[114:117], v[190:193], v[18:21], v[50:53]
	v_mfma_f32_16x16x32_f16 v[50:53], v[6:9], v[30:33], v[74:77]
	v_mfma_f32_16x16x32_f16 v[102:105], v[26:29], v[222:225], v[50:53]
	v_mfma_f32_16x16x32_f16 v[50:53], v[186:189], v[30:33], v[78:81]
	v_mfma_f32_16x16x32_f16 v[98:101], v[190:193], v[222:225], v[50:53]
	v_mfma_f32_16x16x32_f16 v[50:53], v[6:9], v[226:229], v[82:85]
	v_mfma_f32_16x16x32_f16 v[86:89], v[26:29], v[242:245], v[50:53]
	v_mfma_f32_16x16x32_f16 v[50:53], v[186:189], v[226:229], v[90:93]
	v_mfma_f32_16x16x32_f16 v[78:81], v[190:193], v[242:245], v[50:53]
	v_mfma_f32_16x16x32_f16 v[50:53], v[6:9], v[246:249], v[94:97]
	v_mfma_f32_16x16x32_f16 v[58:61], v[26:29], v[250:253], v[50:53]
	v_mfma_f32_16x16x32_f16 v[50:53], v[186:189], v[246:249], v[106:109]
	v_mfma_f32_16x16x32_f16 v[50:53], v[190:193], v[250:253], v[50:53]
	v_mfma_f32_16x16x32_f16 v[66:69], v[206:209], v[14:17], v[110:113]
	v_mfma_f32_16x16x32_f16 v[126:129], v[210:213], v[18:21], v[66:69]
	v_mfma_f32_16x16x32_f16 v[14:17], v[214:217], v[14:17], v[34:37]
	v_mfma_f32_16x16x32_f16 v[122:125], v[218:221], v[18:21], v[14:17]
	v_mfma_f32_16x16x32_f16 v[14:17], v[206:209], v[30:33], v[38:41]
	v_mfma_f32_16x16x32_f16 v[110:113], v[210:213], v[222:225], v[14:17]
	v_mfma_f32_16x16x32_f16 v[14:17], v[214:217], v[30:33], v[42:45]
	v_mfma_f32_16x16x32_f16 v[106:109], v[218:221], v[222:225], v[14:17]
	v_mfma_f32_16x16x32_f16 v[14:17], v[206:209], v[226:229], v[46:49]
	v_mfma_f32_16x16x32_f16 v[94:97], v[210:213], v[242:245], v[14:17]
	v_mfma_f32_16x16x32_f16 v[14:17], v[214:217], v[226:229], v[54:57]
	v_mfma_f32_16x16x32_f16 v[90:93], v[218:221], v[242:245], v[14:17]
	v_mfma_f32_16x16x32_f16 v[14:17], v[206:209], v[246:249], v[130:133]
	v_mfma_f32_16x16x32_f16 v[74:77], v[210:213], v[250:253], v[14:17]
	v_mfma_f32_16x16x32_f16 v[14:17], v[214:217], v[246:249], v[62:65]
	v_mfma_f32_16x16x32_f16 v[66:69], v[218:221], v[250:253], v[14:17]
	s_barrier
	s_setprio 0
	ds_read_b128 v[38:41], v238 offset:49152
	ds_read_b128 v[42:45], v238 offset:50176
	ds_read_b128 v[130:133], v238 offset:51200
	ds_read_b128 v[222:225], v238 offset:52224
	ds_read_b128 v[226:229], v238 offset:53248
	ds_read_b128 v[242:245], v238 offset:54272
	ds_read_b128 v[246:249], v238 offset:55296
	ds_read_b128 v[250:253], v238 offset:56320
	s_add_u32 m0, s28, 0x18000
	s_nop 0
	global_load_lds_dwordx4 v233, s[26:27]
	s_nop 0
	s_add_u32 m0, s28, 0x1a000
	s_nop 0
	global_load_lds_dwordx4 v235, s[26:27]
	s_add_u32 s26, s6, 0x40180
	s_addc_u32 s27, s7, 0
	s_add_u32 m0, s28, 0x1c000
	s_nop 0
	global_load_lds_dwordx4 v233, s[26:27]
	s_nop 0
	s_add_u32 m0, s28, 0x1e000
	s_nop 0
	global_load_lds_dwordx4 v235, s[26:27]
	s_nop 0
	s_add_u32 m0, s28, 0x8000
	s_nop 0
	global_load_lds_dwordx4 v232, s[24:25]
	s_nop 0
	s_add_u32 m0, s28, 0xa000
	s_nop 0
	global_load_lds_dwordx4 v234, s[24:25]
	s_waitcnt vmcnt(8)
	s_waitcnt lgkmcnt(0)
	s_barrier
	v_mfma_f32_16x16x32_f16 v[14:17], v[6:9], v[38:41], v[134:137]
	s_setprio 1
	v_mfma_f32_16x16x32_f16 v[54:57], v[26:29], v[42:45], v[14:17]
	v_mfma_f32_16x16x32_f16 v[14:17], v[190:193], v[42:45], v[138:141]
	v_mfma_f32_16x16x32_f16 v[46:49], v[186:189], v[38:41], v[14:17]
	v_mfma_f32_16x16x32_f16 v[14:17], v[6:9], v[130:133], v[142:145]
	v_mfma_f32_16x16x32_f16 v[34:37], v[26:29], v[222:225], v[14:17]
	v_mfma_f32_16x16x32_f16 v[14:17], v[190:193], v[222:225], v[146:149]
	v_mfma_f32_16x16x32_f16 v[30:33], v[186:189], v[130:133], v[14:17]
	v_mfma_f32_16x16x32_f16 v[14:17], v[6:9], v[226:229], v[150:153]
	v_mfma_f32_16x16x32_f16 v[18:21], v[26:29], v[242:245], v[14:17]
	v_mfma_f32_16x16x32_f16 v[2:5], v[26:29], v[250:253], v[2:5]
	v_mfma_f32_16x16x32_f16 v[6:9], v[6:9], v[246:249], v[2:5]
	v_mfma_f32_16x16x32_f16 v[2:5], v[186:189], v[246:249], v[10:13]
	v_mfma_f32_16x16x32_f16 v[2:5], v[190:193], v[250:253], v[2:5]
	v_mfma_f32_16x16x32_f16 v[14:17], v[190:193], v[242:245], v[154:157]
	v_mfma_f32_16x16x32_f16 v[14:17], v[186:189], v[226:229], v[14:17]
	v_mfma_f32_16x16x32_f16 v[10:13], v[206:209], v[38:41], v[158:161]
	v_mfma_f32_16x16x32_f16 v[82:85], v[210:213], v[42:45], v[10:13]
	v_mfma_f32_16x16x32_f16 v[10:13], v[218:221], v[42:45], v[162:165]
	v_mfma_f32_16x16x32_f16 v[70:73], v[214:217], v[38:41], v[10:13]
	v_mfma_f32_16x16x32_f16 v[10:13], v[206:209], v[130:133], v[166:169]
	v_mfma_f32_16x16x32_f16 v[62:65], v[210:213], v[222:225], v[10:13]
	v_mfma_f32_16x16x32_f16 v[10:13], v[218:221], v[222:225], v[170:173]
	v_mfma_f32_16x16x32_f16 v[42:45], v[214:217], v[130:133], v[10:13]
	v_mfma_f32_16x16x32_f16 v[10:13], v[206:209], v[226:229], v[174:177]
	v_mfma_f32_16x16x32_f16 v[38:41], v[210:213], v[242:245], v[10:13]
	v_mfma_f32_16x16x32_f16 v[10:13], v[218:221], v[242:245], v[178:181]
	v_mfma_f32_16x16x32_f16 v[26:29], v[214:217], v[226:229], v[10:13]
	v_mfma_f32_16x16x32_f16 v[10:13], v[206:209], v[246:249], v[22:25]
	v_mfma_f32_16x16x32_f16 v[22:25], v[210:213], v[250:253], v[10:13]
	v_mfma_f32_16x16x32_f16 v[10:13], v[218:221], v[250:253], v[182:185]
	v_mfma_f32_16x16x32_f16 v[10:13], v[214:217], v[246:249], v[10:13]
	s_barrier
	s_setprio 0
	s_add_u32 s53, s6, 0x200
	s_addc_u32 s61, s7, 0
	s_mov_b32 s64, 0
	s_branch .LBB0_231
; #define PG8_STAGE(bufoff, gbase, voff) do { if constexpr (ABL & 1) break; glds16s<(bufoff)>((voff)[0], (const void*)(gbase), ldsbw); glds16s<(bufoff) + 8192>((voff)[1], (const void*)(gbase), ldsbw); } while (0)
; #define PG8_LDA(dst, b, h) do { if constexpr (ABL & 4) break; _Pragma("unroll") for (int m = 0; m < 4; ++m) _Pragma("unroll") for (int k = 0; k < 2; ++k) dst[m][k] = *(const LAS f16x8*)(lds + PG8_SA(b, h) + aoff + m * 2048 + k * 1024); } while (0)
; #define PG8_LDB(dst, b, h) do { if constexpr (ABL & 4) break; _Pragma("unroll") for (int n = 0; n < 2; ++n) _Pragma("unroll") for (int k = 0; k < 2; ++k) dst[n][k] = *(const LAS f16x8*)(lds + PG8_SB(b, h) + boff + n * 2048 + k * 1024); } while (0)
; #define PG8_MMA(ai, bj, At, Bt) do { if constexpr (ABL & 2) break; __builtin_amdgcn_s_setprio(1); _Pragma("unroll") for (int m = 0; m < 4; ++m) _Pragma("unroll") for (int n = 0; n < 2; ++n) _Pragma("unroll") for (int k = 0; k < 2; ++k) \
;         acc[ai][bj][m][n] = __builtin_amdgcn_mfma_f32_16x16x32_f16(Bt[n][k], At[m][k], acc[ai][bj][m][n], 0, 0, 0); __builtin_amdgcn_s_setprio(0); } while (0)
; #define PG8_WAIT_V(n) asm volatile("s_waitcnt vmcnt(" #n ")" ::: "memory")
;     ...
;             PG8_LDB(B0, 0, 0); PG8_LDB(B1, 0, 1); PG8_SCHED; PG8_LDA(At, 0, 0); PG8_STAGE(PG8_SA(1, 1), a1 + hstep, voffA);
;             PG8_WAIT_V(8); PG8_WAIT_L(0); PG8_BAR; PG8_MMAF(0, 0, At, B0); PG8_MMAF(0, 1, At, B1); PG8_BAR; PG8_SCHED;
;             const bool fin = last && !has_next;
;             PG8_LDA(At, 0, 1); if (!fin) { PG8_STAGE(PG8_SB(0, 0), b2, voffB); PG8_STAGE(PG8_SB(0, 1), b2 + hstep, voffB); PG8_STAGE(PG8_SA(0, 0), a2, voffA); }
;             if (!fin) PG8_WAIT_V(8); else PG8_WAIT_V(2); PG8_WAIT_L(0); PG8_BAR; PG8_MMAF(1, 0, At, B0); PG8_MMAF(1, 1, At, B1); PG8_BAR; PG8_SCHED;
;             PG8_LDB(B0, 1, 0); PG8_LDB(B1, 1, 1); PG8_SCHED; PG8_LDA(At, 1, 0); if (!fin) PG8_STAGE(PG8_SA(0, 1), a2 + hstep, voffA);
;             if (!fin) PG8_WAIT_V(8); else PG8_WAIT_V(0); PG8_WAIT_L(0); PG8_BAR; PG8_MMA(0, 0, At, B0); PG8_MMA(0, 1, At, B1); PG8_BAR; PG8_SCHED;
;             PG8_LDA(At, 1, 1); if (!fin) { PG8_STAGE(PG8_SB(1, 0), b3, voffB); PG8_STAGE(PG8_SB(1, 1), b3 + hstep, voffB); PG8_STAGE(PG8_SA(1, 0), a3, voffA); }
;             if (!fin) PG8_WAIT_V(8); PG8_WAIT_L(0); PG8_BAR; PG8_MMA(1, 0, At, B0); PG8_MMA(1, 1, At, B1); PG8_BAR; PG8_SCHED;
.LBB0_230:
	s_waitcnt lgkmcnt(0)
	s_barrier
	v_mfma_f32_16x16x32_f16 v[54:57], v[154:157], v[186:189], v[54:57]
	s_setprio 1
	v_mfma_f32_16x16x32_f16 v[54:57], v[158:161], v[190:193], v[54:57]
	v_mfma_f32_16x16x32_f16 v[46:49], v[150:153], v[190:193], v[46:49]
	v_mfma_f32_16x16x32_f16 v[46:49], v[146:149], v[186:189], v[46:49]
	v_mfma_f32_16x16x32_f16 v[30:33], v[146:149], v[178:181], v[30:33]
	v_mfma_f32_16x16x32_f16 v[30:33], v[150:153], v[182:185], v[30:33]
	v_mfma_f32_16x16x32_f16 v[34:37], v[158:161], v[182:185], v[34:37]
	v_mfma_f32_16x16x32_f16 v[34:37], v[154:157], v[178:181], v[34:37]
	v_mfma_f32_16x16x32_f16 v[18:21], v[154:157], v[170:173], v[18:21]
	v_mfma_f32_16x16x32_f16 v[18:21], v[158:161], v[174:177], v[18:21]
	v_mfma_f32_16x16x32_f16 v[14:17], v[150:153], v[174:177], v[14:17]
	v_mfma_f32_16x16x32_f16 v[14:17], v[146:149], v[170:173], v[14:17]
	v_mfma_f32_16x16x32_f16 v[2:5], v[146:149], v[162:165], v[2:5]
	v_mfma_f32_16x16x32_f16 v[2:5], v[150:153], v[166:169], v[2:5]
	v_mfma_f32_16x16x32_f16 v[6:9], v[158:161], v[166:169], v[6:9]
	v_mfma_f32_16x16x32_f16 v[6:9], v[154:157], v[162:165], v[6:9]
	v_mfma_f32_16x16x32_f16 v[22:25], v[138:141], v[162:165], v[22:25]
	v_mfma_f32_16x16x32_f16 v[22:25], v[142:145], v[166:169], v[22:25]
	v_mfma_f32_16x16x32_f16 v[82:85], v[142:145], v[190:193], v[82:85]
	v_mfma_f32_16x16x32_f16 v[82:85], v[138:141], v[186:189], v[82:85]
	v_mfma_f32_16x16x32_f16 v[70:73], v[130:133], v[186:189], v[70:73]
	v_mfma_f32_16x16x32_f16 v[70:73], v[134:137], v[190:193], v[70:73]
	v_mfma_f32_16x16x32_f16 v[42:45], v[134:137], v[182:185], v[42:45]
	v_mfma_f32_16x16x32_f16 v[42:45], v[130:133], v[178:181], v[42:45]
	v_mfma_f32_16x16x32_f16 v[62:65], v[138:141], v[178:181], v[62:65]
	v_mfma_f32_16x16x32_f16 v[62:65], v[142:145], v[182:185], v[62:65]
	v_mfma_f32_16x16x32_f16 v[38:41], v[142:145], v[174:177], v[38:41]
	v_mfma_f32_16x16x32_f16 v[38:41], v[138:141], v[170:173], v[38:41]
	v_mfma_f32_16x16x32_f16 v[26:29], v[130:133], v[170:173], v[26:29]
	v_mfma_f32_16x16x32_f16 v[26:29], v[134:137], v[174:177], v[26:29]
	v_mfma_f32_16x16x32_f16 v[10:13], v[134:137], v[166:169], v[10:13]
	v_mfma_f32_16x16x32_f16 v[10:13], v[130:133], v[162:165], v[10:13]
	s_barrier
	s_setprio 0
	s_add_i32 s64, s64, 2
	s_add_u32 s53, s53, 0x100
	s_addc_u32 s61, s61, 0
	s_cmp_gt_u32 s64, 13
	s_cbranch_scc1 .LBB0_241
.LBB0_231:
	ds_read_b128 v[146:149], v236
	ds_read_b128 v[150:153], v236 offset:1024
	ds_read_b128 v[154:157], v236 offset:2048
	ds_read_b128 v[158:161], v236 offset:3072
	ds_read_b128 v[130:133], v237
	ds_read_b128 v[134:137], v237 offset:1024
	ds_read_b128 v[138:141], v237 offset:2048
	ds_read_b128 v[142:145], v237 offset:3072
	s_mov_b64 s[6:7], s[8:9]
	s_add_u32 s8, s6, 0x100
	s_addc_u32 s9, s7, 0
	s_cmp_eq_u32 s64, 12
	s_cselect_b64 s[62:63], -1, 0
	s_and_b64 s[24:25], s[62:63], exec
	s_cselect_b32 s27, s11, s9
	s_cselect_b32 s26, s35, s8
	s_cselect_b32 s25, s1, s61
	s_cselect_b32 s24, s46, s53
	ds_read_b128 v[162:165], v238
	ds_read_b128 v[166:169], v238 offset:1024
	ds_read_b128 v[170:173], v238 offset:2048
	ds_read_b128 v[174:177], v238 offset:3072
	ds_read_b128 v[178:181], v238 offset:4096
	ds_read_b128 v[182:185], v238 offset:5120
	ds_read_b128 v[186:189], v238 offset:6144
	ds_read_b128 v[190:193], v238 offset:7168
	s_add_u32 s6, s6, 0x40080
	s_addc_u32 s7, s7, 0
	s_add_u32 m0, s28, 0xc000
	s_nop 0
	global_load_lds_dwordx4 v232, s[6:7]
	s_nop 0
	s_add_u32 m0, s28, 0xe000
	s_nop 0
	global_load_lds_dwordx4 v234, s[6:7]
	s_waitcnt vmcnt(8)
	s_waitcnt lgkmcnt(0)
	s_barrier
	v_mfma_f32_16x16x32_f16 v[118:121], v[146:149], v[162:165], v[118:121]
	s_setprio 1
	v_mfma_f32_16x16x32_f16 v[118:121], v[150:153], v[166:169], v[118:121]
	v_mfma_f32_16x16x32_f16 v[114:117], v[158:161], v[166:169], v[114:117]
	v_mfma_f32_16x16x32_f16 v[114:117], v[154:157], v[162:165], v[114:117]
	v_mfma_f32_16x16x32_f16 v[98:101], v[154:157], v[170:173], v[98:101]
	v_mfma_f32_16x16x32_f16 v[98:101], v[158:161], v[174:177], v[98:101]
	v_mfma_f32_16x16x32_f16 v[102:105], v[150:153], v[174:177], v[102:105]
	v_mfma_f32_16x16x32_f16 v[102:105], v[146:149], v[170:173], v[102:105]
	v_mfma_f32_16x16x32_f16 v[86:89], v[146:149], v[178:181], v[86:89]
	v_mfma_f32_16x16x32_f16 v[86:89], v[150:153], v[182:185], v[86:89]
	v_mfma_f32_16x16x32_f16 v[78:81], v[158:161], v[182:185], v[78:81]
	v_mfma_f32_16x16x32_f16 v[78:81], v[154:157], v[178:181], v[78:81]
	v_mfma_f32_16x16x32_f16 v[50:53], v[154:157], v[186:189], v[50:53]
	v_mfma_f32_16x16x32_f16 v[50:53], v[158:161], v[190:193], v[50:53]
	v_mfma_f32_16x16x32_f16 v[58:61], v[150:153], v[190:193], v[58:61]
	v_mfma_f32_16x16x32_f16 v[58:61], v[146:149], v[186:189], v[58:61]
	v_mfma_f32_16x16x32_f16 v[74:77], v[130:133], v[186:189], v[74:77]
	v_mfma_f32_16x16x32_f16 v[74:77], v[134:137], v[190:193], v[74:77]
	v_mfma_f32_16x16x32_f16 v[126:129], v[134:137], v[166:169], v[126:129]
	v_mfma_f32_16x16x32_f16 v[126:129], v[130:133], v[162:165], v[126:129]
	v_mfma_f32_16x16x32_f16 v[122:125], v[138:141], v[162:165], v[122:125]
	v_mfma_f32_16x16x32_f16 v[122:125], v[142:145], v[166:169], v[122:125]
	v_mfma_f32_16x16x32_f16 v[106:109], v[142:145], v[174:177], v[106:109]
	v_mfma_f32_16x16x32_f16 v[106:109], v[138:141], v[170:173], v[106:109]
	v_mfma_f32_16x16x32_f16 v[110:113], v[130:133], v[170:173], v[110:113]
	v_mfma_f32_16x16x32_f16 v[110:113], v[134:137], v[174:177], v[110:113]
	v_mfma_f32_16x16x32_f16 v[94:97], v[134:137], v[182:185], v[94:97]
	v_mfma_f32_16x16x32_f16 v[94:97], v[130:133], v[178:181], v[94:97]
	v_mfma_f32_16x16x32_f16 v[90:93], v[138:141], v[178:181], v[90:93]
	v_mfma_f32_16x16x32_f16 v[90:93], v[142:145], v[182:185], v[90:93]
	v_mfma_f32_16x16x32_f16 v[66:69], v[142:145], v[190:193], v[66:69]
	v_mfma_f32_16x16x32_f16 v[66:69], v[138:141], v[186:189], v[66:69]
	s_barrier
	s_setprio 0
	ds_read_b128 v[186:189], v238 offset:16384
	ds_read_b128 v[190:193], v238 offset:17408
	ds_read_b128 v[178:181], v238 offset:18432
	ds_read_b128 v[182:185], v238 offset:19456
	ds_read_b128 v[170:173], v238 offset:20480
	ds_read_b128 v[174:177], v238 offset:21504
	ds_read_b128 v[162:165], v238 offset:22528
	ds_read_b128 v[166:169], v238 offset:23552
	s_and_b64 s[6:7], s[4:5], s[62:63]
	s_mov_b64 s[62:63], -1
	s_and_b64 vcc, exec, s[6:7]
	s_cbranch_vccnz .LBB0_233
	s_add_u32 m0, s28, 0x10000
	s_nop 0
	global_load_lds_dwordx4 v233, s[24:25]
	s_nop 0
	s_add_u32 m0, s28, 0x12000
	s_nop 0
	global_load_lds_dwordx4 v235, s[24:25]
	s_add_u32 s62, s24, 0x40000
	s_addc_u32 s63, s25, 0
	s_add_u32 m0, s28, 0x14000
	s_nop 0
	global_load_lds_dwordx4 v233, s[62:63]
	s_nop 0
	s_add_u32 m0, s28, 0x16000
	s_nop 0
	global_load_lds_dwordx4 v235, s[62:63]
	s_mov_b64 s[62:63], 0
	s_add_u32 m0, s28, 0
	s_nop 0
	global_load_lds_dwordx4 v232, s[26:27]
	s_nop 0
	s_add_u32 m0, s28, 0x2000
	s_nop 0
	global_load_lds_dwordx4 v234, s[26:27]
	s_waitcnt vmcnt(8)

; #define PG8_STAGE(bufoff, gbase, voff) do { if constexpr (ABL & 1) break; glds16s<(bufoff)>((voff)[0], (const void*)(gbase), ldsbw); glds16s<(bufoff) + 8192>((voff)[1], (const void*)(gbase), ldsbw); } while (0)
; #define PG8_LDA(dst, b, h) do { if constexpr (ABL & 4) break; _Pragma("unroll") for (int m = 0; m < 4; ++m) _Pragma("unroll") for (int k = 0; k < 2; ++k) dst[m][k] = *(const LAS f16x8*)(lds + PG8_SA(b, h) + aoff + m * 2048 + k * 1024); } while (0)
; #define PG8_LDB(dst, b, h) do { if constexpr (ABL & 4) break; _Pragma("unroll") for (int n = 0; n < 2; ++n) _Pragma("unroll") for (int k = 0; k < 2; ++k) dst[n][k] = *(const LAS f16x8*)(lds + PG8_SB(b, h) + boff + n * 2048 + k * 1024); } while (0)
; #define PG8_MMA(ai, bj, At, Bt) do { if constexpr (ABL & 2) break; __builtin_amdgcn_s_setprio(1); _Pragma("unroll") for (int m = 0; m < 4; ++m) _Pragma("unroll") for (int n = 0; n < 2; ++n) _Pragma("unroll") for (int k = 0; k < 2; ++k) \
;         acc[ai][bj][m][n] = __builtin_amdgcn_mfma_f32_16x16x32_f16(Bt[n][k], At[m][k], acc[ai][bj][m][n], 0, 0, 0); __builtin_amdgcn_s_setprio(0); } while (0)
; #define PG8_MMAF(ai, bj, At, Bt) do { if (t == 0) PG8_MMA0(ai, bj, At, Bt); else PG8_MMA(ai, bj, At, Bt); } while (0)
; #define PG8_WAIT_V(n) asm volatile("s_waitcnt vmcnt(" #n ")" ::: "memory")
; #define PG8_WAIT_L(n) asm volatile("s_waitcnt lgkmcnt(" #n ")" ::: "memory")
; #define PG8_BAR __builtin_amdgcn_s_barrier()
; #define PG8_SCHED __builtin_amdgcn_sched_barrier(0)
;     ...
;             if (!fin) PG8_WAIT_V(8); else PG8_WAIT_V(2); PG8_WAIT_L(0); PG8_BAR; PG8_MMAF(1, 0, At, B0); PG8_MMAF(1, 1, At, B1); PG8_BAR; PG8_SCHED;
;             PG8_LDB(B0, 1, 0); PG8_LDB(B1, 1, 1); PG8_SCHED; PG8_LDA(At, 1, 0); if (!fin) PG8_STAGE(PG8_SA(0, 1), a2 + hstep, voffA);
;             if (!fin) PG8_WAIT_V(8); else PG8_WAIT_V(0); PG8_WAIT_L(0); PG8_BAR; PG8_MMA(0, 0, At, B0); PG8_MMA(0, 1, At, B1); PG8_BAR; PG8_SCHED;
.LBB0_235:
	s_waitcnt lgkmcnt(0)
	s_xor_b64 s[62:63], s[6:7], -1
	s_barrier
	v_mfma_f32_16x16x32_f16 v[54:57], v[146:149], v[186:189], v[54:57]
	s_setprio 1
	v_mfma_f32_16x16x32_f16 v[54:57], v[150:153], v[190:193], v[54:57]
	v_mfma_f32_16x16x32_f16 v[46:49], v[158:161], v[190:193], v[46:49]
	v_mfma_f32_16x16x32_f16 v[46:49], v[154:157], v[186:189], v[46:49]
	v_mfma_f32_16x16x32_f16 v[30:33], v[154:157], v[178:181], v[30:33]
	v_mfma_f32_16x16x32_f16 v[30:33], v[158:161], v[182:185], v[30:33]
	v_mfma_f32_16x16x32_f16 v[34:37], v[150:153], v[182:185], v[34:37]
	v_mfma_f32_16x16x32_f16 v[34:37], v[146:149], v[178:181], v[34:37]
	v_mfma_f32_16x16x32_f16 v[18:21], v[146:149], v[170:173], v[18:21]
	v_mfma_f32_16x16x32_f16 v[18:21], v[150:153], v[174:177], v[18:21]
	v_mfma_f32_16x16x32_f16 v[14:17], v[158:161], v[174:177], v[14:17]
	v_mfma_f32_16x16x32_f16 v[14:17], v[154:157], v[170:173], v[14:17]
	v_mfma_f32_16x16x32_f16 v[2:5], v[154:157], v[162:165], v[2:5]
	v_mfma_f32_16x16x32_f16 v[2:5], v[158:161], v[166:169], v[2:5]
	v_mfma_f32_16x16x32_f16 v[6:9], v[150:153], v[166:169], v[6:9]
	v_mfma_f32_16x16x32_f16 v[6:9], v[146:149], v[162:165], v[6:9]
	v_mfma_f32_16x16x32_f16 v[22:25], v[130:133], v[162:165], v[22:25]
	v_mfma_f32_16x16x32_f16 v[22:25], v[134:137], v[166:169], v[22:25]
	v_mfma_f32_16x16x32_f16 v[82:85], v[134:137], v[190:193], v[82:85]
	v_mfma_f32_16x16x32_f16 v[82:85], v[130:133], v[186:189], v[82:85]
	v_mfma_f32_16x16x32_f16 v[70:73], v[138:141], v[186:189], v[70:73]
	v_mfma_f32_16x16x32_f16 v[70:73], v[142:145], v[190:193], v[70:73]
	v_mfma_f32_16x16x32_f16 v[42:45], v[142:145], v[182:185], v[42:45]
	v_mfma_f32_16x16x32_f16 v[42:45], v[138:141], v[178:181], v[42:45]
	v_mfma_f32_16x16x32_f16 v[62:65], v[130:133], v[178:181], v[62:65]
	v_mfma_f32_16x16x32_f16 v[62:65], v[134:137], v[182:185], v[62:65]
	v_mfma_f32_16x16x32_f16 v[38:41], v[134:137], v[174:177], v[38:41]
	v_mfma_f32_16x16x32_f16 v[38:41], v[130:133], v[170:173], v[38:41]
	v_mfma_f32_16x16x32_f16 v[26:29], v[138:141], v[170:173], v[26:29]
	v_mfma_f32_16x16x32_f16 v[26:29], v[142:145], v[174:177], v[26:29]
	v_mfma_f32_16x16x32_f16 v[10:13], v[142:145], v[166:169], v[10:13]
	v_mfma_f32_16x16x32_f16 v[10:13], v[138:141], v[162:165], v[10:13]
	s_barrier
	s_setprio 0
	ds_read_b128 v[154:157], v239
	ds_read_b128 v[158:161], v239 offset:1024
	ds_read_b128 v[146:149], v239 offset:2048
	ds_read_b128 v[150:153], v239 offset:3072
	ds_read_b128 v[138:141], v240
	ds_read_b128 v[142:145], v240 offset:1024
	ds_read_b128 v[130:133], v240 offset:2048
	ds_read_b128 v[134:137], v240 offset:3072
	ds_read_b128 v[186:189], v238 offset:32768
	ds_read_b128 v[190:193], v238 offset:33792
	ds_read_b128 v[178:181], v238 offset:34816
	ds_read_b128 v[182:185], v238 offset:35840
	ds_read_b128 v[170:173], v238 offset:36864
	ds_read_b128 v[174:177], v238 offset:37888
	ds_read_b128 v[162:165], v238 offset:38912
	ds_read_b128 v[166:169], v238 offset:39936
	v_cndmask_b32_e64 v198, 0, 1, s[62:63]
	v_cmp_ne_u32_e64 s[6:7], 1, v198
	s_andn2_b64 vcc, exec, s[62:63]
	s_mov_b64 s[62:63], -1
	s_cbranch_vccnz .LBB0_237
	s_add_u32 s62, s26, 0x40000
	s_addc_u32 s63, s27, 0
	s_add_u32 m0, s28, 0x4000
	s_nop 0
	global_load_lds_dwordx4 v232, s[62:63]
	s_nop 0
	s_add_u32 m0, s28, 0x6000
	s_nop 0
	global_load_lds_dwordx4 v234, s[62:63]
	s_waitcnt vmcnt(8)
	s_mov_b64 s[62:63], 0

; #define PG8_STAGE(bufoff, gbase, voff) do { if constexpr (ABL & 1) break; glds16s<(bufoff)>((voff)[0], (const void*)(gbase), ldsbw); glds16s<(bufoff) + 8192>((voff)[1], (const void*)(gbase), ldsbw); } while (0)
; #define PG8_LDA(dst, b, h) do { if constexpr (ABL & 4) break; _Pragma("unroll") for (int m = 0; m < 4; ++m) _Pragma("unroll") for (int k = 0; k < 2; ++k) dst[m][k] = *(const LAS f16x8*)(lds + PG8_SA(b, h) + aoff + m * 2048 + k * 1024); } while (0)
; #define PG8_MMA(ai, bj, At, Bt) do { if constexpr (ABL & 2) break; __builtin_amdgcn_s_setprio(1); _Pragma("unroll") for (int m = 0; m < 4; ++m) _Pragma("unroll") for (int n = 0; n < 2; ++n) _Pragma("unroll") for (int k = 0; k < 2; ++k) \
;         acc[ai][bj][m][n] = __builtin_amdgcn_mfma_f32_16x16x32_f16(Bt[n][k], At[m][k], acc[ai][bj][m][n], 0, 0, 0); __builtin_amdgcn_s_setprio(0); } while (0)
; #define PG8_WAIT_V(n) asm volatile("s_waitcnt vmcnt(" #n ")" ::: "memory")
; #define PG8_WAIT_L(n) asm volatile("s_waitcnt lgkmcnt(" #n ")" ::: "memory")
; #define PG8_BAR __builtin_amdgcn_s_barrier()
; #define PG8_SCHED __builtin_amdgcn_sched_barrier(0)
;     ...
;             if (!fin) PG8_WAIT_V(8); else PG8_WAIT_V(0); PG8_WAIT_L(0); PG8_BAR; PG8_MMA(0, 0, At, B0); PG8_MMA(0, 1, At, B1); PG8_BAR; PG8_SCHED;
;             PG8_LDA(At, 1, 1); if (!fin) { PG8_STAGE(PG8_SB(1, 0), b3, voffB); PG8_STAGE(PG8_SB(1, 1), b3 + hstep, voffB); PG8_STAGE(PG8_SA(1, 0), a3, voffA); }
;             if (!fin) PG8_WAIT_V(8); PG8_WAIT_L(0); PG8_BAR; PG8_MMA(1, 0, At, B0); PG8_MMA(1, 1, At, B1); PG8_BAR; PG8_SCHED;
.LBB0_239:
	s_waitcnt lgkmcnt(0)
	s_barrier
	v_mfma_f32_16x16x32_f16 v[118:121], v[154:157], v[186:189], v[118:121]
	s_setprio 1
	v_mfma_f32_16x16x32_f16 v[118:121], v[158:161], v[190:193], v[118:121]
	v_mfma_f32_16x16x32_f16 v[114:117], v[150:153], v[190:193], v[114:117]
	v_mfma_f32_16x16x32_f16 v[114:117], v[146:149], v[186:189], v[114:117]
	v_mfma_f32_16x16x32_f16 v[98:101], v[146:149], v[178:181], v[98:101]
	v_mfma_f32_16x16x32_f16 v[98:101], v[150:153], v[182:185], v[98:101]
	v_mfma_f32_16x16x32_f16 v[102:105], v[158:161], v[182:185], v[102:105]
	v_mfma_f32_16x16x32_f16 v[102:105], v[154:157], v[178:181], v[102:105]
	v_mfma_f32_16x16x32_f16 v[86:89], v[154:157], v[170:173], v[86:89]
	v_mfma_f32_16x16x32_f16 v[86:89], v[158:161], v[174:177], v[86:89]
	v_mfma_f32_16x16x32_f16 v[78:81], v[150:153], v[174:177], v[78:81]
	v_mfma_f32_16x16x32_f16 v[78:81], v[146:149], v[170:173], v[78:81]
	v_mfma_f32_16x16x32_f16 v[50:53], v[146:149], v[162:165], v[50:53]
	v_mfma_f32_16x16x32_f16 v[50:53], v[150:153], v[166:169], v[50:53]
	v_mfma_f32_16x16x32_f16 v[58:61], v[158:161], v[166:169], v[58:61]
	v_mfma_f32_16x16x32_f16 v[58:61], v[154:157], v[162:165], v[58:61]
	v_mfma_f32_16x16x32_f16 v[74:77], v[138:141], v[162:165], v[74:77]
	v_mfma_f32_16x16x32_f16 v[74:77], v[142:145], v[166:169], v[74:77]
	v_mfma_f32_16x16x32_f16 v[126:129], v[142:145], v[190:193], v[126:129]
	v_mfma_f32_16x16x32_f16 v[126:129], v[138:141], v[186:189], v[126:129]
	v_mfma_f32_16x16x32_f16 v[122:125], v[130:133], v[186:189], v[122:125]
	v_mfma_f32_16x16x32_f16 v[122:125], v[134:137], v[190:193], v[122:125]
	v_mfma_f32_16x16x32_f16 v[106:109], v[134:137], v[182:185], v[106:109]
	v_mfma_f32_16x16x32_f16 v[106:109], v[130:133], v[178:181], v[106:109]
	v_mfma_f32_16x16x32_f16 v[110:113], v[138:141], v[178:181], v[110:113]
	v_mfma_f32_16x16x32_f16 v[110:113], v[142:145], v[182:185], v[110:113]
	v_mfma_f32_16x16x32_f16 v[94:97], v[142:145], v[174:177], v[94:97]
	v_mfma_f32_16x16x32_f16 v[94:97], v[138:141], v[170:173], v[94:97]
	v_mfma_f32_16x16x32_f16 v[90:93], v[130:133], v[170:173], v[90:93]
	v_mfma_f32_16x16x32_f16 v[90:93], v[134:137], v[174:177], v[90:93]
	v_mfma_f32_16x16x32_f16 v[66:69], v[134:137], v[166:169], v[66:69]
	v_mfma_f32_16x16x32_f16 v[66:69], v[130:133], v[162:165], v[66:69]
	s_barrier
	s_setprio 0
	ds_read_b128 v[186:189], v238 offset:49152
	ds_read_b128 v[190:193], v238 offset:50176
	ds_read_b128 v[178:181], v238 offset:51200
	ds_read_b128 v[182:185], v238 offset:52224
	ds_read_b128 v[170:173], v238 offset:53248
	ds_read_b128 v[174:177], v238 offset:54272
	ds_read_b128 v[162:165], v238 offset:55296
	ds_read_b128 v[166:169], v238 offset:56320
	s_and_b64 vcc, exec, s[6:7]
	s_cbranch_vccnz .LBB0_230
	s_add_u32 s6, s26, 0x80
	s_addc_u32 s7, s27, 0
	s_add_u32 s26, s24, 0x80
	s_addc_u32 s27, s25, 0
	s_add_u32 m0, s28, 0x18000
	s_nop 0
	global_load_lds_dwordx4 v233, s[26:27]
	s_nop 0
	s_add_u32 m0, s28, 0x1a000
	s_nop 0
	global_load_lds_dwordx4 v235, s[26:27]
	s_add_u32 s24, s24, 0x40080
	s_addc_u32 s25, s25, 0
	s_add_u32 m0, s28, 0x1c000
	s_nop 0
	global_load_lds_dwordx4 v233, s[24:25]
	s_nop 0
	s_add_u32 m0, s28, 0x1e000
	s_nop 0
	global_load_lds_dwordx4 v235, s[24:25]
	s_nop 0
	s_add_u32 m0, s28, 0x8000
	s_nop 0
	global_load_lds_dwordx4 v232, s[6:7]
	s_nop 0
	s_add_u32 m0, s28, 0xa000
	s_nop 0
	global_load_lds_dwordx4 v234, s[6:7]
	s_waitcnt vmcnt(8)
	s_branch .LBB0_230

;     __device__ __forceinline__ bool next(int i, Unit& u) const { if (i >= count) return false; const int L = first + i; u.pm = L / nN; u.pn = L % nN; return true; }
; #define PG8_STAGE(bufoff, gbase, voff) do { if constexpr (ABL & 1) break; glds16s<(bufoff)>((voff)[0], (const void*)(gbase), ldsbw); glds16s<(bufoff) + 8192>((voff)[1], (const void*)(gbase), ldsbw); } while (0)
; #define PG8_LDA(dst, b, h) do { if constexpr (ABL & 4) break; _Pragma("unroll") for (int m = 0; m < 4; ++m) _Pragma("unroll") for (int k = 0; k < 2; ++k) dst[m][k] = *(const LAS f16x8*)(lds + PG8_SA(b, h) + aoff + m * 2048 + k * 1024); } while (0)
; #define PG8_LDB(dst, b, h) do { if constexpr (ABL & 4) break; _Pragma("unroll") for (int n = 0; n < 2; ++n) _Pragma("unroll") for (int k = 0; k < 2; ++k) dst[n][k] = *(const LAS f16x8*)(lds + PG8_SB(b, h) + boff + n * 2048 + k * 1024); } while (0)
; #define PG8_MMAF(ai, bj, At, Bt) do { if (t == 0) PG8_MMA0(ai, bj, At, Bt); else PG8_MMA(ai, bj, At, Bt); } while (0)
; #define PG8_WAIT_V(n) asm volatile("s_waitcnt vmcnt(" #n ")" ::: "memory")
; #define PG8_BAR __builtin_amdgcn_s_barrier()
;     ...
;         const bool has_next = S.next(ui + 1, nxt);
;         const char* nA = has_next ? (const char*)g.A + (size_t)nxt.pm * tstep : cA; const char* nB = has_next ? (const char*)g.Bt + (size_t)nxt.pn * tstep : cB;
;         for (int t = 0; t < nt; t += 2) {
;             const bool last = (t == nt - 2);
;             const char* a1 = cA + (size_t)(t + 1) * kstep;
;             const char* a2 = last ? nA : cA + (size_t)(t + 2) * kstep; const char* b2 = last ? nB : cB + (size_t)(t + 2) * kstep;
;             const char* a3 = a2 + kstep; const char* b3 = b2 + kstep;
;             if (last && has_next) S.a_ready(nxt);
;             if constexpr (SP2) {
;             PG8_LDB(B0, 0, 0); PG8_LDB(B1, 0, 1); PG8_SCHED; PG8_LDA(At, 0, 0); PG8_STAGE(PG8_SA(1, 1), a1 + hstep, voffA);
;             PG8_WAIT_V(8); PG8_WAIT_L(0); PG8_BAR; PG8_MMAF(0, 0, At, B0); PG8_MMAF(0, 1, At, B1); PG8_BAR; PG8_SCHED;
;             const bool fin = last && !has_next;
;             PG8_LDA(At, 0, 1); if (!fin) { PG8_STAGE(PG8_SB(0, 0), b2, voffB); PG8_STAGE(PG8_SB(0, 1), b2 + hstep, voffB); PG8_STAGE(PG8_SA(0, 0), a2, voffA); }
;             if (!fin) PG8_WAIT_V(8); else PG8_WAIT_V(2); PG8_WAIT_L(0); PG8_BAR; PG8_MMAF(1, 0, At, B0); PG8_MMAF(1, 1, At, B1); PG8_BAR; PG8_SCHED;
.LBB0_748:
	s_ashr_i32 s47, s46, 31
	s_lshl_b64 s[8:9], s[46:47], 19
	s_add_u32 s48, s12, s8
	s_addc_u32 s49, s13, s9
	s_and_b64 s[8:9], exec, s[4:5]
	s_waitcnt lgkmcnt(0)
	ds_read_b128 v[2:5], v222
	ds_read_b128 v[6:9], v222 offset:1024
	ds_read_b128 v[10:13], v222 offset:2048
	ds_read_b128 v[14:17], v222 offset:3072
	ds_read_b128 v[18:21], v223
	ds_read_b128 v[22:25], v223 offset:1024
	ds_read_b128 v[26:29], v223 offset:2048
	ds_read_b128 v[30:33], v223 offset:3072
	s_cselect_b32 s47, s31, s49
	s_cselect_b32 s55, s30, s48
	s_ashr_i32 s45, s44, 31
	s_lshl_b64 s[8:9], s[44:45], 19
	s_add_u32 s50, s90, s8
	s_addc_u32 s51, s91, s9
	s_and_b64 s[8:9], exec, s[4:5]
	s_cselect_b32 s45, s7, s51
	s_cselect_b32 s58, s6, s50
	s_add_u32 s56, s30, 0x100
	s_addc_u32 s57, s31, 0
	s_add_u32 s26, s6, 0x100
	s_addc_u32 s27, s7, 0
	s_add_u32 s8, s30, 0x180
	s_addc_u32 s9, s31, 0
	ds_read_b128 v[34:37], v224
	ds_read_b128 v[38:41], v224 offset:1024
	ds_read_b128 v[42:45], v224 offset:2048
	ds_read_b128 v[46:49], v224 offset:3072
	ds_read_b128 v[50:53], v224 offset:4096
	ds_read_b128 v[54:57], v224 offset:5120
	ds_read_b128 v[58:61], v224 offset:6144
	ds_read_b128 v[62:65], v224 offset:7168
	s_add_u32 s24, s6, 0x180
	s_addc_u32 s25, s7, 0
	s_add_u32 s60, s30, 0x40080
	s_addc_u32 s61, s31, 0
	s_add_u32 m0, s14, 0xc000
	s_nop 0
	global_load_lds_dwordx4 v1, s[60:61]
	s_nop 0
	s_add_u32 m0, s14, 0xe000
	s_nop 0
	global_load_lds_dwordx4 v213, s[60:61]
	s_waitcnt vmcnt(8)
	s_waitcnt lgkmcnt(0)
	s_barrier
	v_mfma_f32_16x16x32_f16 v[66:69], v[2:5], v[34:37], 0
	s_setprio 1
	v_mfma_f32_16x16x32_f16 v[66:69], v[6:9], v[38:41], v[66:69]
	v_mfma_f32_16x16x32_f16 v[70:73], v[10:13], v[34:37], 0
	v_mfma_f32_16x16x32_f16 v[70:73], v[14:17], v[38:41], v[70:73]
	v_mfma_f32_16x16x32_f16 v[78:81], v[10:13], v[42:45], 0
	v_mfma_f32_16x16x32_f16 v[78:81], v[14:17], v[46:49], v[78:81]
	v_mfma_f32_16x16x32_f16 v[82:85], v[2:5], v[50:53], 0
	v_mfma_f32_16x16x32_f16 v[82:85], v[6:9], v[54:57], v[82:85]
	v_mfma_f32_16x16x32_f16 v[90:93], v[2:5], v[58:61], 0
	v_mfma_f32_16x16x32_f16 v[90:93], v[6:9], v[62:65], v[90:93]
	v_mfma_f32_16x16x32_f16 v[94:97], v[10:13], v[58:61], 0
	v_mfma_f32_16x16x32_f16 v[94:97], v[14:17], v[62:65], v[94:97]
	v_mfma_f32_16x16x32_f16 v[74:77], v[2:5], v[42:45], 0
	v_mfma_f32_16x16x32_f16 v[74:77], v[6:9], v[46:49], v[74:77]
	v_mfma_f32_16x16x32_f16 v[86:89], v[10:13], v[50:53], 0
	v_mfma_f32_16x16x32_f16 v[86:89], v[14:17], v[54:57], v[86:89]
	v_mfma_f32_16x16x32_f16 v[98:101], v[18:21], v[34:37], 0
	v_mfma_f32_16x16x32_f16 v[98:101], v[22:25], v[38:41], v[98:101]
	v_mfma_f32_16x16x32_f16 v[34:37], v[26:29], v[34:37], 0
	v_mfma_f32_16x16x32_f16 v[34:37], v[30:33], v[38:41], v[34:37]
	v_mfma_f32_16x16x32_f16 v[38:41], v[18:21], v[42:45], 0
	v_mfma_f32_16x16x32_f16 v[38:41], v[22:25], v[46:49], v[38:41]
	v_mfma_f32_16x16x32_f16 v[42:45], v[26:29], v[42:45], 0
	v_mfma_f32_16x16x32_f16 v[42:45], v[30:33], v[46:49], v[42:45]
	v_mfma_f32_16x16x32_f16 v[46:49], v[18:21], v[50:53], 0
	v_mfma_f32_16x16x32_f16 v[46:49], v[22:25], v[54:57], v[46:49]
	v_mfma_f32_16x16x32_f16 v[50:53], v[26:29], v[50:53], 0
	v_mfma_f32_16x16x32_f16 v[50:53], v[30:33], v[54:57], v[50:53]
	v_mfma_f32_16x16x32_f16 v[54:57], v[18:21], v[58:61], 0
	v_mfma_f32_16x16x32_f16 v[54:57], v[22:25], v[62:65], v[54:57]
	v_mfma_f32_16x16x32_f16 v[58:61], v[26:29], v[58:61], 0
	v_mfma_f32_16x16x32_f16 v[58:61], v[30:33], v[62:65], v[58:61]
	s_barrier
	s_setprio 0
	ds_read_b128 v[62:65], v224 offset:16384
	ds_read_b128 v[102:105], v224 offset:17408
	ds_read_b128 v[106:109], v224 offset:18432
	ds_read_b128 v[110:113], v224 offset:19456
	ds_read_b128 v[114:117], v224 offset:20480
	ds_read_b128 v[118:121], v224 offset:21504
	ds_read_b128 v[122:125], v224 offset:22528
	ds_read_b128 v[126:129], v224 offset:23552
	s_add_u32 m0, s14, 0x10000
	s_nop 0
	global_load_lds_dwordx4 v209, s[26:27]
	s_nop 0
	s_add_u32 m0, s14, 0x12000
	s_nop 0
	global_load_lds_dwordx4 v219, s[26:27]
	s_add_u32 s26, s6, 0x40100
	s_addc_u32 s27, s7, 0
	s_add_u32 m0, s14, 0x14000
	s_nop 0
	global_load_lds_dwordx4 v209, s[26:27]
	s_nop 0
	s_add_u32 m0, s14, 0x16000
	s_nop 0
	global_load_lds_dwordx4 v219, s[26:27]
	s_nop 0
	s_add_u32 m0, s14, 0
	s_nop 0
	global_load_lds_dwordx4 v1, s[56:57]
	s_nop 0
	s_add_u32 m0, s14, 0x2000
	s_nop 0
	global_load_lds_dwordx4 v213, s[56:57]
	s_waitcnt vmcnt(8)
	s_waitcnt lgkmcnt(0)
	s_barrier
	v_mfma_f32_16x16x32_f16 v[130:133], v[2:5], v[62:65], 0
	s_setprio 1
	v_mfma_f32_16x16x32_f16 v[134:137], v[6:9], v[102:105], v[130:133]
	v_mfma_f32_16x16x32_f16 v[130:133], v[10:13], v[62:65], 0
	v_mfma_f32_16x16x32_f16 v[146:149], v[14:17], v[102:105], v[130:133]
	v_mfma_f32_16x16x32_f16 v[130:133], v[2:5], v[106:109], 0
	v_mfma_f32_16x16x32_f16 v[158:161], v[6:9], v[110:113], v[130:133]
	v_mfma_f32_16x16x32_f16 v[130:133], v[10:13], v[106:109], 0
	v_mfma_f32_16x16x32_f16 v[162:165], v[14:17], v[110:113], v[130:133]
	v_mfma_f32_16x16x32_f16 v[130:133], v[2:5], v[114:117], 0
	v_mfma_f32_16x16x32_f16 v[166:169], v[6:9], v[118:121], v[130:133]
	v_mfma_f32_16x16x32_f16 v[2:5], v[2:5], v[122:125], 0
	v_mfma_f32_16x16x32_f16 v[2:5], v[6:9], v[126:129], v[2:5]
	v_mfma_f32_16x16x32_f16 v[6:9], v[10:13], v[122:125], 0
	v_mfma_f32_16x16x32_f16 v[6:9], v[14:17], v[126:129], v[6:9]
	v_mfma_f32_16x16x32_f16 v[130:133], v[10:13], v[114:117], 0
	v_mfma_f32_16x16x32_f16 v[170:173], v[14:17], v[118:121], v[130:133]
	v_mfma_f32_16x16x32_f16 v[10:13], v[18:21], v[62:65], 0
	v_mfma_f32_16x16x32_f16 v[174:177], v[22:25], v[102:105], v[10:13]
	v_mfma_f32_16x16x32_f16 v[10:13], v[26:29], v[62:65], 0
	v_mfma_f32_16x16x32_f16 v[178:181], v[30:33], v[102:105], v[10:13]
	v_mfma_f32_16x16x32_f16 v[10:13], v[18:21], v[106:109], 0
	v_mfma_f32_16x16x32_f16 v[182:185], v[22:25], v[110:113], v[10:13]
	v_mfma_f32_16x16x32_f16 v[10:13], v[26:29], v[106:109], 0
	v_mfma_f32_16x16x32_f16 v[110:113], v[30:33], v[110:113], v[10:13]
	v_mfma_f32_16x16x32_f16 v[10:13], v[18:21], v[114:117], 0
	v_mfma_f32_16x16x32_f16 v[186:189], v[22:25], v[118:121], v[10:13]
	v_mfma_f32_16x16x32_f16 v[10:13], v[26:29], v[114:117], 0
	v_mfma_f32_16x16x32_f16 v[190:193], v[30:33], v[118:121], v[10:13]
	v_mfma_f32_16x16x32_f16 v[10:13], v[18:21], v[122:125], 0
	v_mfma_f32_16x16x32_f16 v[194:197], v[22:25], v[126:129], v[10:13]
	v_mfma_f32_16x16x32_f16 v[10:13], v[26:29], v[122:125], 0
	v_mfma_f32_16x16x32_f16 v[122:125], v[30:33], v[126:129], v[10:13]
	s_barrier
; #define PG8_STAGE(bufoff, gbase, voff) do { if constexpr (ABL & 1) break; glds16s<(bufoff)>((voff)[0], (const void*)(gbase), ldsbw); glds16s<(bufoff) + 8192>((voff)[1], (const void*)(gbase), ldsbw); } while (0)
; #define PG8_LDA(dst, b, h) do { if constexpr (ABL & 4) break; _Pragma("unroll") for (int m = 0; m < 4; ++m) _Pragma("unroll") for (int k = 0; k < 2; ++k) dst[m][k] = *(const LAS f16x8*)(lds + PG8_SA(b, h) + aoff + m * 2048 + k * 1024); } while (0)
; #define PG8_LDB(dst, b, h) do { if constexpr (ABL & 4) break; _Pragma("unroll") for (int n = 0; n < 2; ++n) _Pragma("unroll") for (int k = 0; k < 2; ++k) dst[n][k] = *(const LAS f16x8*)(lds + PG8_SB(b, h) + boff + n * 2048 + k * 1024); } while (0)
; #define PG8_MMA(ai, bj, At, Bt) do { if constexpr (ABL & 2) break; __builtin_amdgcn_s_setprio(1); _Pragma("unroll") for (int m = 0; m < 4; ++m) _Pragma("unroll") for (int n = 0; n < 2; ++n) _Pragma("unroll") for (int k = 0; k < 2; ++k) \
;         acc[ai][bj][m][n] = __builtin_amdgcn_mfma_f32_16x16x32_f16(Bt[n][k], At[m][k], acc[ai][bj][m][n], 0, 0, 0); __builtin_amdgcn_s_setprio(0); } while (0)
; #define PG8_WAIT_V(n) asm volatile("s_waitcnt vmcnt(" #n ")" ::: "memory")
; #define PG8_WAIT_L(n) asm volatile("s_waitcnt lgkmcnt(" #n ")" ::: "memory")
; #define PG8_BAR __builtin_amdgcn_s_barrier()
; #define PG8_SCHED __builtin_amdgcn_sched_barrier(0)
;     ...
;             PG8_LDB(B0, 1, 0); PG8_LDB(B1, 1, 1); PG8_SCHED; PG8_LDA(At, 1, 0); if (!fin) PG8_STAGE(PG8_SA(0, 1), a2 + hstep, voffA);
;             if (!fin) PG8_WAIT_V(8); else PG8_WAIT_V(0); PG8_WAIT_L(0); PG8_BAR; PG8_MMA(0, 0, At, B0); PG8_MMA(0, 1, At, B1); PG8_BAR; PG8_SCHED;
;             PG8_LDA(At, 1, 1); if (!fin) { PG8_STAGE(PG8_SB(1, 0), b3, voffB); PG8_STAGE(PG8_SB(1, 1), b3 + hstep, voffB); PG8_STAGE(PG8_SA(1, 0), a3, voffA); }
;             if (!fin) PG8_WAIT_V(8); PG8_WAIT_L(0); PG8_BAR; PG8_MMA(1, 0, At, B0); PG8_MMA(1, 1, At, B1); PG8_BAR; PG8_SCHED;
	s_setprio 0
	s_nop 4
	ds_read_b128 v[10:13], v225
	ds_read_b128 v[14:17], v225 offset:1024
	ds_read_b128 v[18:21], v225 offset:2048
	ds_read_b128 v[22:25], v225 offset:3072
	ds_read_b128 v[198:201], v226
	ds_read_b128 v[214:217], v226 offset:1024
	ds_read_b128 v[228:231], v226 offset:2048
	ds_read_b128 v[232:235], v226 offset:3072
	ds_read_b128 v[26:29], v224 offset:32768
	ds_read_b128 v[30:33], v224 offset:33792
	ds_read_b128 v[62:65], v224 offset:34816
	ds_read_b128 v[114:117], v224 offset:35840
	ds_read_b128 v[236:239], v224 offset:36864
	ds_read_b128 v[240:243], v224 offset:37888
	ds_read_b128 v[244:247], v224 offset:38912
	ds_read_b128 v[248:251], v224 offset:39936
	s_add_u32 s26, s30, 0x40100
	s_addc_u32 s27, s31, 0
	s_add_u32 m0, s14, 0x4000
	s_nop 0
	global_load_lds_dwordx4 v1, s[26:27]
	s_nop 0
	s_add_u32 m0, s14, 0x6000
	s_nop 0
	global_load_lds_dwordx4 v213, s[26:27]
	s_waitcnt vmcnt(8)
	s_waitcnt lgkmcnt(0)
	s_barrier
	v_mfma_f32_16x16x32_f16 v[66:69], v[10:13], v[26:29], v[66:69]
	s_setprio 1
	v_mfma_f32_16x16x32_f16 v[154:157], v[14:17], v[30:33], v[66:69]
	v_mfma_f32_16x16x32_f16 v[66:69], v[18:21], v[26:29], v[70:73]
	v_mfma_f32_16x16x32_f16 v[150:153], v[22:25], v[30:33], v[66:69]
	v_mfma_f32_16x16x32_f16 v[66:69], v[10:13], v[62:65], v[74:77]
	v_mfma_f32_16x16x32_f16 v[130:133], v[14:17], v[114:117], v[66:69]
	v_mfma_f32_16x16x32_f16 v[66:69], v[18:21], v[62:65], v[78:81]
	v_mfma_f32_16x16x32_f16 v[126:129], v[22:25], v[114:117], v[66:69]
	v_mfma_f32_16x16x32_f16 v[66:69], v[10:13], v[236:239], v[82:85]
	v_mfma_f32_16x16x32_f16 v[106:109], v[14:17], v[240:243], v[66:69]
	v_mfma_f32_16x16x32_f16 v[66:69], v[18:21], v[236:239], v[86:89]
	v_mfma_f32_16x16x32_f16 v[102:105], v[22:25], v[240:243], v[66:69]
	v_mfma_f32_16x16x32_f16 v[66:69], v[10:13], v[244:247], v[90:93]
	v_mfma_f32_16x16x32_f16 v[82:85], v[14:17], v[248:251], v[66:69]
	v_mfma_f32_16x16x32_f16 v[66:69], v[18:21], v[244:247], v[94:97]
	v_mfma_f32_16x16x32_f16 v[78:81], v[22:25], v[248:251], v[66:69]
	v_mfma_f32_16x16x32_f16 v[66:69], v[198:201], v[26:29], v[98:101]
	v_mfma_f32_16x16x32_f16 v[142:145], v[214:217], v[30:33], v[66:69]
	v_mfma_f32_16x16x32_f16 v[26:29], v[228:231], v[26:29], v[34:37]
	v_mfma_f32_16x16x32_f16 v[138:141], v[232:235], v[30:33], v[26:29]
	v_mfma_f32_16x16x32_f16 v[26:29], v[198:201], v[62:65], v[38:41]
	v_mfma_f32_16x16x32_f16 v[118:121], v[214:217], v[114:117], v[26:29]
	v_mfma_f32_16x16x32_f16 v[26:29], v[228:231], v[62:65], v[42:45]
	v_mfma_f32_16x16x32_f16 v[114:117], v[232:235], v[114:117], v[26:29]
	v_mfma_f32_16x16x32_f16 v[26:29], v[198:201], v[236:239], v[46:49]
	v_mfma_f32_16x16x32_f16 v[94:97], v[214:217], v[240:243], v[26:29]
	v_mfma_f32_16x16x32_f16 v[26:29], v[228:231], v[236:239], v[50:53]
	v_mfma_f32_16x16x32_f16 v[90:93], v[232:235], v[240:243], v[26:29]
	v_mfma_f32_16x16x32_f16 v[26:29], v[198:201], v[244:247], v[54:57]
	v_mfma_f32_16x16x32_f16 v[70:73], v[214:217], v[248:251], v[26:29]
	v_mfma_f32_16x16x32_f16 v[26:29], v[228:231], v[244:247], v[58:61]
	v_mfma_f32_16x16x32_f16 v[66:69], v[232:235], v[248:251], v[26:29]
	s_barrier
	s_setprio 0
	ds_read_b128 v[34:37], v224 offset:49152
	ds_read_b128 v[38:41], v224 offset:50176
	ds_read_b128 v[74:77], v224 offset:51200
	ds_read_b128 v[86:89], v224 offset:52224
	ds_read_b128 v[98:101], v224 offset:53248
	ds_read_b128 v[236:239], v224 offset:54272
	ds_read_b128 v[240:243], v224 offset:55296
	ds_read_b128 v[244:247], v224 offset:56320
	s_add_u32 m0, s14, 0x18000
	s_nop 0
	global_load_lds_dwordx4 v209, s[24:25]
	s_nop 0
	s_add_u32 m0, s14, 0x1a000
	s_nop 0
	global_load_lds_dwordx4 v219, s[24:25]
	s_add_u32 s24, s6, 0x40180
	s_addc_u32 s25, s7, 0
	s_add_u32 m0, s14, 0x1c000
	s_nop 0
	global_load_lds_dwordx4 v209, s[24:25]
	s_nop 0
	s_add_u32 m0, s14, 0x1e000
	s_nop 0
	global_load_lds_dwordx4 v219, s[24:25]
	s_nop 0
	s_add_u32 m0, s14, 0x8000
	s_nop 0
	global_load_lds_dwordx4 v1, s[8:9]
	s_nop 0
	s_add_u32 m0, s14, 0xa000
	s_nop 0
	global_load_lds_dwordx4 v213, s[8:9]
	s_waitcnt vmcnt(8)
	s_waitcnt lgkmcnt(0)
	s_barrier
	v_mfma_f32_16x16x32_f16 v[26:29], v[10:13], v[34:37], v[134:137]
	s_setprio 1
	v_mfma_f32_16x16x32_f16 v[62:65], v[14:17], v[38:41], v[26:29]
	v_mfma_f32_16x16x32_f16 v[26:29], v[22:25], v[38:41], v[146:149]
	v_mfma_f32_16x16x32_f16 v[58:61], v[18:21], v[34:37], v[26:29]
	v_mfma_f32_16x16x32_f16 v[26:29], v[10:13], v[74:77], v[158:161]
	v_mfma_f32_16x16x32_f16 v[46:49], v[14:17], v[86:89], v[26:29]
	v_mfma_f32_16x16x32_f16 v[26:29], v[22:25], v[86:89], v[162:165]
	v_mfma_f32_16x16x32_f16 v[42:45], v[18:21], v[74:77], v[26:29]
	v_mfma_f32_16x16x32_f16 v[26:29], v[10:13], v[98:101], v[166:169]
	v_mfma_f32_16x16x32_f16 v[30:33], v[14:17], v[236:239], v[26:29]
	v_mfma_f32_16x16x32_f16 v[2:5], v[14:17], v[244:247], v[2:5]
	v_mfma_f32_16x16x32_f16 v[14:17], v[10:13], v[240:243], v[2:5]
	v_mfma_f32_16x16x32_f16 v[2:5], v[18:21], v[240:243], v[6:9]
	v_mfma_f32_16x16x32_f16 v[10:13], v[22:25], v[244:247], v[2:5]
	v_mfma_f32_16x16x32_f16 v[26:29], v[22:25], v[236:239], v[170:173]
	v_mfma_f32_16x16x32_f16 v[26:29], v[18:21], v[98:101], v[26:29]
	v_mfma_f32_16x16x32_f16 v[2:5], v[198:201], v[34:37], v[174:177]
	v_mfma_f32_16x16x32_f16 v[54:57], v[214:217], v[38:41], v[2:5]
	v_mfma_f32_16x16x32_f16 v[2:5], v[232:235], v[38:41], v[178:181]
	v_mfma_f32_16x16x32_f16 v[50:53], v[228:231], v[34:37], v[2:5]
	v_mfma_f32_16x16x32_f16 v[2:5], v[198:201], v[74:77], v[182:185]
	v_mfma_f32_16x16x32_f16 v[38:41], v[214:217], v[86:89], v[2:5]
	v_mfma_f32_16x16x32_f16 v[2:5], v[232:235], v[86:89], v[110:113]
	v_mfma_f32_16x16x32_f16 v[34:37], v[228:231], v[74:77], v[2:5]
	v_mfma_f32_16x16x32_f16 v[2:5], v[198:201], v[98:101], v[186:189]
	v_mfma_f32_16x16x32_f16 v[22:25], v[214:217], v[236:239], v[2:5]
	v_mfma_f32_16x16x32_f16 v[2:5], v[232:235], v[236:239], v[190:193]
	v_mfma_f32_16x16x32_f16 v[18:21], v[228:231], v[98:101], v[2:5]
	v_mfma_f32_16x16x32_f16 v[2:5], v[198:201], v[240:243], v[194:197]
	v_mfma_f32_16x16x32_f16 v[6:9], v[214:217], v[244:247], v[2:5]
	v_mfma_f32_16x16x32_f16 v[2:5], v[232:235], v[244:247], v[122:125]
	v_mfma_f32_16x16x32_f16 v[2:5], v[228:231], v[240:243], v[2:5]
	s_barrier
	s_setprio 0
	s_add_u32 s30, s6, 0x200
	s_addc_u32 s31, s7, 0
	s_mov_b32 s59, 0
	s_branch .LBB0_750
; #define PG8_STAGE(bufoff, gbase, voff) do { if constexpr (ABL & 1) break; glds16s<(bufoff)>((voff)[0], (const void*)(gbase), ldsbw); glds16s<(bufoff) + 8192>((voff)[1], (const void*)(gbase), ldsbw); } while (0)
; #define PG8_LDA(dst, b, h) do { if constexpr (ABL & 4) break; _Pragma("unroll") for (int m = 0; m < 4; ++m) _Pragma("unroll") for (int k = 0; k < 2; ++k) dst[m][k] = *(const LAS f16x8*)(lds + PG8_SA(b, h) + aoff + m * 2048 + k * 1024); } while (0)
; #define PG8_LDB(dst, b, h) do { if constexpr (ABL & 4) break; _Pragma("unroll") for (int n = 0; n < 2; ++n) _Pragma("unroll") for (int k = 0; k < 2; ++k) dst[n][k] = *(const LAS f16x8*)(lds + PG8_SB(b, h) + boff + n * 2048 + k * 1024); } while (0)
; #define PG8_MMA(ai, bj, At, Bt) do { if constexpr (ABL & 2) break; __builtin_amdgcn_s_setprio(1); _Pragma("unroll") for (int m = 0; m < 4; ++m) _Pragma("unroll") for (int n = 0; n < 2; ++n) _Pragma("unroll") for (int k = 0; k < 2; ++k) \
;         acc[ai][bj][m][n] = __builtin_amdgcn_mfma_f32_16x16x32_f16(Bt[n][k], At[m][k], acc[ai][bj][m][n], 0, 0, 0); __builtin_amdgcn_s_setprio(0); } while (0)
; #define PG8_WAIT_V(n) asm volatile("s_waitcnt vmcnt(" #n ")" ::: "memory")
;     ...
;             PG8_LDB(B0, 0, 0); PG8_LDB(B1, 0, 1); PG8_SCHED; PG8_LDA(At, 0, 0); PG8_STAGE(PG8_SA(1, 1), a1 + hstep, voffA);
;             PG8_WAIT_V(8); PG8_WAIT_L(0); PG8_BAR; PG8_MMAF(0, 0, At, B0); PG8_MMAF(0, 1, At, B1); PG8_BAR; PG8_SCHED;
;             const bool fin = last && !has_next;
;             PG8_LDA(At, 0, 1); if (!fin) { PG8_STAGE(PG8_SB(0, 0), b2, voffB); PG8_STAGE(PG8_SB(0, 1), b2 + hstep, voffB); PG8_STAGE(PG8_SA(0, 0), a2, voffA); }
;             if (!fin) PG8_WAIT_V(8); else PG8_WAIT_V(2); PG8_WAIT_L(0); PG8_BAR; PG8_MMAF(1, 0, At, B0); PG8_MMAF(1, 1, At, B1); PG8_BAR; PG8_SCHED;
;             PG8_LDB(B0, 1, 0); PG8_LDB(B1, 1, 1); PG8_SCHED; PG8_LDA(At, 1, 0); if (!fin) PG8_STAGE(PG8_SA(0, 1), a2 + hstep, voffA);
;             if (!fin) PG8_WAIT_V(8); else PG8_WAIT_V(0); PG8_WAIT_L(0); PG8_BAR; PG8_MMA(0, 0, At, B0); PG8_MMA(0, 1, At, B1); PG8_BAR; PG8_SCHED;
;             PG8_LDA(At, 1, 1); if (!fin) { PG8_STAGE(PG8_SB(1, 0), b3, voffB); PG8_STAGE(PG8_SB(1, 1), b3 + hstep, voffB); PG8_STAGE(PG8_SA(1, 0), a3, voffA); }
;             if (!fin) PG8_WAIT_V(8); PG8_WAIT_L(0); PG8_BAR; PG8_MMA(1, 0, At, B0); PG8_MMA(1, 1, At, B1); PG8_BAR; PG8_SCHED;
.LBB0_749:
	s_waitcnt lgkmcnt(0)
	s_barrier
	v_mfma_f32_16x16x32_f16 v[62:65], v[162:165], v[186:189], v[62:65]
	s_setprio 1
	v_mfma_f32_16x16x32_f16 v[62:65], v[166:169], v[190:193], v[62:65]
	v_mfma_f32_16x16x32_f16 v[58:61], v[158:161], v[190:193], v[58:61]
	v_mfma_f32_16x16x32_f16 v[58:61], v[146:149], v[186:189], v[58:61]
	v_mfma_f32_16x16x32_f16 v[42:45], v[146:149], v[178:181], v[42:45]
	v_mfma_f32_16x16x32_f16 v[42:45], v[158:161], v[182:185], v[42:45]
	v_mfma_f32_16x16x32_f16 v[46:49], v[166:169], v[182:185], v[46:49]
	v_mfma_f32_16x16x32_f16 v[46:49], v[162:165], v[178:181], v[46:49]
	v_mfma_f32_16x16x32_f16 v[30:33], v[162:165], v[170:173], v[30:33]
	v_mfma_f32_16x16x32_f16 v[30:33], v[166:169], v[174:177], v[30:33]
	v_mfma_f32_16x16x32_f16 v[26:29], v[158:161], v[174:177], v[26:29]
	v_mfma_f32_16x16x32_f16 v[26:29], v[146:149], v[170:173], v[26:29]
	v_mfma_f32_16x16x32_f16 v[10:13], v[146:149], v[122:125], v[10:13]
	v_mfma_f32_16x16x32_f16 v[10:13], v[158:161], v[134:137], v[10:13]
	v_mfma_f32_16x16x32_f16 v[14:17], v[166:169], v[134:137], v[14:17]
	v_mfma_f32_16x16x32_f16 v[14:17], v[162:165], v[122:125], v[14:17]
	v_mfma_f32_16x16x32_f16 v[6:9], v[98:101], v[122:125], v[6:9]
	v_mfma_f32_16x16x32_f16 v[6:9], v[110:113], v[134:137], v[6:9]
	v_mfma_f32_16x16x32_f16 v[54:57], v[110:113], v[190:193], v[54:57]
	v_mfma_f32_16x16x32_f16 v[54:57], v[98:101], v[186:189], v[54:57]
	v_mfma_f32_16x16x32_f16 v[50:53], v[74:77], v[186:189], v[50:53]
	v_mfma_f32_16x16x32_f16 v[50:53], v[86:89], v[190:193], v[50:53]
	v_mfma_f32_16x16x32_f16 v[34:37], v[86:89], v[182:185], v[34:37]
	v_mfma_f32_16x16x32_f16 v[34:37], v[74:77], v[178:181], v[34:37]
	v_mfma_f32_16x16x32_f16 v[38:41], v[98:101], v[178:181], v[38:41]
	v_mfma_f32_16x16x32_f16 v[38:41], v[110:113], v[182:185], v[38:41]
	v_mfma_f32_16x16x32_f16 v[22:25], v[110:113], v[174:177], v[22:25]
	v_mfma_f32_16x16x32_f16 v[22:25], v[98:101], v[170:173], v[22:25]
	v_mfma_f32_16x16x32_f16 v[18:21], v[74:77], v[170:173], v[18:21]
	v_mfma_f32_16x16x32_f16 v[18:21], v[86:89], v[174:177], v[18:21]
	v_mfma_f32_16x16x32_f16 v[2:5], v[86:89], v[134:137], v[2:5]
	v_mfma_f32_16x16x32_f16 v[2:5], v[74:77], v[122:125], v[2:5]
	s_barrier
	s_setprio 0
	s_add_i32 s59, s59, 2
	s_add_u32 s30, s30, 0x100
	s_addc_u32 s31, s31, 0
	s_cmp_gt_u32 s59, 13
	s_cbranch_scc1 .LBB0_760
.LBB0_750:
	ds_read_b128 v[146:149], v222
	ds_read_b128 v[158:161], v222 offset:1024
	ds_read_b128 v[162:165], v222 offset:2048
	ds_read_b128 v[166:169], v222 offset:3072
	ds_read_b128 v[74:77], v223
	ds_read_b128 v[86:89], v223 offset:1024
	ds_read_b128 v[98:101], v223 offset:2048
	ds_read_b128 v[110:113], v223 offset:3072
	s_mov_b64 s[6:7], s[56:57]
	s_add_u32 s56, s6, 0x100
	s_addc_u32 s57, s7, 0
	s_cmp_eq_u32 s59, 12
	s_cselect_b64 s[26:27], -1, 0
	s_and_b64 s[8:9], s[26:27], exec
	s_cselect_b32 s25, s47, s57
	s_cselect_b32 s24, s55, s56
	s_cselect_b32 s9, s45, s31
	s_cselect_b32 s8, s58, s30
	ds_read_b128 v[170:173], v224
	ds_read_b128 v[174:177], v224 offset:1024
	ds_read_b128 v[178:181], v224 offset:2048
	ds_read_b128 v[182:185], v224 offset:3072
	ds_read_b128 v[186:189], v224 offset:4096
	ds_read_b128 v[190:193], v224 offset:5120
	ds_read_b128 v[194:197], v224 offset:6144
	ds_read_b128 v[198:201], v224 offset:7168
	s_add_u32 s6, s6, 0x40080
	s_addc_u32 s7, s7, 0
	s_add_u32 m0, s14, 0xc000
	s_nop 0
	global_load_lds_dwordx4 v1, s[6:7]
	s_nop 0
	s_add_u32 m0, s14, 0xe000
	s_nop 0
	global_load_lds_dwordx4 v213, s[6:7]
	s_waitcnt vmcnt(8)
	s_waitcnt lgkmcnt(0)
	s_barrier
	v_mfma_f32_16x16x32_f16 v[122:125], v[146:149], v[170:173], v[154:157]
	s_setprio 1
	v_mfma_f32_16x16x32_f16 v[122:125], v[158:161], v[174:177], v[122:125]
	v_mfma_f32_16x16x32_f16 v[134:137], v[166:169], v[174:177], v[150:153]
	v_mfma_f32_16x16x32_f16 v[134:137], v[162:165], v[170:173], v[134:137]
	v_mfma_f32_16x16x32_f16 v[126:129], v[162:165], v[178:181], v[126:129]
	v_mfma_f32_16x16x32_f16 v[126:129], v[166:169], v[182:185], v[126:129]
	v_mfma_f32_16x16x32_f16 v[130:133], v[158:161], v[182:185], v[130:133]
	v_mfma_f32_16x16x32_f16 v[130:133], v[146:149], v[178:181], v[130:133]
	v_mfma_f32_16x16x32_f16 v[106:109], v[146:149], v[186:189], v[106:109]
	v_mfma_f32_16x16x32_f16 v[106:109], v[158:161], v[190:193], v[106:109]
	v_mfma_f32_16x16x32_f16 v[102:105], v[166:169], v[190:193], v[102:105]
	v_mfma_f32_16x16x32_f16 v[102:105], v[162:165], v[186:189], v[102:105]
	v_mfma_f32_16x16x32_f16 v[78:81], v[162:165], v[194:197], v[78:81]
	v_mfma_f32_16x16x32_f16 v[78:81], v[166:169], v[198:201], v[78:81]
	v_mfma_f32_16x16x32_f16 v[82:85], v[158:161], v[198:201], v[82:85]
	v_mfma_f32_16x16x32_f16 v[82:85], v[146:149], v[194:197], v[82:85]
	v_mfma_f32_16x16x32_f16 v[70:73], v[74:77], v[194:197], v[70:73]
	v_mfma_f32_16x16x32_f16 v[70:73], v[86:89], v[198:201], v[70:73]
	v_mfma_f32_16x16x32_f16 v[142:145], v[86:89], v[174:177], v[142:145]
	v_mfma_f32_16x16x32_f16 v[142:145], v[74:77], v[170:173], v[142:145]
	v_mfma_f32_16x16x32_f16 v[138:141], v[98:101], v[170:173], v[138:141]
	v_mfma_f32_16x16x32_f16 v[138:141], v[110:113], v[174:177], v[138:141]
	v_mfma_f32_16x16x32_f16 v[114:117], v[110:113], v[182:185], v[114:117]
	v_mfma_f32_16x16x32_f16 v[114:117], v[98:101], v[178:181], v[114:117]
	v_mfma_f32_16x16x32_f16 v[118:121], v[74:77], v[178:181], v[118:121]
	v_mfma_f32_16x16x32_f16 v[118:121], v[86:89], v[182:185], v[118:121]
	v_mfma_f32_16x16x32_f16 v[94:97], v[86:89], v[190:193], v[94:97]
	v_mfma_f32_16x16x32_f16 v[94:97], v[74:77], v[186:189], v[94:97]
	v_mfma_f32_16x16x32_f16 v[90:93], v[98:101], v[186:189], v[90:93]
	v_mfma_f32_16x16x32_f16 v[90:93], v[110:113], v[190:193], v[90:93]
	v_mfma_f32_16x16x32_f16 v[66:69], v[110:113], v[198:201], v[66:69]
	v_mfma_f32_16x16x32_f16 v[66:69], v[98:101], v[194:197], v[66:69]
	s_barrier
	s_setprio 0
	ds_read_b128 v[186:189], v224 offset:16384
	ds_read_b128 v[190:193], v224 offset:17408
	ds_read_b128 v[178:181], v224 offset:18432
	ds_read_b128 v[182:185], v224 offset:19456
	ds_read_b128 v[170:173], v224 offset:20480
	ds_read_b128 v[174:177], v224 offset:21504
	ds_read_b128 v[150:153], v224 offset:22528
	ds_read_b128 v[154:157], v224 offset:23552
	s_and_b64 s[6:7], s[4:5], s[26:27]
	s_mov_b64 s[26:27], -1
	s_and_b64 vcc, exec, s[6:7]
	s_cbranch_vccnz .LBB0_752
	s_add_u32 m0, s14, 0x10000
	s_nop 0
	global_load_lds_dwordx4 v209, s[8:9]
	s_nop 0
	s_add_u32 m0, s14, 0x12000
	s_nop 0
	global_load_lds_dwordx4 v219, s[8:9]
	s_add_u32 s26, s8, 0x40000
	s_addc_u32 s27, s9, 0
	s_add_u32 m0, s14, 0x14000
	s_nop 0
	global_load_lds_dwordx4 v209, s[26:27]
	s_nop 0
	s_add_u32 m0, s14, 0x16000
	s_nop 0
	global_load_lds_dwordx4 v219, s[26:27]
	s_mov_b64 s[26:27], 0
	s_add_u32 m0, s14, 0
	s_nop 0
	global_load_lds_dwordx4 v1, s[24:25]
	s_nop 0
	s_add_u32 m0, s14, 0x2000
	s_nop 0
	global_load_lds_dwordx4 v213, s[24:25]
	s_waitcnt vmcnt(8)

; #define PG8_STAGE(bufoff, gbase, voff) do { if constexpr (ABL & 1) break; glds16s<(bufoff)>((voff)[0], (const void*)(gbase), ldsbw); glds16s<(bufoff) + 8192>((voff)[1], (const void*)(gbase), ldsbw); } while (0)
; #define PG8_LDA(dst, b, h) do { if constexpr (ABL & 4) break; _Pragma("unroll") for (int m = 0; m < 4; ++m) _Pragma("unroll") for (int k = 0; k < 2; ++k) dst[m][k] = *(const LAS f16x8*)(lds + PG8_SA(b, h) + aoff + m * 2048 + k * 1024); } while (0)
; #define PG8_LDB(dst, b, h) do { if constexpr (ABL & 4) break; _Pragma("unroll") for (int n = 0; n < 2; ++n) _Pragma("unroll") for (int k = 0; k < 2; ++k) dst[n][k] = *(const LAS f16x8*)(lds + PG8_SB(b, h) + boff + n * 2048 + k * 1024); } while (0)
; #define PG8_MMA(ai, bj, At, Bt) do { if constexpr (ABL & 2) break; __builtin_amdgcn_s_setprio(1); _Pragma("unroll") for (int m = 0; m < 4; ++m) _Pragma("unroll") for (int n = 0; n < 2; ++n) _Pragma("unroll") for (int k = 0; k < 2; ++k) \
;         acc[ai][bj][m][n] = __builtin_amdgcn_mfma_f32_16x16x32_f16(Bt[n][k], At[m][k], acc[ai][bj][m][n], 0, 0, 0); __builtin_amdgcn_s_setprio(0); } while (0)
; #define PG8_MMAF(ai, bj, At, Bt) do { if (t == 0) PG8_MMA0(ai, bj, At, Bt); else PG8_MMA(ai, bj, At, Bt); } while (0)
; #define PG8_WAIT_V(n) asm volatile("s_waitcnt vmcnt(" #n ")" ::: "memory")
; #define PG8_WAIT_L(n) asm volatile("s_waitcnt lgkmcnt(" #n ")" ::: "memory")
; #define PG8_BAR __builtin_amdgcn_s_barrier()
; #define PG8_SCHED __builtin_amdgcn_sched_barrier(0)
;     ...
;             if (!fin) PG8_WAIT_V(8); else PG8_WAIT_V(2); PG8_WAIT_L(0); PG8_BAR; PG8_MMAF(1, 0, At, B0); PG8_MMAF(1, 1, At, B1); PG8_BAR; PG8_SCHED;
;             PG8_LDB(B0, 1, 0); PG8_LDB(B1, 1, 1); PG8_SCHED; PG8_LDA(At, 1, 0); if (!fin) PG8_STAGE(PG8_SA(0, 1), a2 + hstep, voffA);
;             if (!fin) PG8_WAIT_V(8); else PG8_WAIT_V(0); PG8_WAIT_L(0); PG8_BAR; PG8_MMA(0, 0, At, B0); PG8_MMA(0, 1, At, B1); PG8_BAR; PG8_SCHED;
.LBB0_754:
	s_waitcnt lgkmcnt(0)
	s_xor_b64 s[26:27], s[6:7], -1
	s_barrier
	v_mfma_f32_16x16x32_f16 v[62:65], v[146:149], v[186:189], v[62:65]
	s_setprio 1
	v_mfma_f32_16x16x32_f16 v[62:65], v[158:161], v[190:193], v[62:65]
	v_mfma_f32_16x16x32_f16 v[58:61], v[166:169], v[190:193], v[58:61]
	v_mfma_f32_16x16x32_f16 v[58:61], v[162:165], v[186:189], v[58:61]
	v_mfma_f32_16x16x32_f16 v[42:45], v[162:165], v[178:181], v[42:45]
	v_mfma_f32_16x16x32_f16 v[42:45], v[166:169], v[182:185], v[42:45]
	v_mfma_f32_16x16x32_f16 v[46:49], v[158:161], v[182:185], v[46:49]
	v_mfma_f32_16x16x32_f16 v[46:49], v[146:149], v[178:181], v[46:49]
	v_mfma_f32_16x16x32_f16 v[30:33], v[146:149], v[170:173], v[30:33]
	v_mfma_f32_16x16x32_f16 v[30:33], v[158:161], v[174:177], v[30:33]
	v_mfma_f32_16x16x32_f16 v[26:29], v[166:169], v[174:177], v[26:29]
	v_mfma_f32_16x16x32_f16 v[26:29], v[162:165], v[170:173], v[26:29]
	v_mfma_f32_16x16x32_f16 v[10:13], v[162:165], v[150:153], v[10:13]
	v_mfma_f32_16x16x32_f16 v[10:13], v[166:169], v[154:157], v[10:13]
	v_mfma_f32_16x16x32_f16 v[14:17], v[158:161], v[154:157], v[14:17]
	v_mfma_f32_16x16x32_f16 v[14:17], v[146:149], v[150:153], v[14:17]
	v_mfma_f32_16x16x32_f16 v[6:9], v[74:77], v[150:153], v[6:9]
	v_mfma_f32_16x16x32_f16 v[6:9], v[86:89], v[154:157], v[6:9]
	v_mfma_f32_16x16x32_f16 v[54:57], v[86:89], v[190:193], v[54:57]
	v_mfma_f32_16x16x32_f16 v[54:57], v[74:77], v[186:189], v[54:57]
	v_mfma_f32_16x16x32_f16 v[50:53], v[98:101], v[186:189], v[50:53]
	v_mfma_f32_16x16x32_f16 v[50:53], v[110:113], v[190:193], v[50:53]
	v_mfma_f32_16x16x32_f16 v[34:37], v[110:113], v[182:185], v[34:37]
	v_mfma_f32_16x16x32_f16 v[34:37], v[98:101], v[178:181], v[34:37]
	v_mfma_f32_16x16x32_f16 v[38:41], v[74:77], v[178:181], v[38:41]
	v_mfma_f32_16x16x32_f16 v[38:41], v[86:89], v[182:185], v[38:41]
	v_mfma_f32_16x16x32_f16 v[22:25], v[86:89], v[174:177], v[22:25]
	v_mfma_f32_16x16x32_f16 v[22:25], v[74:77], v[170:173], v[22:25]
	v_mfma_f32_16x16x32_f16 v[18:21], v[98:101], v[170:173], v[18:21]
	v_mfma_f32_16x16x32_f16 v[18:21], v[110:113], v[174:177], v[18:21]
	v_mfma_f32_16x16x32_f16 v[2:5], v[110:113], v[154:157], v[2:5]
	v_mfma_f32_16x16x32_f16 v[2:5], v[98:101], v[150:153], v[2:5]
	s_barrier
	s_setprio 0
	ds_read_b128 v[162:165], v225
	ds_read_b128 v[166:169], v225 offset:1024
	ds_read_b128 v[146:149], v225 offset:2048
	ds_read_b128 v[158:161], v225 offset:3072
	ds_read_b128 v[98:101], v226
	ds_read_b128 v[110:113], v226 offset:1024
	ds_read_b128 v[74:77], v226 offset:2048
	ds_read_b128 v[86:89], v226 offset:3072
	ds_read_b128 v[194:197], v224 offset:32768
	ds_read_b128 v[198:201], v224 offset:33792
	ds_read_b128 v[186:189], v224 offset:34816
	ds_read_b128 v[190:193], v224 offset:35840
	ds_read_b128 v[178:181], v224 offset:36864
	ds_read_b128 v[182:185], v224 offset:37888
	ds_read_b128 v[170:173], v224 offset:38912
	ds_read_b128 v[174:177], v224 offset:39936
	v_cndmask_b32_e64 v150, 0, 1, s[26:27]
	v_cmp_ne_u32_e64 s[6:7], 1, v150
	s_andn2_b64 vcc, exec, s[26:27]
	s_mov_b64 s[26:27], -1
	s_cbranch_vccnz .LBB0_756
	s_add_u32 s26, s24, 0x40000
	s_addc_u32 s27, s25, 0
	s_add_u32 m0, s14, 0x4000
	s_nop 0
	global_load_lds_dwordx4 v1, s[26:27]
	s_nop 0
	s_add_u32 m0, s14, 0x6000
	s_nop 0
	global_load_lds_dwordx4 v213, s[26:27]
	s_waitcnt vmcnt(8)
	s_mov_b64 s[26:27], 0

; #define PG8_STAGE(bufoff, gbase, voff) do { if constexpr (ABL & 1) break; glds16s<(bufoff)>((voff)[0], (const void*)(gbase), ldsbw); glds16s<(bufoff) + 8192>((voff)[1], (const void*)(gbase), ldsbw); } while (0)
; #define PG8_LDA(dst, b, h) do { if constexpr (ABL & 4) break; _Pragma("unroll") for (int m = 0; m < 4; ++m) _Pragma("unroll") for (int k = 0; k < 2; ++k) dst[m][k] = *(const LAS f16x8*)(lds + PG8_SA(b, h) + aoff + m * 2048 + k * 1024); } while (0)
; #define PG8_MMA(ai, bj, At, Bt) do { if constexpr (ABL & 2) break; __builtin_amdgcn_s_setprio(1); _Pragma("unroll") for (int m = 0; m < 4; ++m) _Pragma("unroll") for (int n = 0; n < 2; ++n) _Pragma("unroll") for (int k = 0; k < 2; ++k) \
;         acc[ai][bj][m][n] = __builtin_amdgcn_mfma_f32_16x16x32_f16(Bt[n][k], At[m][k], acc[ai][bj][m][n], 0, 0, 0); __builtin_amdgcn_s_setprio(0); } while (0)
; #define PG8_WAIT_V(n) asm volatile("s_waitcnt vmcnt(" #n ")" ::: "memory")
; #define PG8_WAIT_L(n) asm volatile("s_waitcnt lgkmcnt(" #n ")" ::: "memory")
; #define PG8_BAR __builtin_amdgcn_s_barrier()
; #define PG8_SCHED __builtin_amdgcn_sched_barrier(0)
;     ...
;             if (!fin) PG8_WAIT_V(8); else PG8_WAIT_V(0); PG8_WAIT_L(0); PG8_BAR; PG8_MMA(0, 0, At, B0); PG8_MMA(0, 1, At, B1); PG8_BAR; PG8_SCHED;
;             PG8_LDA(At, 1, 1); if (!fin) { PG8_STAGE(PG8_SB(1, 0), b3, voffB); PG8_STAGE(PG8_SB(1, 1), b3 + hstep, voffB); PG8_STAGE(PG8_SA(1, 0), a3, voffA); }
;             if (!fin) PG8_WAIT_V(8); PG8_WAIT_L(0); PG8_BAR; PG8_MMA(1, 0, At, B0); PG8_MMA(1, 1, At, B1); PG8_BAR; PG8_SCHED;
.LBB0_758:
	s_waitcnt lgkmcnt(0)
	s_barrier
	v_mfma_f32_16x16x32_f16 v[122:125], v[162:165], v[194:197], v[122:125]
	s_setprio 1
	v_mfma_f32_16x16x32_f16 v[154:157], v[166:169], v[198:201], v[122:125]
	v_mfma_f32_16x16x32_f16 v[122:125], v[158:161], v[198:201], v[134:137]
	v_mfma_f32_16x16x32_f16 v[150:153], v[146:149], v[194:197], v[122:125]
	v_mfma_f32_16x16x32_f16 v[102:105], v[146:149], v[178:181], v[102:105]
	v_mfma_f32_16x16x32_f16 v[102:105], v[158:161], v[182:185], v[102:105]
	v_mfma_f32_16x16x32_f16 v[106:109], v[166:169], v[182:185], v[106:109]
	v_mfma_f32_16x16x32_f16 v[106:109], v[162:165], v[178:181], v[106:109]
	v_mfma_f32_16x16x32_f16 v[122:125], v[162:165], v[186:189], v[130:133]
	v_mfma_f32_16x16x32_f16 v[130:133], v[166:169], v[190:193], v[122:125]
	v_mfma_f32_16x16x32_f16 v[122:125], v[158:161], v[190:193], v[126:129]
	v_mfma_f32_16x16x32_f16 v[126:129], v[146:149], v[186:189], v[122:125]
	v_mfma_f32_16x16x32_f16 v[78:81], v[146:149], v[170:173], v[78:81]
	v_mfma_f32_16x16x32_f16 v[78:81], v[158:161], v[174:177], v[78:81]
	v_mfma_f32_16x16x32_f16 v[82:85], v[166:169], v[174:177], v[82:85]
	v_mfma_f32_16x16x32_f16 v[82:85], v[162:165], v[170:173], v[82:85]
	v_mfma_f32_16x16x32_f16 v[70:73], v[98:101], v[170:173], v[70:73]
	v_mfma_f32_16x16x32_f16 v[70:73], v[110:113], v[174:177], v[70:73]
	v_mfma_f32_16x16x32_f16 v[122:125], v[110:113], v[198:201], v[142:145]
	v_mfma_f32_16x16x32_f16 v[142:145], v[98:101], v[194:197], v[122:125]
	v_mfma_f32_16x16x32_f16 v[122:125], v[74:77], v[194:197], v[138:141]
	v_mfma_f32_16x16x32_f16 v[138:141], v[86:89], v[198:201], v[122:125]
	v_mfma_f32_16x16x32_f16 v[114:117], v[86:89], v[190:193], v[114:117]
	v_mfma_f32_16x16x32_f16 v[114:117], v[74:77], v[186:189], v[114:117]
	v_mfma_f32_16x16x32_f16 v[118:121], v[98:101], v[186:189], v[118:121]
	v_mfma_f32_16x16x32_f16 v[118:121], v[110:113], v[190:193], v[118:121]
	v_mfma_f32_16x16x32_f16 v[94:97], v[110:113], v[182:185], v[94:97]
	v_mfma_f32_16x16x32_f16 v[94:97], v[98:101], v[178:181], v[94:97]
	v_mfma_f32_16x16x32_f16 v[90:93], v[74:77], v[178:181], v[90:93]
	v_mfma_f32_16x16x32_f16 v[90:93], v[86:89], v[182:185], v[90:93]
	v_mfma_f32_16x16x32_f16 v[66:69], v[86:89], v[174:177], v[66:69]
	v_mfma_f32_16x16x32_f16 v[66:69], v[74:77], v[170:173], v[66:69]
	s_barrier
	s_setprio 0
	ds_read_b128 v[186:189], v224 offset:49152
	ds_read_b128 v[190:193], v224 offset:50176
	ds_read_b128 v[178:181], v224 offset:51200
	ds_read_b128 v[182:185], v224 offset:52224
	ds_read_b128 v[170:173], v224 offset:53248
	ds_read_b128 v[174:177], v224 offset:54272
	ds_read_b128 v[122:125], v224 offset:55296
	ds_read_b128 v[134:137], v224 offset:56320
	s_and_b64 vcc, exec, s[6:7]
	s_cbranch_vccnz .LBB0_749
	s_add_u32 s6, s24, 0x80
	s_addc_u32 s7, s25, 0
	s_add_u32 s24, s8, 0x80
	s_addc_u32 s25, s9, 0
	s_add_u32 m0, s14, 0x18000
	s_nop 0
	global_load_lds_dwordx4 v209, s[24:25]
	s_nop 0
	s_add_u32 m0, s14, 0x1a000
	s_nop 0
	global_load_lds_dwordx4 v219, s[24:25]
	s_add_u32 s8, s8, 0x40080
	s_addc_u32 s9, s9, 0
	s_add_u32 m0, s14, 0x1c000
	s_nop 0
	global_load_lds_dwordx4 v209, s[8:9]
	s_nop 0
	s_add_u32 m0, s14, 0x1e000
	s_nop 0
	global_load_lds_dwordx4 v219, s[8:9]
	s_nop 0
	s_add_u32 m0, s14, 0x8000
	s_nop 0
	global_load_lds_dwordx4 v1, s[6:7]
	s_nop 0
	s_add_u32 m0, s14, 0xa000
	s_nop 0
	global_load_lds_dwordx4 v213, s[6:7]
	s_waitcnt vmcnt(8)
	s_branch .LBB0_749

;     __device__ __forceinline__ bool next(int i, Unit& u) const { if (i >= count) return false; const int L = first + i; u.pm = L / nN; u.pn = L % nN; return true; }
; #define PG8_STAGE(bufoff, gbase, voff) do { if constexpr (ABL & 1) break; glds16s<(bufoff)>((voff)[0], (const void*)(gbase), ldsbw); glds16s<(bufoff) + 8192>((voff)[1], (const void*)(gbase), ldsbw); } while (0)
; #define PG8_LDA(dst, b, h) do { if constexpr (ABL & 4) break; _Pragma("unroll") for (int m = 0; m < 4; ++m) _Pragma("unroll") for (int k = 0; k < 2; ++k) dst[m][k] = *(const LAS f16x8*)(lds + PG8_SA(b, h) + aoff + m * 2048 + k * 1024); } while (0)
; #define PG8_LDB(dst, b, h) do { if constexpr (ABL & 4) break; _Pragma("unroll") for (int n = 0; n < 2; ++n) _Pragma("unroll") for (int k = 0; k < 2; ++k) dst[n][k] = *(const LAS f16x8*)(lds + PG8_SB(b, h) + boff + n * 2048 + k * 1024); } while (0)
; #define PG8_MMAF(ai, bj, At, Bt) do { if (t == 0) PG8_MMA0(ai, bj, At, Bt); else PG8_MMA(ai, bj, At, Bt); } while (0)
; #define PG8_WAIT_V(n) asm volatile("s_waitcnt vmcnt(" #n ")" ::: "memory")
; #define PG8_BAR __builtin_amdgcn_s_barrier()
;     ...
;         const bool has_next = S.next(ui + 1, nxt);
;         const char* nA = has_next ? (const char*)g.A + (size_t)nxt.pm * tstep : cA; const char* nB = has_next ? (const char*)g.Bt + (size_t)nxt.pn * tstep : cB;
;         for (int t = 0; t < nt; t += 2) {
;             const bool last = (t == nt - 2);
;             const char* a1 = cA + (size_t)(t + 1) * kstep;
;             const char* a2 = last ? nA : cA + (size_t)(t + 2) * kstep; const char* b2 = last ? nB : cB + (size_t)(t + 2) * kstep;
;             const char* a3 = a2 + kstep; const char* b3 = b2 + kstep;
;             if (last && has_next) S.a_ready(nxt);
;             if constexpr (SP2) {
;             PG8_LDB(B0, 0, 0); PG8_LDB(B1, 0, 1); PG8_SCHED; PG8_LDA(At, 0, 0); PG8_STAGE(PG8_SA(1, 1), a1 + hstep, voffA);
;             PG8_WAIT_V(8); PG8_WAIT_L(0); PG8_BAR; PG8_MMAF(0, 0, At, B0); PG8_MMAF(0, 1, At, B1); PG8_BAR; PG8_SCHED;
;             const bool fin = last && !has_next;
;             PG8_LDA(At, 0, 1); if (!fin) { PG8_STAGE(PG8_SB(0, 0), b2, voffB); PG8_STAGE(PG8_SB(0, 1), b2 + hstep, voffB); PG8_STAGE(PG8_SA(0, 0), a2, voffA); }
;             if (!fin) PG8_WAIT_V(8); else PG8_WAIT_V(2); PG8_WAIT_L(0); PG8_BAR; PG8_MMAF(1, 0, At, B0); PG8_MMAF(1, 1, At, B1); PG8_BAR; PG8_SCHED;
.LBB0_841:
	s_ashr_i32 s41, s40, 31
	s_lshl_b64 s[24:25], s[40:41], 19
	s_add_u32 s42, s74, s24
	s_addc_u32 s43, s75, s25
	s_and_b64 s[24:25], exec, s[4:5]
	ds_read_b128 v[2:5], v210
	ds_read_b128 v[6:9], v210 offset:1024
	ds_read_b128 v[10:13], v210 offset:2048
	ds_read_b128 v[14:17], v210 offset:3072
	ds_read_b128 v[18:21], v211
	ds_read_b128 v[22:25], v211 offset:1024
	ds_read_b128 v[26:29], v211 offset:2048
	ds_read_b128 v[30:33], v211 offset:3072
	s_cselect_b32 s41, s9, s43
	s_cselect_b32 s51, s8, s42
	s_ashr_i32 s39, s38, 31
	s_lshl_b64 s[24:25], s[38:39], 19
	s_add_u32 s44, s58, s24
	s_addc_u32 s45, s59, s25
	s_and_b64 s[24:25], exec, s[4:5]
	s_cselect_b32 s39, s7, s45
	s_cselect_b32 s52, s6, s44
	s_add_u32 s48, s8, 0x100
	s_addc_u32 s49, s9, 0
	s_add_u32 s54, s6, 0x100
	s_addc_u32 s55, s7, 0
	s_add_u32 s24, s8, 0x180
	s_addc_u32 s25, s9, 0
	ds_read_b128 v[34:37], v212
	ds_read_b128 v[38:41], v212 offset:1024
	ds_read_b128 v[42:45], v212 offset:2048
	ds_read_b128 v[46:49], v212 offset:3072
	ds_read_b128 v[50:53], v212 offset:4096
	ds_read_b128 v[54:57], v212 offset:5120
	ds_read_b128 v[58:61], v212 offset:6144
	ds_read_b128 v[62:65], v212 offset:7168
	s_add_u32 s26, s6, 0x180
	s_addc_u32 s27, s7, 0
	s_add_u32 s56, s8, 0x40080
	s_addc_u32 s57, s9, 0
	s_add_u32 m0, s14, 0xc000
	s_nop 0
	global_load_lds_dwordx4 v206, s[56:57]
	s_nop 0
	s_add_u32 m0, s14, 0xe000
	s_nop 0
	global_load_lds_dwordx4 v208, s[56:57]
	s_waitcnt vmcnt(8)
	s_waitcnt lgkmcnt(0)
	s_barrier
	v_mfma_f32_16x16x32_f16 v[90:93], v[2:5], v[58:61], 0
	s_setprio 1
	v_mfma_f32_16x16x32_f16 v[94:97], v[6:9], v[62:65], v[90:93]
	v_mfma_f32_16x16x32_f16 v[66:69], v[2:5], v[34:37], 0
	v_mfma_f32_16x16x32_f16 v[66:69], v[6:9], v[38:41], v[66:69]
	v_mfma_f32_16x16x32_f16 v[70:73], v[10:13], v[34:37], 0
	v_mfma_f32_16x16x32_f16 v[70:73], v[14:17], v[38:41], v[70:73]
	v_mfma_f32_16x16x32_f16 v[74:77], v[2:5], v[42:45], 0
	v_mfma_f32_16x16x32_f16 v[74:77], v[6:9], v[46:49], v[74:77]
	v_mfma_f32_16x16x32_f16 v[78:81], v[10:13], v[42:45], 0
	v_mfma_f32_16x16x32_f16 v[78:81], v[14:17], v[46:49], v[78:81]
	v_mfma_f32_16x16x32_f16 v[82:85], v[2:5], v[50:53], 0
	v_mfma_f32_16x16x32_f16 v[82:85], v[6:9], v[54:57], v[82:85]
	v_mfma_f32_16x16x32_f16 v[86:89], v[10:13], v[50:53], 0
	v_mfma_f32_16x16x32_f16 v[86:89], v[14:17], v[54:57], v[86:89]
	v_mfma_f32_16x16x32_f16 v[90:93], v[10:13], v[58:61], 0
	v_mfma_f32_16x16x32_f16 v[102:105], v[14:17], v[62:65], v[90:93]
	v_mfma_f32_16x16x32_f16 v[90:93], v[18:21], v[34:37], 0
	v_mfma_f32_16x16x32_f16 v[118:121], v[22:25], v[38:41], v[90:93]
	v_mfma_f32_16x16x32_f16 v[34:37], v[26:29], v[34:37], 0
	v_mfma_f32_16x16x32_f16 v[34:37], v[30:33], v[38:41], v[34:37]
	v_mfma_f32_16x16x32_f16 v[38:41], v[18:21], v[42:45], 0
	v_mfma_f32_16x16x32_f16 v[38:41], v[22:25], v[46:49], v[38:41]
	v_mfma_f32_16x16x32_f16 v[42:45], v[26:29], v[42:45], 0
	v_mfma_f32_16x16x32_f16 v[42:45], v[30:33], v[46:49], v[42:45]
	v_mfma_f32_16x16x32_f16 v[46:49], v[18:21], v[50:53], 0
	v_mfma_f32_16x16x32_f16 v[46:49], v[22:25], v[54:57], v[46:49]
	v_mfma_f32_16x16x32_f16 v[50:53], v[26:29], v[50:53], 0
	v_mfma_f32_16x16x32_f16 v[50:53], v[30:33], v[54:57], v[50:53]
	v_mfma_f32_16x16x32_f16 v[54:57], v[18:21], v[58:61], 0
	v_mfma_f32_16x16x32_f16 v[54:57], v[22:25], v[62:65], v[54:57]
	v_mfma_f32_16x16x32_f16 v[58:61], v[26:29], v[58:61], 0
	v_mfma_f32_16x16x32_f16 v[58:61], v[30:33], v[62:65], v[58:61]
	s_barrier
	s_setprio 0
	ds_read_b128 v[62:65], v212 offset:16384
	ds_read_b128 v[90:93], v212 offset:17408
	ds_read_b128 v[98:101], v212 offset:18432
	ds_read_b128 v[106:109], v212 offset:19456
	ds_read_b128 v[110:113], v212 offset:20480
	ds_read_b128 v[114:117], v212 offset:21504
	ds_read_b128 v[122:125], v212 offset:22528
	ds_read_b128 v[126:129], v212 offset:23552
	s_add_u32 m0, s14, 0x10000
	s_nop 0
	global_load_lds_dwordx4 v207, s[54:55]
	s_nop 0
	s_add_u32 m0, s14, 0x12000
	s_nop 0
	global_load_lds_dwordx4 v209, s[54:55]
	s_add_u32 s54, s6, 0x40100
	s_addc_u32 s55, s7, 0
	s_add_u32 m0, s14, 0x14000
	s_nop 0
	global_load_lds_dwordx4 v207, s[54:55]
	s_nop 0
	s_add_u32 m0, s14, 0x16000
	s_nop 0
	global_load_lds_dwordx4 v209, s[54:55]
	s_nop 0
	s_add_u32 m0, s14, 0
	s_nop 0
	global_load_lds_dwordx4 v206, s[48:49]
	s_nop 0
	s_add_u32 m0, s14, 0x2000
	s_nop 0
	global_load_lds_dwordx4 v208, s[48:49]
	s_waitcnt vmcnt(8)
	s_waitcnt lgkmcnt(0)
	s_barrier
	v_mfma_f32_16x16x32_f16 v[130:133], v[2:5], v[62:65], 0
	s_setprio 1
	v_mfma_f32_16x16x32_f16 v[130:133], v[6:9], v[90:93], v[130:133]
	v_mfma_f32_16x16x32_f16 v[138:141], v[2:5], v[98:101], 0
	v_mfma_f32_16x16x32_f16 v[138:141], v[6:9], v[106:109], v[138:141]
	v_mfma_f32_16x16x32_f16 v[146:149], v[2:5], v[110:113], 0
	v_mfma_f32_16x16x32_f16 v[146:149], v[6:9], v[114:117], v[146:149]
	v_mfma_f32_16x16x32_f16 v[2:5], v[2:5], v[122:125], 0
	v_mfma_f32_16x16x32_f16 v[2:5], v[6:9], v[126:129], v[2:5]
	v_mfma_f32_16x16x32_f16 v[6:9], v[10:13], v[122:125], 0
	v_mfma_f32_16x16x32_f16 v[6:9], v[14:17], v[126:129], v[6:9]
	v_mfma_f32_16x16x32_f16 v[134:137], v[10:13], v[62:65], 0
	v_mfma_f32_16x16x32_f16 v[134:137], v[14:17], v[90:93], v[134:137]
	v_mfma_f32_16x16x32_f16 v[142:145], v[10:13], v[98:101], 0
	v_mfma_f32_16x16x32_f16 v[142:145], v[14:17], v[106:109], v[142:145]
	v_mfma_f32_16x16x32_f16 v[150:153], v[10:13], v[110:113], 0
	v_mfma_f32_16x16x32_f16 v[150:153], v[14:17], v[114:117], v[150:153]
	v_mfma_f32_16x16x32_f16 v[10:13], v[18:21], v[62:65], 0
	v_mfma_f32_16x16x32_f16 v[14:17], v[22:25], v[90:93], v[10:13]
	v_mfma_f32_16x16x32_f16 v[10:13], v[26:29], v[62:65], 0
	v_mfma_f32_16x16x32_f16 v[154:157], v[30:33], v[90:93], v[10:13]
	v_mfma_f32_16x16x32_f16 v[10:13], v[18:21], v[98:101], 0
	v_mfma_f32_16x16x32_f16 v[158:161], v[22:25], v[106:109], v[10:13]
	v_mfma_f32_16x16x32_f16 v[10:13], v[26:29], v[98:101], 0
	v_mfma_f32_16x16x32_f16 v[162:165], v[30:33], v[106:109], v[10:13]
	v_mfma_f32_16x16x32_f16 v[10:13], v[18:21], v[110:113], 0
	v_mfma_f32_16x16x32_f16 v[166:169], v[22:25], v[114:117], v[10:13]
	v_mfma_f32_16x16x32_f16 v[10:13], v[26:29], v[110:113], 0
	v_mfma_f32_16x16x32_f16 v[170:173], v[30:33], v[114:117], v[10:13]
	v_mfma_f32_16x16x32_f16 v[10:13], v[18:21], v[122:125], 0
	v_mfma_f32_16x16x32_f16 v[174:177], v[22:25], v[126:129], v[10:13]
	v_mfma_f32_16x16x32_f16 v[10:13], v[26:29], v[122:125], 0
	v_mfma_f32_16x16x32_f16 v[178:181], v[30:33], v[126:129], v[10:13]
	s_barrier
; #define PG8_STAGE(bufoff, gbase, voff) do { if constexpr (ABL & 1) break; glds16s<(bufoff)>((voff)[0], (const void*)(gbase), ldsbw); glds16s<(bufoff) + 8192>((voff)[1], (const void*)(gbase), ldsbw); } while (0)
; #define PG8_LDA(dst, b, h) do { if constexpr (ABL & 4) break; _Pragma("unroll") for (int m = 0; m < 4; ++m) _Pragma("unroll") for (int k = 0; k < 2; ++k) dst[m][k] = *(const LAS f16x8*)(lds + PG8_SA(b, h) + aoff + m * 2048 + k * 1024); } while (0)
; #define PG8_LDB(dst, b, h) do { if constexpr (ABL & 4) break; _Pragma("unroll") for (int n = 0; n < 2; ++n) _Pragma("unroll") for (int k = 0; k < 2; ++k) dst[n][k] = *(const LAS f16x8*)(lds + PG8_SB(b, h) + boff + n * 2048 + k * 1024); } while (0)
; #define PG8_MMA(ai, bj, At, Bt) do { if constexpr (ABL & 2) break; __builtin_amdgcn_s_setprio(1); _Pragma("unroll") for (int m = 0; m < 4; ++m) _Pragma("unroll") for (int n = 0; n < 2; ++n) _Pragma("unroll") for (int k = 0; k < 2; ++k) \
;         acc[ai][bj][m][n] = __builtin_amdgcn_mfma_f32_16x16x32_f16(Bt[n][k], At[m][k], acc[ai][bj][m][n], 0, 0, 0); __builtin_amdgcn_s_setprio(0); } while (0)
; #define PG8_WAIT_V(n) asm volatile("s_waitcnt vmcnt(" #n ")" ::: "memory")
; #define PG8_WAIT_L(n) asm volatile("s_waitcnt lgkmcnt(" #n ")" ::: "memory")
; #define PG8_BAR __builtin_amdgcn_s_barrier()
; #define PG8_SCHED __builtin_amdgcn_sched_barrier(0)
;     ...
;             PG8_LDB(B0, 1, 0); PG8_LDB(B1, 1, 1); PG8_SCHED; PG8_LDA(At, 1, 0); if (!fin) PG8_STAGE(PG8_SA(0, 1), a2 + hstep, voffA);
;             if (!fin) PG8_WAIT_V(8); else PG8_WAIT_V(0); PG8_WAIT_L(0); PG8_BAR; PG8_MMA(0, 0, At, B0); PG8_MMA(0, 1, At, B1); PG8_BAR; PG8_SCHED;
;             PG8_LDA(At, 1, 1); if (!fin) { PG8_STAGE(PG8_SB(1, 0), b3, voffB); PG8_STAGE(PG8_SB(1, 1), b3 + hstep, voffB); PG8_STAGE(PG8_SA(1, 0), a3, voffA); }
;             if (!fin) PG8_WAIT_V(8); PG8_WAIT_L(0); PG8_BAR; PG8_MMA(1, 0, At, B0); PG8_MMA(1, 1, At, B1); PG8_BAR; PG8_SCHED;
	s_setprio 0
	s_nop 4
	ds_read_b128 v[10:13], v213
	ds_read_b128 v[22:25], v213 offset:1024
	ds_read_b128 v[30:33], v213 offset:2048
	ds_read_b128 v[182:185], v213 offset:3072
	ds_read_b128 v[186:189], v214
	ds_read_b128 v[190:193], v214 offset:1024
	ds_read_b128 v[216:219], v214 offset:2048
	ds_read_b128 v[220:223], v214 offset:3072
	ds_read_b128 v[18:21], v212 offset:32768
	ds_read_b128 v[26:29], v212 offset:33792
	ds_read_b128 v[224:227], v212 offset:34816
	ds_read_b128 v[228:231], v212 offset:35840
	ds_read_b128 v[232:235], v212 offset:36864
	ds_read_b128 v[236:239], v212 offset:37888
	ds_read_b128 v[240:243], v212 offset:38912
	ds_read_b128 v[244:247], v212 offset:39936
	s_add_u32 s8, s8, 0x40100
	s_addc_u32 s9, s9, 0
	s_add_u32 m0, s14, 0x4000
	s_nop 0
	global_load_lds_dwordx4 v206, s[8:9]
	s_nop 0
	s_add_u32 m0, s14, 0x6000
	s_nop 0
	global_load_lds_dwordx4 v208, s[8:9]
	s_waitcnt vmcnt(8)
	s_waitcnt lgkmcnt(0)
	s_barrier
	v_mfma_f32_16x16x32_f16 v[62:65], v[10:13], v[18:21], v[66:69]
	s_setprio 1
	v_mfma_f32_16x16x32_f16 v[114:117], v[22:25], v[26:29], v[62:65]
	v_mfma_f32_16x16x32_f16 v[62:65], v[30:33], v[18:21], v[70:73]
	v_mfma_f32_16x16x32_f16 v[110:113], v[182:185], v[26:29], v[62:65]
	v_mfma_f32_16x16x32_f16 v[62:65], v[10:13], v[224:227], v[74:77]
	v_mfma_f32_16x16x32_f16 v[106:109], v[22:25], v[228:231], v[62:65]
	v_mfma_f32_16x16x32_f16 v[62:65], v[30:33], v[224:227], v[78:81]
	v_mfma_f32_16x16x32_f16 v[98:101], v[182:185], v[228:231], v[62:65]
	v_mfma_f32_16x16x32_f16 v[62:65], v[10:13], v[232:235], v[82:85]
	v_mfma_f32_16x16x32_f16 v[90:93], v[22:25], v[236:239], v[62:65]
	v_mfma_f32_16x16x32_f16 v[62:65], v[30:33], v[232:235], v[86:89]
	v_mfma_f32_16x16x32_f16 v[82:85], v[182:185], v[236:239], v[62:65]
	v_mfma_f32_16x16x32_f16 v[62:65], v[10:13], v[240:243], v[94:97]
	v_mfma_f32_16x16x32_f16 v[74:77], v[22:25], v[244:247], v[62:65]
	v_mfma_f32_16x16x32_f16 v[62:65], v[30:33], v[240:243], v[102:105]
	v_mfma_f32_16x16x32_f16 v[62:65], v[182:185], v[244:247], v[62:65]
	v_mfma_f32_16x16x32_f16 v[66:69], v[186:189], v[18:21], v[118:121]
	v_mfma_f32_16x16x32_f16 v[126:129], v[190:193], v[26:29], v[66:69]
	v_mfma_f32_16x16x32_f16 v[18:21], v[216:219], v[18:21], v[34:37]
	v_mfma_f32_16x16x32_f16 v[122:125], v[220:223], v[26:29], v[18:21]
	v_mfma_f32_16x16x32_f16 v[18:21], v[186:189], v[224:227], v[38:41]
	v_mfma_f32_16x16x32_f16 v[118:121], v[190:193], v[228:231], v[18:21]
	v_mfma_f32_16x16x32_f16 v[18:21], v[216:219], v[224:227], v[42:45]
	v_mfma_f32_16x16x32_f16 v[102:105], v[220:223], v[228:231], v[18:21]
	v_mfma_f32_16x16x32_f16 v[18:21], v[186:189], v[232:235], v[46:49]
	v_mfma_f32_16x16x32_f16 v[94:97], v[190:193], v[236:239], v[18:21]
	v_mfma_f32_16x16x32_f16 v[18:21], v[216:219], v[232:235], v[50:53]
	v_mfma_f32_16x16x32_f16 v[86:89], v[220:223], v[236:239], v[18:21]
	v_mfma_f32_16x16x32_f16 v[18:21], v[186:189], v[240:243], v[54:57]
	v_mfma_f32_16x16x32_f16 v[78:81], v[190:193], v[244:247], v[18:21]
	v_mfma_f32_16x16x32_f16 v[18:21], v[216:219], v[240:243], v[58:61]
	v_mfma_f32_16x16x32_f16 v[70:73], v[220:223], v[244:247], v[18:21]
	s_barrier
	s_setprio 0
	ds_read_b128 v[38:41], v212 offset:49152
	ds_read_b128 v[46:49], v212 offset:50176
	ds_read_b128 v[224:227], v212 offset:51200
	ds_read_b128 v[228:231], v212 offset:52224
	ds_read_b128 v[232:235], v212 offset:53248
	ds_read_b128 v[236:239], v212 offset:54272
	ds_read_b128 v[240:243], v212 offset:55296
	ds_read_b128 v[244:247], v212 offset:56320
	s_add_u32 m0, s14, 0x18000
	s_nop 0
	global_load_lds_dwordx4 v207, s[26:27]
	s_nop 0
	s_add_u32 m0, s14, 0x1a000
	s_nop 0
	global_load_lds_dwordx4 v209, s[26:27]
	s_add_u32 s8, s6, 0x40180
	s_addc_u32 s9, s7, 0
	s_add_u32 m0, s14, 0x1c000
	s_nop 0
	global_load_lds_dwordx4 v207, s[8:9]
	s_nop 0
	s_add_u32 m0, s14, 0x1e000
	s_nop 0
	global_load_lds_dwordx4 v209, s[8:9]
	s_nop 0
	s_add_u32 m0, s14, 0x8000
	s_nop 0
	global_load_lds_dwordx4 v206, s[24:25]
	s_nop 0
	s_add_u32 m0, s14, 0xa000
	s_nop 0
	global_load_lds_dwordx4 v208, s[24:25]
	s_waitcnt vmcnt(8)
	s_waitcnt lgkmcnt(0)
	s_barrier
	v_mfma_f32_16x16x32_f16 v[18:21], v[10:13], v[38:41], v[130:133]
	s_setprio 1
	v_mfma_f32_16x16x32_f16 v[58:61], v[22:25], v[46:49], v[18:21]
	v_mfma_f32_16x16x32_f16 v[18:21], v[182:185], v[46:49], v[134:137]
	v_mfma_f32_16x16x32_f16 v[50:53], v[30:33], v[38:41], v[18:21]
	v_mfma_f32_16x16x32_f16 v[18:21], v[10:13], v[224:227], v[138:141]
	v_mfma_f32_16x16x32_f16 v[42:45], v[22:25], v[228:231], v[18:21]
	v_mfma_f32_16x16x32_f16 v[18:21], v[182:185], v[228:231], v[142:145]
	v_mfma_f32_16x16x32_f16 v[34:37], v[30:33], v[224:227], v[18:21]
	v_mfma_f32_16x16x32_f16 v[18:21], v[10:13], v[232:235], v[146:149]
	v_mfma_f32_16x16x32_f16 v[26:29], v[22:25], v[236:239], v[18:21]
	v_mfma_f32_16x16x32_f16 v[2:5], v[22:25], v[244:247], v[2:5]
	v_mfma_f32_16x16x32_f16 v[10:13], v[10:13], v[240:243], v[2:5]
	v_mfma_f32_16x16x32_f16 v[2:5], v[30:33], v[240:243], v[6:9]
	v_mfma_f32_16x16x32_f16 v[2:5], v[182:185], v[244:247], v[2:5]
	v_mfma_f32_16x16x32_f16 v[18:21], v[182:185], v[236:239], v[150:153]
	v_mfma_f32_16x16x32_f16 v[18:21], v[30:33], v[232:235], v[18:21]
	v_mfma_f32_16x16x32_f16 v[6:9], v[186:189], v[38:41], v[14:17]
	v_mfma_f32_16x16x32_f16 v[66:69], v[190:193], v[46:49], v[6:9]
	v_mfma_f32_16x16x32_f16 v[6:9], v[220:223], v[46:49], v[154:157]
	v_mfma_f32_16x16x32_f16 v[54:57], v[216:219], v[38:41], v[6:9]
	v_mfma_f32_16x16x32_f16 v[6:9], v[186:189], v[224:227], v[158:161]
	v_mfma_f32_16x16x32_f16 v[46:49], v[190:193], v[228:231], v[6:9]
	v_mfma_f32_16x16x32_f16 v[6:9], v[220:223], v[228:231], v[162:165]
	v_mfma_f32_16x16x32_f16 v[38:41], v[216:219], v[224:227], v[6:9]
	v_mfma_f32_16x16x32_f16 v[6:9], v[186:189], v[232:235], v[166:169]
	v_mfma_f32_16x16x32_f16 v[30:33], v[190:193], v[236:239], v[6:9]
	v_mfma_f32_16x16x32_f16 v[6:9], v[220:223], v[236:239], v[170:173]
	v_mfma_f32_16x16x32_f16 v[22:25], v[216:219], v[232:235], v[6:9]
	v_mfma_f32_16x16x32_f16 v[6:9], v[186:189], v[240:243], v[174:177]
	v_mfma_f32_16x16x32_f16 v[14:17], v[190:193], v[244:247], v[6:9]
	v_mfma_f32_16x16x32_f16 v[6:9], v[220:223], v[244:247], v[178:181]
	v_mfma_f32_16x16x32_f16 v[6:9], v[216:219], v[240:243], v[6:9]
	s_barrier
	s_setprio 0
	s_add_u32 s53, s6, 0x200
	s_addc_u32 s54, s7, 0
	s_mov_b32 s55, 0
	s_branch .LBB0_843
; #define PG8_STAGE(bufoff, gbase, voff) do { if constexpr (ABL & 1) break; glds16s<(bufoff)>((voff)[0], (const void*)(gbase), ldsbw); glds16s<(bufoff) + 8192>((voff)[1], (const void*)(gbase), ldsbw); } while (0)
; #define PG8_LDA(dst, b, h) do { if constexpr (ABL & 4) break; _Pragma("unroll") for (int m = 0; m < 4; ++m) _Pragma("unroll") for (int k = 0; k < 2; ++k) dst[m][k] = *(const LAS f16x8*)(lds + PG8_SA(b, h) + aoff + m * 2048 + k * 1024); } while (0)
; #define PG8_LDB(dst, b, h) do { if constexpr (ABL & 4) break; _Pragma("unroll") for (int n = 0; n < 2; ++n) _Pragma("unroll") for (int k = 0; k < 2; ++k) dst[n][k] = *(const LAS f16x8*)(lds + PG8_SB(b, h) + boff + n * 2048 + k * 1024); } while (0)
; #define PG8_MMA(ai, bj, At, Bt) do { if constexpr (ABL & 2) break; __builtin_amdgcn_s_setprio(1); _Pragma("unroll") for (int m = 0; m < 4; ++m) _Pragma("unroll") for (int n = 0; n < 2; ++n) _Pragma("unroll") for (int k = 0; k < 2; ++k) \
;         acc[ai][bj][m][n] = __builtin_amdgcn_mfma_f32_16x16x32_f16(Bt[n][k], At[m][k], acc[ai][bj][m][n], 0, 0, 0); __builtin_amdgcn_s_setprio(0); } while (0)
; #define PG8_WAIT_V(n) asm volatile("s_waitcnt vmcnt(" #n ")" ::: "memory")
;     ...
;             PG8_LDB(B0, 0, 0); PG8_LDB(B1, 0, 1); PG8_SCHED; PG8_LDA(At, 0, 0); PG8_STAGE(PG8_SA(1, 1), a1 + hstep, voffA);
;             PG8_WAIT_V(8); PG8_WAIT_L(0); PG8_BAR; PG8_MMAF(0, 0, At, B0); PG8_MMAF(0, 1, At, B1); PG8_BAR; PG8_SCHED;
;             const bool fin = last && !has_next;
;             PG8_LDA(At, 0, 1); if (!fin) { PG8_STAGE(PG8_SB(0, 0), b2, voffB); PG8_STAGE(PG8_SB(0, 1), b2 + hstep, voffB); PG8_STAGE(PG8_SA(0, 0), a2, voffA); }
;             if (!fin) PG8_WAIT_V(8); else PG8_WAIT_V(2); PG8_WAIT_L(0); PG8_BAR; PG8_MMAF(1, 0, At, B0); PG8_MMAF(1, 1, At, B1); PG8_BAR; PG8_SCHED;
;             PG8_LDB(B0, 1, 0); PG8_LDB(B1, 1, 1); PG8_SCHED; PG8_LDA(At, 1, 0); if (!fin) PG8_STAGE(PG8_SA(0, 1), a2 + hstep, voffA);
;             if (!fin) PG8_WAIT_V(8); else PG8_WAIT_V(0); PG8_WAIT_L(0); PG8_BAR; PG8_MMA(0, 0, At, B0); PG8_MMA(0, 1, At, B1); PG8_BAR; PG8_SCHED;
;             PG8_LDA(At, 1, 1); if (!fin) { PG8_STAGE(PG8_SB(1, 0), b3, voffB); PG8_STAGE(PG8_SB(1, 1), b3 + hstep, voffB); PG8_STAGE(PG8_SA(1, 0), a3, voffA); }
;             if (!fin) PG8_WAIT_V(8); PG8_WAIT_L(0); PG8_BAR; PG8_MMA(1, 0, At, B0); PG8_MMA(1, 1, At, B1); PG8_BAR; PG8_SCHED;
.LBB0_842:
	s_waitcnt lgkmcnt(0)
	s_barrier
	v_mfma_f32_16x16x32_f16 v[58:61], v[146:149], v[186:189], v[58:61]
	s_setprio 1
	v_mfma_f32_16x16x32_f16 v[58:61], v[150:153], v[190:193], v[58:61]
	v_mfma_f32_16x16x32_f16 v[50:53], v[158:161], v[190:193], v[50:53]
	v_mfma_f32_16x16x32_f16 v[50:53], v[154:157], v[186:189], v[50:53]
	v_mfma_f32_16x16x32_f16 v[34:37], v[154:157], v[178:181], v[34:37]
	v_mfma_f32_16x16x32_f16 v[34:37], v[158:161], v[182:185], v[34:37]
	v_mfma_f32_16x16x32_f16 v[42:45], v[150:153], v[182:185], v[42:45]
	v_mfma_f32_16x16x32_f16 v[42:45], v[146:149], v[178:181], v[42:45]
	v_mfma_f32_16x16x32_f16 v[26:29], v[146:149], v[170:173], v[26:29]
	v_mfma_f32_16x16x32_f16 v[26:29], v[150:153], v[174:177], v[26:29]
	v_mfma_f32_16x16x32_f16 v[18:21], v[158:161], v[174:177], v[18:21]
	v_mfma_f32_16x16x32_f16 v[18:21], v[154:157], v[170:173], v[18:21]
	v_mfma_f32_16x16x32_f16 v[2:5], v[154:157], v[162:165], v[2:5]
	v_mfma_f32_16x16x32_f16 v[2:5], v[158:161], v[166:169], v[2:5]
	v_mfma_f32_16x16x32_f16 v[10:13], v[150:153], v[166:169], v[10:13]
	v_mfma_f32_16x16x32_f16 v[10:13], v[146:149], v[162:165], v[10:13]
	v_mfma_f32_16x16x32_f16 v[14:17], v[130:133], v[162:165], v[14:17]
	v_mfma_f32_16x16x32_f16 v[14:17], v[134:137], v[166:169], v[14:17]
	v_mfma_f32_16x16x32_f16 v[66:69], v[134:137], v[190:193], v[66:69]
	v_mfma_f32_16x16x32_f16 v[66:69], v[130:133], v[186:189], v[66:69]
	v_mfma_f32_16x16x32_f16 v[54:57], v[138:141], v[186:189], v[54:57]
	v_mfma_f32_16x16x32_f16 v[54:57], v[142:145], v[190:193], v[54:57]
	v_mfma_f32_16x16x32_f16 v[38:41], v[142:145], v[182:185], v[38:41]
	v_mfma_f32_16x16x32_f16 v[38:41], v[138:141], v[178:181], v[38:41]
	v_mfma_f32_16x16x32_f16 v[46:49], v[130:133], v[178:181], v[46:49]
	v_mfma_f32_16x16x32_f16 v[46:49], v[134:137], v[182:185], v[46:49]
	v_mfma_f32_16x16x32_f16 v[30:33], v[134:137], v[174:177], v[30:33]
	v_mfma_f32_16x16x32_f16 v[30:33], v[130:133], v[170:173], v[30:33]
	v_mfma_f32_16x16x32_f16 v[22:25], v[138:141], v[170:173], v[22:25]
	v_mfma_f32_16x16x32_f16 v[22:25], v[142:145], v[174:177], v[22:25]
	v_mfma_f32_16x16x32_f16 v[6:9], v[142:145], v[166:169], v[6:9]
	v_mfma_f32_16x16x32_f16 v[6:9], v[138:141], v[162:165], v[6:9]
	s_barrier
	s_setprio 0
	s_add_i32 s55, s55, 2
	s_add_u32 s53, s53, 0x100
	s_addc_u32 s54, s54, 0
	s_cmp_gt_u32 s55, 13
	s_cbranch_scc1 .LBB0_853
.LBB0_843:
	ds_read_b128 v[146:149], v210
	ds_read_b128 v[150:153], v210 offset:1024
	ds_read_b128 v[154:157], v210 offset:2048
	ds_read_b128 v[158:161], v210 offset:3072
	ds_read_b128 v[130:133], v211
	ds_read_b128 v[134:137], v211 offset:1024
	ds_read_b128 v[138:141], v211 offset:2048
	ds_read_b128 v[142:145], v211 offset:3072
	s_mov_b64 s[6:7], s[48:49]
	s_add_u32 s48, s6, 0x100
	s_addc_u32 s49, s7, 0
	s_cmp_eq_u32 s55, 12
	s_cselect_b64 s[26:27], -1, 0
	s_and_b64 s[8:9], s[26:27], exec
	s_cselect_b32 s25, s41, s49
	s_cselect_b32 s24, s51, s48
	s_cselect_b32 s9, s39, s54
	s_cselect_b32 s8, s52, s53
	ds_read_b128 v[162:165], v212
	ds_read_b128 v[166:169], v212 offset:1024
	ds_read_b128 v[170:173], v212 offset:2048
	ds_read_b128 v[174:177], v212 offset:3072
	ds_read_b128 v[178:181], v212 offset:4096
	ds_read_b128 v[182:185], v212 offset:5120
	ds_read_b128 v[186:189], v212 offset:6144
	ds_read_b128 v[190:193], v212 offset:7168
	s_add_u32 s6, s6, 0x40080
	s_addc_u32 s7, s7, 0
	s_add_u32 m0, s14, 0xc000
	s_nop 0
	global_load_lds_dwordx4 v206, s[6:7]
	s_nop 0
	s_add_u32 m0, s14, 0xe000
	s_nop 0
	global_load_lds_dwordx4 v208, s[6:7]
	s_waitcnt vmcnt(8)
	s_waitcnt lgkmcnt(0)
	s_barrier
	v_mfma_f32_16x16x32_f16 v[114:117], v[146:149], v[162:165], v[114:117]
	s_setprio 1
	v_mfma_f32_16x16x32_f16 v[114:117], v[150:153], v[166:169], v[114:117]
	v_mfma_f32_16x16x32_f16 v[110:113], v[158:161], v[166:169], v[110:113]
	v_mfma_f32_16x16x32_f16 v[110:113], v[154:157], v[162:165], v[110:113]
	v_mfma_f32_16x16x32_f16 v[98:101], v[154:157], v[170:173], v[98:101]
	v_mfma_f32_16x16x32_f16 v[98:101], v[158:161], v[174:177], v[98:101]
	v_mfma_f32_16x16x32_f16 v[106:109], v[150:153], v[174:177], v[106:109]
	v_mfma_f32_16x16x32_f16 v[106:109], v[146:149], v[170:173], v[106:109]
	v_mfma_f32_16x16x32_f16 v[90:93], v[146:149], v[178:181], v[90:93]
	v_mfma_f32_16x16x32_f16 v[90:93], v[150:153], v[182:185], v[90:93]
	v_mfma_f32_16x16x32_f16 v[82:85], v[158:161], v[182:185], v[82:85]
	v_mfma_f32_16x16x32_f16 v[82:85], v[154:157], v[178:181], v[82:85]
	v_mfma_f32_16x16x32_f16 v[62:65], v[154:157], v[186:189], v[62:65]
	v_mfma_f32_16x16x32_f16 v[62:65], v[158:161], v[190:193], v[62:65]
	v_mfma_f32_16x16x32_f16 v[74:77], v[150:153], v[190:193], v[74:77]
	v_mfma_f32_16x16x32_f16 v[74:77], v[146:149], v[186:189], v[74:77]
	v_mfma_f32_16x16x32_f16 v[78:81], v[130:133], v[186:189], v[78:81]
	v_mfma_f32_16x16x32_f16 v[78:81], v[134:137], v[190:193], v[78:81]
	v_mfma_f32_16x16x32_f16 v[126:129], v[134:137], v[166:169], v[126:129]
	v_mfma_f32_16x16x32_f16 v[126:129], v[130:133], v[162:165], v[126:129]
	v_mfma_f32_16x16x32_f16 v[122:125], v[138:141], v[162:165], v[122:125]
	v_mfma_f32_16x16x32_f16 v[122:125], v[142:145], v[166:169], v[122:125]
	v_mfma_f32_16x16x32_f16 v[102:105], v[142:145], v[174:177], v[102:105]
	v_mfma_f32_16x16x32_f16 v[102:105], v[138:141], v[170:173], v[102:105]
	v_mfma_f32_16x16x32_f16 v[118:121], v[130:133], v[170:173], v[118:121]
	v_mfma_f32_16x16x32_f16 v[118:121], v[134:137], v[174:177], v[118:121]
	v_mfma_f32_16x16x32_f16 v[94:97], v[134:137], v[182:185], v[94:97]
	v_mfma_f32_16x16x32_f16 v[94:97], v[130:133], v[178:181], v[94:97]
	v_mfma_f32_16x16x32_f16 v[86:89], v[138:141], v[178:181], v[86:89]
	v_mfma_f32_16x16x32_f16 v[86:89], v[142:145], v[182:185], v[86:89]
	v_mfma_f32_16x16x32_f16 v[70:73], v[142:145], v[190:193], v[70:73]
	v_mfma_f32_16x16x32_f16 v[70:73], v[138:141], v[186:189], v[70:73]
	s_barrier
	s_setprio 0
	ds_read_b128 v[186:189], v212 offset:16384
	ds_read_b128 v[190:193], v212 offset:17408
	ds_read_b128 v[178:181], v212 offset:18432
	ds_read_b128 v[182:185], v212 offset:19456
	ds_read_b128 v[170:173], v212 offset:20480
	ds_read_b128 v[174:177], v212 offset:21504
	ds_read_b128 v[162:165], v212 offset:22528
	ds_read_b128 v[166:169], v212 offset:23552
	s_and_b64 s[6:7], s[4:5], s[26:27]
	s_mov_b64 s[26:27], -1
	s_and_b64 vcc, exec, s[6:7]
	s_cbranch_vccnz .LBB0_845
	s_add_u32 m0, s14, 0x10000
	s_nop 0
	global_load_lds_dwordx4 v207, s[8:9]
	s_nop 0
	s_add_u32 m0, s14, 0x12000
	s_nop 0
	global_load_lds_dwordx4 v209, s[8:9]
	s_add_u32 s26, s8, 0x40000
	s_addc_u32 s27, s9, 0
	s_add_u32 m0, s14, 0x14000
	s_nop 0
	global_load_lds_dwordx4 v207, s[26:27]
	s_nop 0
	s_add_u32 m0, s14, 0x16000
	s_nop 0
	global_load_lds_dwordx4 v209, s[26:27]
	s_mov_b64 s[26:27], 0
	s_add_u32 m0, s14, 0
	s_nop 0
	global_load_lds_dwordx4 v206, s[24:25]
	s_nop 0
	s_add_u32 m0, s14, 0x2000
	s_nop 0
	global_load_lds_dwordx4 v208, s[24:25]
	s_waitcnt vmcnt(8)

; #define PG8_STAGE(bufoff, gbase, voff) do { if constexpr (ABL & 1) break; glds16s<(bufoff)>((voff)[0], (const void*)(gbase), ldsbw); glds16s<(bufoff) + 8192>((voff)[1], (const void*)(gbase), ldsbw); } while (0)
; #define PG8_LDA(dst, b, h) do { if constexpr (ABL & 4) break; _Pragma("unroll") for (int m = 0; m < 4; ++m) _Pragma("unroll") for (int k = 0; k < 2; ++k) dst[m][k] = *(const LAS f16x8*)(lds + PG8_SA(b, h) + aoff + m * 2048 + k * 1024); } while (0)
; #define PG8_LDB(dst, b, h) do { if constexpr (ABL & 4) break; _Pragma("unroll") for (int n = 0; n < 2; ++n) _Pragma("unroll") for (int k = 0; k < 2; ++k) dst[n][k] = *(const LAS f16x8*)(lds + PG8_SB(b, h) + boff + n * 2048 + k * 1024); } while (0)
; #define PG8_MMA(ai, bj, At, Bt) do { if constexpr (ABL & 2) break; __builtin_amdgcn_s_setprio(1); _Pragma("unroll") for (int m = 0; m < 4; ++m) _Pragma("unroll") for (int n = 0; n < 2; ++n) _Pragma("unroll") for (int k = 0; k < 2; ++k) \
;         acc[ai][bj][m][n] = __builtin_amdgcn_mfma_f32_16x16x32_f16(Bt[n][k], At[m][k], acc[ai][bj][m][n], 0, 0, 0); __builtin_amdgcn_s_setprio(0); } while (0)
; #define PG8_MMAF(ai, bj, At, Bt) do { if (t == 0) PG8_MMA0(ai, bj, At, Bt); else PG8_MMA(ai, bj, At, Bt); } while (0)
; #define PG8_WAIT_V(n) asm volatile("s_waitcnt vmcnt(" #n ")" ::: "memory")
; #define PG8_WAIT_L(n) asm volatile("s_waitcnt lgkmcnt(" #n ")" ::: "memory")
; #define PG8_BAR __builtin_amdgcn_s_barrier()
; #define PG8_SCHED __builtin_amdgcn_sched_barrier(0)
;     ...
;             if (!fin) PG8_WAIT_V(8); else PG8_WAIT_V(2); PG8_WAIT_L(0); PG8_BAR; PG8_MMAF(1, 0, At, B0); PG8_MMAF(1, 1, At, B1); PG8_BAR; PG8_SCHED;
;             PG8_LDB(B0, 1, 0); PG8_LDB(B1, 1, 1); PG8_SCHED; PG8_LDA(At, 1, 0); if (!fin) PG8_STAGE(PG8_SA(0, 1), a2 + hstep, voffA);
;             if (!fin) PG8_WAIT_V(8); else PG8_WAIT_V(0); PG8_WAIT_L(0); PG8_BAR; PG8_MMA(0, 0, At, B0); PG8_MMA(0, 1, At, B1); PG8_BAR; PG8_SCHED;
.LBB0_847:
	s_waitcnt lgkmcnt(0)
	s_xor_b64 s[26:27], s[6:7], -1
	s_barrier
	v_mfma_f32_16x16x32_f16 v[58:61], v[146:149], v[186:189], v[58:61]
	s_setprio 1
	v_mfma_f32_16x16x32_f16 v[58:61], v[150:153], v[190:193], v[58:61]
	v_mfma_f32_16x16x32_f16 v[50:53], v[158:161], v[190:193], v[50:53]
	v_mfma_f32_16x16x32_f16 v[50:53], v[154:157], v[186:189], v[50:53]
	v_mfma_f32_16x16x32_f16 v[34:37], v[154:157], v[178:181], v[34:37]
	v_mfma_f32_16x16x32_f16 v[34:37], v[158:161], v[182:185], v[34:37]
	v_mfma_f32_16x16x32_f16 v[42:45], v[150:153], v[182:185], v[42:45]
	v_mfma_f32_16x16x32_f16 v[42:45], v[146:149], v[178:181], v[42:45]
	v_mfma_f32_16x16x32_f16 v[26:29], v[146:149], v[170:173], v[26:29]
	v_mfma_f32_16x16x32_f16 v[26:29], v[150:153], v[174:177], v[26:29]
	v_mfma_f32_16x16x32_f16 v[18:21], v[158:161], v[174:177], v[18:21]
	v_mfma_f32_16x16x32_f16 v[18:21], v[154:157], v[170:173], v[18:21]
	v_mfma_f32_16x16x32_f16 v[2:5], v[154:157], v[162:165], v[2:5]
	v_mfma_f32_16x16x32_f16 v[2:5], v[158:161], v[166:169], v[2:5]
	v_mfma_f32_16x16x32_f16 v[10:13], v[150:153], v[166:169], v[10:13]
	v_mfma_f32_16x16x32_f16 v[10:13], v[146:149], v[162:165], v[10:13]
	v_mfma_f32_16x16x32_f16 v[14:17], v[130:133], v[162:165], v[14:17]
	v_mfma_f32_16x16x32_f16 v[14:17], v[134:137], v[166:169], v[14:17]
	v_mfma_f32_16x16x32_f16 v[66:69], v[134:137], v[190:193], v[66:69]
	v_mfma_f32_16x16x32_f16 v[66:69], v[130:133], v[186:189], v[66:69]
	v_mfma_f32_16x16x32_f16 v[54:57], v[138:141], v[186:189], v[54:57]
	v_mfma_f32_16x16x32_f16 v[54:57], v[142:145], v[190:193], v[54:57]
	v_mfma_f32_16x16x32_f16 v[38:41], v[142:145], v[182:185], v[38:41]
	v_mfma_f32_16x16x32_f16 v[38:41], v[138:141], v[178:181], v[38:41]
	v_mfma_f32_16x16x32_f16 v[46:49], v[130:133], v[178:181], v[46:49]
	v_mfma_f32_16x16x32_f16 v[46:49], v[134:137], v[182:185], v[46:49]
	v_mfma_f32_16x16x32_f16 v[30:33], v[134:137], v[174:177], v[30:33]
	v_mfma_f32_16x16x32_f16 v[30:33], v[130:133], v[170:173], v[30:33]
	v_mfma_f32_16x16x32_f16 v[22:25], v[138:141], v[170:173], v[22:25]
	v_mfma_f32_16x16x32_f16 v[22:25], v[142:145], v[174:177], v[22:25]
	v_mfma_f32_16x16x32_f16 v[6:9], v[142:145], v[166:169], v[6:9]
	v_mfma_f32_16x16x32_f16 v[6:9], v[138:141], v[162:165], v[6:9]
	s_barrier
	s_setprio 0
	ds_read_b128 v[146:149], v213
	ds_read_b128 v[150:153], v213 offset:1024
	ds_read_b128 v[154:157], v213 offset:2048
	ds_read_b128 v[158:161], v213 offset:3072
	ds_read_b128 v[130:133], v214
	ds_read_b128 v[134:137], v214 offset:1024
	ds_read_b128 v[138:141], v214 offset:2048
	ds_read_b128 v[142:145], v214 offset:3072
	ds_read_b128 v[186:189], v212 offset:32768
	ds_read_b128 v[190:193], v212 offset:33792
	ds_read_b128 v[178:181], v212 offset:34816
	ds_read_b128 v[182:185], v212 offset:35840
	ds_read_b128 v[170:173], v212 offset:36864
	ds_read_b128 v[174:177], v212 offset:37888
	ds_read_b128 v[162:165], v212 offset:38912
	ds_read_b128 v[166:169], v212 offset:39936
	v_cndmask_b32_e64 v216, 0, 1, s[26:27]
	v_cmp_ne_u32_e64 s[6:7], 1, v216
	s_andn2_b64 vcc, exec, s[26:27]
	s_mov_b64 s[26:27], -1
	s_cbranch_vccnz .LBB0_849
	s_add_u32 s26, s24, 0x40000
	s_addc_u32 s27, s25, 0
	s_add_u32 m0, s14, 0x4000
	s_nop 0
	global_load_lds_dwordx4 v206, s[26:27]
	s_nop 0
	s_add_u32 m0, s14, 0x6000
	s_nop 0
	global_load_lds_dwordx4 v208, s[26:27]
	s_waitcnt vmcnt(8)
	s_mov_b64 s[26:27], 0

; #define PG8_STAGE(bufoff, gbase, voff) do { if constexpr (ABL & 1) break; glds16s<(bufoff)>((voff)[0], (const void*)(gbase), ldsbw); glds16s<(bufoff) + 8192>((voff)[1], (const void*)(gbase), ldsbw); } while (0)
; #define PG8_LDA(dst, b, h) do { if constexpr (ABL & 4) break; _Pragma("unroll") for (int m = 0; m < 4; ++m) _Pragma("unroll") for (int k = 0; k < 2; ++k) dst[m][k] = *(const LAS f16x8*)(lds + PG8_SA(b, h) + aoff + m * 2048 + k * 1024); } while (0)
; #define PG8_MMA(ai, bj, At, Bt) do { if constexpr (ABL & 2) break; __builtin_amdgcn_s_setprio(1); _Pragma("unroll") for (int m = 0; m < 4; ++m) _Pragma("unroll") for (int n = 0; n < 2; ++n) _Pragma("unroll") for (int k = 0; k < 2; ++k) \
;         acc[ai][bj][m][n] = __builtin_amdgcn_mfma_f32_16x16x32_f16(Bt[n][k], At[m][k], acc[ai][bj][m][n], 0, 0, 0); __builtin_amdgcn_s_setprio(0); } while (0)
; #define PG8_WAIT_V(n) asm volatile("s_waitcnt vmcnt(" #n ")" ::: "memory")
; #define PG8_WAIT_L(n) asm volatile("s_waitcnt lgkmcnt(" #n ")" ::: "memory")
; #define PG8_BAR __builtin_amdgcn_s_barrier()
; #define PG8_SCHED __builtin_amdgcn_sched_barrier(0)
;     ...
;             if (!fin) PG8_WAIT_V(8); else PG8_WAIT_V(0); PG8_WAIT_L(0); PG8_BAR; PG8_MMA(0, 0, At, B0); PG8_MMA(0, 1, At, B1); PG8_BAR; PG8_SCHED;
;             PG8_LDA(At, 1, 1); if (!fin) { PG8_STAGE(PG8_SB(1, 0), b3, voffB); PG8_STAGE(PG8_SB(1, 1), b3 + hstep, voffB); PG8_STAGE(PG8_SA(1, 0), a3, voffA); }
;             if (!fin) PG8_WAIT_V(8); PG8_WAIT_L(0); PG8_BAR; PG8_MMA(1, 0, At, B0); PG8_MMA(1, 1, At, B1); PG8_BAR; PG8_SCHED;
.LBB0_851:
	s_waitcnt lgkmcnt(0)
	s_barrier
	v_mfma_f32_16x16x32_f16 v[114:117], v[146:149], v[186:189], v[114:117]
	s_setprio 1
	v_mfma_f32_16x16x32_f16 v[114:117], v[150:153], v[190:193], v[114:117]
	v_mfma_f32_16x16x32_f16 v[110:113], v[158:161], v[190:193], v[110:113]
	v_mfma_f32_16x16x32_f16 v[110:113], v[154:157], v[186:189], v[110:113]
	v_mfma_f32_16x16x32_f16 v[98:101], v[154:157], v[178:181], v[98:101]
	v_mfma_f32_16x16x32_f16 v[98:101], v[158:161], v[182:185], v[98:101]
	v_mfma_f32_16x16x32_f16 v[106:109], v[150:153], v[182:185], v[106:109]
	v_mfma_f32_16x16x32_f16 v[106:109], v[146:149], v[178:181], v[106:109]
	v_mfma_f32_16x16x32_f16 v[90:93], v[146:149], v[170:173], v[90:93]
	v_mfma_f32_16x16x32_f16 v[90:93], v[150:153], v[174:177], v[90:93]
	v_mfma_f32_16x16x32_f16 v[82:85], v[158:161], v[174:177], v[82:85]
	v_mfma_f32_16x16x32_f16 v[82:85], v[154:157], v[170:173], v[82:85]
	v_mfma_f32_16x16x32_f16 v[62:65], v[154:157], v[162:165], v[62:65]
	v_mfma_f32_16x16x32_f16 v[62:65], v[158:161], v[166:169], v[62:65]
	v_mfma_f32_16x16x32_f16 v[74:77], v[150:153], v[166:169], v[74:77]
	v_mfma_f32_16x16x32_f16 v[74:77], v[146:149], v[162:165], v[74:77]
	v_mfma_f32_16x16x32_f16 v[78:81], v[130:133], v[162:165], v[78:81]
	v_mfma_f32_16x16x32_f16 v[78:81], v[134:137], v[166:169], v[78:81]
	v_mfma_f32_16x16x32_f16 v[126:129], v[134:137], v[190:193], v[126:129]
	v_mfma_f32_16x16x32_f16 v[126:129], v[130:133], v[186:189], v[126:129]
	v_mfma_f32_16x16x32_f16 v[122:125], v[138:141], v[186:189], v[122:125]
	v_mfma_f32_16x16x32_f16 v[122:125], v[142:145], v[190:193], v[122:125]
	v_mfma_f32_16x16x32_f16 v[102:105], v[142:145], v[182:185], v[102:105]
	v_mfma_f32_16x16x32_f16 v[102:105], v[138:141], v[178:181], v[102:105]
	v_mfma_f32_16x16x32_f16 v[118:121], v[130:133], v[178:181], v[118:121]
	v_mfma_f32_16x16x32_f16 v[118:121], v[134:137], v[182:185], v[118:121]
	v_mfma_f32_16x16x32_f16 v[94:97], v[134:137], v[174:177], v[94:97]
	v_mfma_f32_16x16x32_f16 v[94:97], v[130:133], v[170:173], v[94:97]
	v_mfma_f32_16x16x32_f16 v[86:89], v[138:141], v[170:173], v[86:89]
	v_mfma_f32_16x16x32_f16 v[86:89], v[142:145], v[174:177], v[86:89]
	v_mfma_f32_16x16x32_f16 v[70:73], v[142:145], v[166:169], v[70:73]
	v_mfma_f32_16x16x32_f16 v[70:73], v[138:141], v[162:165], v[70:73]
	s_barrier
	s_setprio 0
	ds_read_b128 v[186:189], v212 offset:49152
	ds_read_b128 v[190:193], v212 offset:50176
	ds_read_b128 v[178:181], v212 offset:51200
	ds_read_b128 v[182:185], v212 offset:52224
	ds_read_b128 v[170:173], v212 offset:53248
	ds_read_b128 v[174:177], v212 offset:54272
	ds_read_b128 v[162:165], v212 offset:55296
	ds_read_b128 v[166:169], v212 offset:56320
	s_and_b64 vcc, exec, s[6:7]
	s_cbranch_vccnz .LBB0_842
	s_add_u32 s6, s24, 0x80
	s_addc_u32 s7, s25, 0
	s_add_u32 s24, s8, 0x80
	s_addc_u32 s25, s9, 0
	s_add_u32 m0, s14, 0x18000
	s_nop 0
	global_load_lds_dwordx4 v207, s[24:25]
	s_nop 0
	s_add_u32 m0, s14, 0x1a000
	s_nop 0
	global_load_lds_dwordx4 v209, s[24:25]
	s_add_u32 s8, s8, 0x40080
	s_addc_u32 s9, s9, 0
	s_add_u32 m0, s14, 0x1c000
	s_nop 0
	global_load_lds_dwordx4 v207, s[8:9]
	s_nop 0
	s_add_u32 m0, s14, 0x1e000
	s_nop 0
	global_load_lds_dwordx4 v209, s[8:9]
	s_nop 0
	s_add_u32 m0, s14, 0x8000
	s_nop 0
	global_load_lds_dwordx4 v206, s[6:7]
	s_nop 0
	s_add_u32 m0, s14, 0xa000
	s_nop 0
	global_load_lds_dwordx4 v208, s[6:7]
	s_waitcnt vmcnt(8)
	s_branch .LBB0_842

;     __device__ __forceinline__ bool next(int i, Unit& u) const { if (i >= count) return false; const int L = first + i; u.pm = L / nN; u.pn = L % nN; return true; }
; #define PG8_STAGE(bufoff, gbase, voff) do { if constexpr (ABL & 1) break; glds16s<(bufoff)>((voff)[0], (const void*)(gbase), ldsbw); glds16s<(bufoff) + 8192>((voff)[1], (const void*)(gbase), ldsbw); } while (0)
; #define PG8_LDA(dst, b, h) do { if constexpr (ABL & 4) break; _Pragma("unroll") for (int m = 0; m < 4; ++m) _Pragma("unroll") for (int k = 0; k < 2; ++k) dst[m][k] = *(const LAS f16x8*)(lds + PG8_SA(b, h) + aoff + m * 2048 + k * 1024); } while (0)
; #define PG8_LDB(dst, b, h) do { if constexpr (ABL & 4) break; _Pragma("unroll") for (int n = 0; n < 2; ++n) _Pragma("unroll") for (int k = 0; k < 2; ++k) dst[n][k] = *(const LAS f16x8*)(lds + PG8_SB(b, h) + boff + n * 2048 + k * 1024); } while (0)
; #define PG8_MMAF(ai, bj, At, Bt) do { if (t == 0) PG8_MMA0(ai, bj, At, Bt); else PG8_MMA(ai, bj, At, Bt); } while (0)
; #define PG8_WAIT_V(n) asm volatile("s_waitcnt vmcnt(" #n ")" ::: "memory")
; #define PG8_BAR __builtin_amdgcn_s_barrier()
;     ...
;         const bool has_next = S.next(ui + 1, nxt);
;         const char* nA = has_next ? (const char*)g.A + (size_t)nxt.pm * tstep : cA; const char* nB = has_next ? (const char*)g.Bt + (size_t)nxt.pn * tstep : cB;
;         for (int t = 0; t < nt; t += 2) {
;             const bool last = (t == nt - 2);
;             const char* a1 = cA + (size_t)(t + 1) * kstep;
;             const char* a2 = last ? nA : cA + (size_t)(t + 2) * kstep; const char* b2 = last ? nB : cB + (size_t)(t + 2) * kstep;
;             const char* a3 = a2 + kstep; const char* b3 = b2 + kstep;
;             if (last && has_next) S.a_ready(nxt);
;             if constexpr (SP2) {
;             PG8_LDB(B0, 0, 0); PG8_LDB(B1, 0, 1); PG8_SCHED; PG8_LDA(At, 0, 0); PG8_STAGE(PG8_SA(1, 1), a1 + hstep, voffA);
;             PG8_WAIT_V(8); PG8_WAIT_L(0); PG8_BAR; PG8_MMAF(0, 0, At, B0); PG8_MMAF(0, 1, At, B1); PG8_BAR; PG8_SCHED;
;             const bool fin = last && !has_next;
;             PG8_LDA(At, 0, 1); if (!fin) { PG8_STAGE(PG8_SB(0, 0), b2, voffB); PG8_STAGE(PG8_SB(0, 1), b2 + hstep, voffB); PG8_STAGE(PG8_SA(0, 0), a2, voffA); }
;             if (!fin) PG8_WAIT_V(8); else PG8_WAIT_V(2); PG8_WAIT_L(0); PG8_BAR; PG8_MMAF(1, 0, At, B0); PG8_MMAF(1, 1, At, B1); PG8_BAR; PG8_SCHED;
.LBB0_987:
	s_waitcnt lgkmcnt(0)
	ds_read_b128 v[2:5], v213
	ds_read_b128 v[6:9], v213 offset:1024
	ds_read_b128 v[10:13], v213 offset:2048
	ds_read_b128 v[14:17], v213 offset:3072
	ds_read_b128 v[18:21], v214
	ds_read_b128 v[22:25], v214 offset:1024
	ds_read_b128 v[26:29], v214 offset:2048
	ds_read_b128 v[30:33], v214 offset:3072
	s_add_u32 s50, s54, 0x100
	s_addc_u32 s51, s55, 0
	s_add_u32 s24, s52, 0x100
	s_addc_u32 s25, s53, 0
	s_add_u32 s6, s54, 0x180
	s_addc_u32 s7, s55, 0
	ds_read_b128 v[34:37], v215
	ds_read_b128 v[38:41], v215 offset:1024
	ds_read_b128 v[42:45], v215 offset:2048
	ds_read_b128 v[46:49], v215 offset:3072
	ds_read_b128 v[50:53], v215 offset:4096
	ds_read_b128 v[54:57], v215 offset:5120
	ds_read_b128 v[58:61], v215 offset:6144
	ds_read_b128 v[62:65], v215 offset:7168
	s_add_u32 s8, s52, 0x180
	s_addc_u32 s9, s53, 0
	s_add_u32 s26, s54, 0xb0080
	s_addc_u32 s27, s55, 0
	s_add_u32 m0, s28, 0xc000
	s_nop 0
	global_load_lds_dwordx4 v1, s[26:27]
	s_nop 0
	s_add_u32 m0, s28, 0xe000
	s_nop 0
	global_load_lds_dwordx4 v211, s[26:27]
	s_waitcnt vmcnt(8)
	s_waitcnt lgkmcnt(0)
	s_barrier
	v_mfma_f32_16x16x32_f16 v[70:73], v[10:13], v[34:37], 0
	s_setprio 1
	v_mfma_f32_16x16x32_f16 v[70:73], v[14:17], v[38:41], v[70:73]
	v_mfma_f32_16x16x32_f16 v[74:77], v[2:5], v[42:45], 0
	v_mfma_f32_16x16x32_f16 v[74:77], v[6:9], v[46:49], v[74:77]
	v_mfma_f32_16x16x32_f16 v[82:85], v[2:5], v[50:53], 0
	v_mfma_f32_16x16x32_f16 v[82:85], v[6:9], v[54:57], v[82:85]
	v_mfma_f32_16x16x32_f16 v[86:89], v[10:13], v[50:53], 0
	v_mfma_f32_16x16x32_f16 v[86:89], v[14:17], v[54:57], v[86:89]
	v_mfma_f32_16x16x32_f16 v[94:97], v[10:13], v[58:61], 0
	v_mfma_f32_16x16x32_f16 v[94:97], v[14:17], v[62:65], v[94:97]
	v_mfma_f32_16x16x32_f16 v[66:69], v[2:5], v[34:37], 0
	v_mfma_f32_16x16x32_f16 v[66:69], v[6:9], v[38:41], v[66:69]
	v_mfma_f32_16x16x32_f16 v[78:81], v[10:13], v[42:45], 0
	v_mfma_f32_16x16x32_f16 v[78:81], v[14:17], v[46:49], v[78:81]
	v_mfma_f32_16x16x32_f16 v[90:93], v[2:5], v[58:61], 0
	v_mfma_f32_16x16x32_f16 v[90:93], v[6:9], v[62:65], v[90:93]
	v_mfma_f32_16x16x32_f16 v[98:101], v[18:21], v[34:37], 0
	v_mfma_f32_16x16x32_f16 v[98:101], v[22:25], v[38:41], v[98:101]
	v_mfma_f32_16x16x32_f16 v[34:37], v[26:29], v[34:37], 0
	v_mfma_f32_16x16x32_f16 v[34:37], v[30:33], v[38:41], v[34:37]
	v_mfma_f32_16x16x32_f16 v[38:41], v[18:21], v[42:45], 0
	v_mfma_f32_16x16x32_f16 v[38:41], v[22:25], v[46:49], v[38:41]
	v_mfma_f32_16x16x32_f16 v[42:45], v[26:29], v[42:45], 0
	v_mfma_f32_16x16x32_f16 v[42:45], v[30:33], v[46:49], v[42:45]
	v_mfma_f32_16x16x32_f16 v[46:49], v[18:21], v[50:53], 0
	v_mfma_f32_16x16x32_f16 v[46:49], v[22:25], v[54:57], v[46:49]
	v_mfma_f32_16x16x32_f16 v[50:53], v[26:29], v[50:53], 0
	v_mfma_f32_16x16x32_f16 v[50:53], v[30:33], v[54:57], v[50:53]
	v_mfma_f32_16x16x32_f16 v[54:57], v[18:21], v[58:61], 0
	v_mfma_f32_16x16x32_f16 v[54:57], v[22:25], v[62:65], v[54:57]
	v_mfma_f32_16x16x32_f16 v[58:61], v[26:29], v[58:61], 0
	v_mfma_f32_16x16x32_f16 v[58:61], v[30:33], v[62:65], v[58:61]
	s_barrier
	s_setprio 0
	ds_read_b128 v[62:65], v215 offset:16384
	ds_read_b128 v[102:105], v215 offset:17408
	ds_read_b128 v[106:109], v215 offset:18432
	ds_read_b128 v[110:113], v215 offset:19456
	ds_read_b128 v[114:117], v215 offset:20480
	ds_read_b128 v[118:121], v215 offset:21504
	ds_read_b128 v[122:125], v215 offset:22528
	ds_read_b128 v[126:129], v215 offset:23552
	s_add_u32 m0, s28, 0x10000
	s_nop 0
	global_load_lds_dwordx4 v210, s[24:25]
	s_nop 0
	s_add_u32 m0, s28, 0x12000
	s_nop 0
	global_load_lds_dwordx4 v212, s[24:25]
	s_add_u32 s24, s52, 0xb0100
	s_addc_u32 s25, s53, 0
	s_add_u32 m0, s28, 0x14000
	s_nop 0
	global_load_lds_dwordx4 v210, s[24:25]
	s_nop 0
	s_add_u32 m0, s28, 0x16000
	s_nop 0
	global_load_lds_dwordx4 v212, s[24:25]
	s_nop 0
	s_add_u32 m0, s28, 0
	s_nop 0
	global_load_lds_dwordx4 v1, s[50:51]
	s_nop 0
	s_add_u32 m0, s28, 0x2000
	s_nop 0
	global_load_lds_dwordx4 v211, s[50:51]
	s_waitcnt vmcnt(8)
	s_waitcnt lgkmcnt(0)
	s_barrier
	v_mfma_f32_16x16x32_f16 v[130:133], v[2:5], v[62:65], 0
	s_setprio 1
	v_mfma_f32_16x16x32_f16 v[138:141], v[6:9], v[102:105], v[130:133]
	v_mfma_f32_16x16x32_f16 v[130:133], v[10:13], v[62:65], 0
	v_mfma_f32_16x16x32_f16 v[158:161], v[14:17], v[102:105], v[130:133]
	v_mfma_f32_16x16x32_f16 v[130:133], v[2:5], v[106:109], 0
	v_mfma_f32_16x16x32_f16 v[162:165], v[6:9], v[110:113], v[130:133]
	v_mfma_f32_16x16x32_f16 v[130:133], v[10:13], v[106:109], 0
	v_mfma_f32_16x16x32_f16 v[166:169], v[14:17], v[110:113], v[130:133]
	v_mfma_f32_16x16x32_f16 v[130:133], v[2:5], v[114:117], 0
	v_mfma_f32_16x16x32_f16 v[170:173], v[6:9], v[118:121], v[130:133]
	v_mfma_f32_16x16x32_f16 v[2:5], v[2:5], v[122:125], 0
	v_mfma_f32_16x16x32_f16 v[2:5], v[6:9], v[126:129], v[2:5]
	v_mfma_f32_16x16x32_f16 v[6:9], v[10:13], v[122:125], 0
	v_mfma_f32_16x16x32_f16 v[6:9], v[14:17], v[126:129], v[6:9]
	v_mfma_f32_16x16x32_f16 v[130:133], v[10:13], v[114:117], 0
	v_mfma_f32_16x16x32_f16 v[174:177], v[14:17], v[118:121], v[130:133]
	v_mfma_f32_16x16x32_f16 v[10:13], v[18:21], v[62:65], 0
	v_mfma_f32_16x16x32_f16 v[178:181], v[22:25], v[102:105], v[10:13]
	v_mfma_f32_16x16x32_f16 v[10:13], v[26:29], v[62:65], 0
	v_mfma_f32_16x16x32_f16 v[102:105], v[30:33], v[102:105], v[10:13]
	v_mfma_f32_16x16x32_f16 v[10:13], v[18:21], v[106:109], 0
	v_mfma_f32_16x16x32_f16 v[182:185], v[22:25], v[110:113], v[10:13]
	v_mfma_f32_16x16x32_f16 v[10:13], v[26:29], v[106:109], 0
	v_mfma_f32_16x16x32_f16 v[186:189], v[30:33], v[110:113], v[10:13]
	v_mfma_f32_16x16x32_f16 v[10:13], v[18:21], v[114:117], 0
	v_mfma_f32_16x16x32_f16 v[190:193], v[22:25], v[118:121], v[10:13]
	v_mfma_f32_16x16x32_f16 v[10:13], v[26:29], v[114:117], 0
	v_mfma_f32_16x16x32_f16 v[114:117], v[30:33], v[118:121], v[10:13]
	v_mfma_f32_16x16x32_f16 v[10:13], v[18:21], v[122:125], 0
	v_mfma_f32_16x16x32_f16 v[194:197], v[22:25], v[126:129], v[10:13]
	v_mfma_f32_16x16x32_f16 v[10:13], v[26:29], v[122:125], 0
	v_mfma_f32_16x16x32_f16 v[126:129], v[30:33], v[126:129], v[10:13]
	s_barrier
; #define PG8_STAGE(bufoff, gbase, voff) do { if constexpr (ABL & 1) break; glds16s<(bufoff)>((voff)[0], (const void*)(gbase), ldsbw); glds16s<(bufoff) + 8192>((voff)[1], (const void*)(gbase), ldsbw); } while (0)
; #define PG8_LDA(dst, b, h) do { if constexpr (ABL & 4) break; _Pragma("unroll") for (int m = 0; m < 4; ++m) _Pragma("unroll") for (int k = 0; k < 2; ++k) dst[m][k] = *(const LAS f16x8*)(lds + PG8_SA(b, h) + aoff + m * 2048 + k * 1024); } while (0)
; #define PG8_LDB(dst, b, h) do { if constexpr (ABL & 4) break; _Pragma("unroll") for (int n = 0; n < 2; ++n) _Pragma("unroll") for (int k = 0; k < 2; ++k) dst[n][k] = *(const LAS f16x8*)(lds + PG8_SB(b, h) + boff + n * 2048 + k * 1024); } while (0)
; #define PG8_MMA(ai, bj, At, Bt) do { if constexpr (ABL & 2) break; __builtin_amdgcn_s_setprio(1); _Pragma("unroll") for (int m = 0; m < 4; ++m) _Pragma("unroll") for (int n = 0; n < 2; ++n) _Pragma("unroll") for (int k = 0; k < 2; ++k) \
;         acc[ai][bj][m][n] = __builtin_amdgcn_mfma_f32_16x16x32_f16(Bt[n][k], At[m][k], acc[ai][bj][m][n], 0, 0, 0); __builtin_amdgcn_s_setprio(0); } while (0)
; #define PG8_WAIT_V(n) asm volatile("s_waitcnt vmcnt(" #n ")" ::: "memory")
; #define PG8_WAIT_L(n) asm volatile("s_waitcnt lgkmcnt(" #n ")" ::: "memory")
; #define PG8_BAR __builtin_amdgcn_s_barrier()
; #define PG8_SCHED __builtin_amdgcn_sched_barrier(0)
;     ...
;             PG8_LDB(B0, 1, 0); PG8_LDB(B1, 1, 1); PG8_SCHED; PG8_LDA(At, 1, 0); if (!fin) PG8_STAGE(PG8_SA(0, 1), a2 + hstep, voffA);
;             if (!fin) PG8_WAIT_V(8); else PG8_WAIT_V(0); PG8_WAIT_L(0); PG8_BAR; PG8_MMA(0, 0, At, B0); PG8_MMA(0, 1, At, B1); PG8_BAR; PG8_SCHED;
;             PG8_LDA(At, 1, 1); if (!fin) { PG8_STAGE(PG8_SB(1, 0), b3, voffB); PG8_STAGE(PG8_SB(1, 1), b3 + hstep, voffB); PG8_STAGE(PG8_SA(1, 0), a3, voffA); }
;             if (!fin) PG8_WAIT_V(8); PG8_WAIT_L(0); PG8_BAR; PG8_MMA(1, 0, At, B0); PG8_MMA(1, 1, At, B1); PG8_BAR; PG8_SCHED;
	s_setprio 0
	s_nop 4
	ds_read_b128 v[10:13], v216
	ds_read_b128 v[14:17], v216 offset:1024
	ds_read_b128 v[18:21], v216 offset:2048
	ds_read_b128 v[22:25], v216 offset:3072
	ds_read_b128 v[198:201], v217
	ds_read_b128 v[202:205], v217 offset:1024
	ds_read_b128 v[220:223], v217 offset:2048
	ds_read_b128 v[224:227], v217 offset:3072
	ds_read_b128 v[26:29], v215 offset:32768
	ds_read_b128 v[30:33], v215 offset:33792
	ds_read_b128 v[62:65], v215 offset:34816
	ds_read_b128 v[118:121], v215 offset:35840
	ds_read_b128 v[228:231], v215 offset:36864
	ds_read_b128 v[232:235], v215 offset:37888
	ds_read_b128 v[236:239], v215 offset:38912
	ds_read_b128 v[240:243], v215 offset:39936
	s_add_u32 s24, s54, 0xb0100
	s_addc_u32 s25, s55, 0
	s_add_u32 m0, s28, 0x4000
	s_nop 0
	global_load_lds_dwordx4 v1, s[24:25]
	s_nop 0
	s_add_u32 m0, s28, 0x6000
	s_nop 0
	global_load_lds_dwordx4 v211, s[24:25]
	s_waitcnt vmcnt(8)
	s_waitcnt lgkmcnt(0)
	s_barrier
	v_mfma_f32_16x16x32_f16 v[66:69], v[10:13], v[26:29], v[66:69]
	s_setprio 1
	v_mfma_f32_16x16x32_f16 v[154:157], v[14:17], v[30:33], v[66:69]
	v_mfma_f32_16x16x32_f16 v[66:69], v[18:21], v[26:29], v[70:73]
	v_mfma_f32_16x16x32_f16 v[150:153], v[22:25], v[30:33], v[66:69]
	v_mfma_f32_16x16x32_f16 v[66:69], v[10:13], v[62:65], v[74:77]
	v_mfma_f32_16x16x32_f16 v[134:137], v[14:17], v[118:121], v[66:69]
	v_mfma_f32_16x16x32_f16 v[66:69], v[18:21], v[62:65], v[78:81]
	v_mfma_f32_16x16x32_f16 v[130:133], v[22:25], v[118:121], v[66:69]
	v_mfma_f32_16x16x32_f16 v[66:69], v[10:13], v[228:231], v[82:85]
	v_mfma_f32_16x16x32_f16 v[110:113], v[14:17], v[232:235], v[66:69]
	v_mfma_f32_16x16x32_f16 v[66:69], v[18:21], v[228:231], v[86:89]
	v_mfma_f32_16x16x32_f16 v[106:109], v[22:25], v[232:235], v[66:69]
	v_mfma_f32_16x16x32_f16 v[66:69], v[10:13], v[236:239], v[90:93]
	v_mfma_f32_16x16x32_f16 v[86:89], v[14:17], v[240:243], v[66:69]
	v_mfma_f32_16x16x32_f16 v[66:69], v[18:21], v[236:239], v[94:97]
	v_mfma_f32_16x16x32_f16 v[82:85], v[22:25], v[240:243], v[66:69]
	v_mfma_f32_16x16x32_f16 v[66:69], v[198:201], v[26:29], v[98:101]
	v_mfma_f32_16x16x32_f16 v[146:149], v[202:205], v[30:33], v[66:69]
	v_mfma_f32_16x16x32_f16 v[26:29], v[220:223], v[26:29], v[34:37]
	v_mfma_f32_16x16x32_f16 v[142:145], v[224:227], v[30:33], v[26:29]
	v_mfma_f32_16x16x32_f16 v[26:29], v[198:201], v[62:65], v[38:41]
	v_mfma_f32_16x16x32_f16 v[122:125], v[202:205], v[118:121], v[26:29]
	v_mfma_f32_16x16x32_f16 v[26:29], v[220:223], v[62:65], v[42:45]
	v_mfma_f32_16x16x32_f16 v[118:121], v[224:227], v[118:121], v[26:29]
	v_mfma_f32_16x16x32_f16 v[26:29], v[198:201], v[228:231], v[46:49]
	v_mfma_f32_16x16x32_f16 v[98:101], v[202:205], v[232:235], v[26:29]
	v_mfma_f32_16x16x32_f16 v[26:29], v[220:223], v[228:231], v[50:53]
	v_mfma_f32_16x16x32_f16 v[94:97], v[224:227], v[232:235], v[26:29]
	v_mfma_f32_16x16x32_f16 v[26:29], v[198:201], v[236:239], v[54:57]
	v_mfma_f32_16x16x32_f16 v[74:77], v[202:205], v[240:243], v[26:29]
	v_mfma_f32_16x16x32_f16 v[26:29], v[220:223], v[236:239], v[58:61]
	v_mfma_f32_16x16x32_f16 v[70:73], v[224:227], v[240:243], v[26:29]
	s_barrier
	s_setprio 0
	ds_read_b128 v[34:37], v215 offset:49152
	ds_read_b128 v[38:41], v215 offset:50176
	ds_read_b128 v[66:69], v215 offset:51200
	ds_read_b128 v[78:81], v215 offset:52224
	ds_read_b128 v[90:93], v215 offset:53248
	ds_read_b128 v[228:231], v215 offset:54272
	ds_read_b128 v[232:235], v215 offset:55296
	ds_read_b128 v[236:239], v215 offset:56320
	s_add_u32 m0, s28, 0x18000
	s_nop 0
	global_load_lds_dwordx4 v210, s[8:9]
	s_nop 0
	s_add_u32 m0, s28, 0x1a000
	s_nop 0
	global_load_lds_dwordx4 v212, s[8:9]
	s_add_u32 s8, s52, 0xb0180
	s_addc_u32 s9, s53, 0
	s_add_u32 m0, s28, 0x1c000
	s_nop 0
	global_load_lds_dwordx4 v210, s[8:9]
	s_nop 0
	s_add_u32 m0, s28, 0x1e000
	s_nop 0
	global_load_lds_dwordx4 v212, s[8:9]
	s_nop 0
	s_add_u32 m0, s28, 0x8000
	s_nop 0
	global_load_lds_dwordx4 v1, s[6:7]
	s_nop 0
	s_add_u32 m0, s28, 0xa000
	s_nop 0
	global_load_lds_dwordx4 v211, s[6:7]
	s_waitcnt vmcnt(8)
	s_waitcnt lgkmcnt(0)
	s_barrier
	v_mfma_f32_16x16x32_f16 v[26:29], v[10:13], v[34:37], v[138:141]
	s_setprio 1
	v_mfma_f32_16x16x32_f16 v[62:65], v[14:17], v[38:41], v[26:29]
	v_mfma_f32_16x16x32_f16 v[26:29], v[22:25], v[38:41], v[158:161]
	v_mfma_f32_16x16x32_f16 v[58:61], v[18:21], v[34:37], v[26:29]
	v_mfma_f32_16x16x32_f16 v[26:29], v[10:13], v[66:69], v[162:165]
	v_mfma_f32_16x16x32_f16 v[46:49], v[14:17], v[78:81], v[26:29]
	v_mfma_f32_16x16x32_f16 v[26:29], v[22:25], v[78:81], v[166:169]
	v_mfma_f32_16x16x32_f16 v[42:45], v[18:21], v[66:69], v[26:29]
	v_mfma_f32_16x16x32_f16 v[26:29], v[10:13], v[90:93], v[170:173]
	v_mfma_f32_16x16x32_f16 v[30:33], v[14:17], v[228:231], v[26:29]
	v_mfma_f32_16x16x32_f16 v[2:5], v[14:17], v[236:239], v[2:5]
	v_mfma_f32_16x16x32_f16 v[14:17], v[10:13], v[232:235], v[2:5]
	v_mfma_f32_16x16x32_f16 v[2:5], v[18:21], v[232:235], v[6:9]
	v_mfma_f32_16x16x32_f16 v[10:13], v[22:25], v[236:239], v[2:5]
	v_mfma_f32_16x16x32_f16 v[26:29], v[22:25], v[228:231], v[174:177]
	v_mfma_f32_16x16x32_f16 v[26:29], v[18:21], v[90:93], v[26:29]
	v_mfma_f32_16x16x32_f16 v[2:5], v[198:201], v[34:37], v[178:181]
	v_mfma_f32_16x16x32_f16 v[54:57], v[202:205], v[38:41], v[2:5]
	v_mfma_f32_16x16x32_f16 v[2:5], v[224:227], v[38:41], v[102:105]
	v_mfma_f32_16x16x32_f16 v[50:53], v[220:223], v[34:37], v[2:5]
	v_mfma_f32_16x16x32_f16 v[2:5], v[198:201], v[66:69], v[182:185]
	v_mfma_f32_16x16x32_f16 v[38:41], v[202:205], v[78:81], v[2:5]
	v_mfma_f32_16x16x32_f16 v[2:5], v[224:227], v[78:81], v[186:189]
	v_mfma_f32_16x16x32_f16 v[34:37], v[220:223], v[66:69], v[2:5]
	v_mfma_f32_16x16x32_f16 v[2:5], v[198:201], v[90:93], v[190:193]
	v_mfma_f32_16x16x32_f16 v[22:25], v[202:205], v[228:231], v[2:5]
	v_mfma_f32_16x16x32_f16 v[2:5], v[224:227], v[228:231], v[114:117]
	v_mfma_f32_16x16x32_f16 v[18:21], v[220:223], v[90:93], v[2:5]
	v_mfma_f32_16x16x32_f16 v[2:5], v[198:201], v[232:235], v[194:197]
	v_mfma_f32_16x16x32_f16 v[6:9], v[202:205], v[236:239], v[2:5]
	v_mfma_f32_16x16x32_f16 v[2:5], v[224:227], v[236:239], v[126:129]
	v_mfma_f32_16x16x32_f16 v[2:5], v[220:223], v[232:235], v[2:5]
	s_barrier
	s_setprio 0
	s_add_u32 s52, s52, 0x200
	s_addc_u32 s53, s53, 0
	s_mov_b32 s54, 0
	s_branch .LBB0_989
; #define PG8_STAGE(bufoff, gbase, voff) do { if constexpr (ABL & 1) break; glds16s<(bufoff)>((voff)[0], (const void*)(gbase), ldsbw); glds16s<(bufoff) + 8192>((voff)[1], (const void*)(gbase), ldsbw); } while (0)
; #define PG8_LDA(dst, b, h) do { if constexpr (ABL & 4) break; _Pragma("unroll") for (int m = 0; m < 4; ++m) _Pragma("unroll") for (int k = 0; k < 2; ++k) dst[m][k] = *(const LAS f16x8*)(lds + PG8_SA(b, h) + aoff + m * 2048 + k * 1024); } while (0)
; #define PG8_LDB(dst, b, h) do { if constexpr (ABL & 4) break; _Pragma("unroll") for (int n = 0; n < 2; ++n) _Pragma("unroll") for (int k = 0; k < 2; ++k) dst[n][k] = *(const LAS f16x8*)(lds + PG8_SB(b, h) + boff + n * 2048 + k * 1024); } while (0)
; #define PG8_MMA(ai, bj, At, Bt) do { if constexpr (ABL & 2) break; __builtin_amdgcn_s_setprio(1); _Pragma("unroll") for (int m = 0; m < 4; ++m) _Pragma("unroll") for (int n = 0; n < 2; ++n) _Pragma("unroll") for (int k = 0; k < 2; ++k) \
;         acc[ai][bj][m][n] = __builtin_amdgcn_mfma_f32_16x16x32_f16(Bt[n][k], At[m][k], acc[ai][bj][m][n], 0, 0, 0); __builtin_amdgcn_s_setprio(0); } while (0)
; #define PG8_WAIT_V(n) asm volatile("s_waitcnt vmcnt(" #n ")" ::: "memory")
;     ...
;             PG8_LDB(B0, 0, 0); PG8_LDB(B1, 0, 1); PG8_SCHED; PG8_LDA(At, 0, 0); PG8_STAGE(PG8_SA(1, 1), a1 + hstep, voffA);
;             PG8_WAIT_V(8); PG8_WAIT_L(0); PG8_BAR; PG8_MMAF(0, 0, At, B0); PG8_MMAF(0, 1, At, B1); PG8_BAR; PG8_SCHED;
;             const bool fin = last && !has_next;
;             PG8_LDA(At, 0, 1); if (!fin) { PG8_STAGE(PG8_SB(0, 0), b2, voffB); PG8_STAGE(PG8_SB(0, 1), b2 + hstep, voffB); PG8_STAGE(PG8_SA(0, 0), a2, voffA); }
;             if (!fin) PG8_WAIT_V(8); else PG8_WAIT_V(2); PG8_WAIT_L(0); PG8_BAR; PG8_MMAF(1, 0, At, B0); PG8_MMAF(1, 1, At, B1); PG8_BAR; PG8_SCHED;
;             PG8_LDB(B0, 1, 0); PG8_LDB(B1, 1, 1); PG8_SCHED; PG8_LDA(At, 1, 0); if (!fin) PG8_STAGE(PG8_SA(0, 1), a2 + hstep, voffA);
;             if (!fin) PG8_WAIT_V(8); else PG8_WAIT_V(0); PG8_WAIT_L(0); PG8_BAR; PG8_MMA(0, 0, At, B0); PG8_MMA(0, 1, At, B1); PG8_BAR; PG8_SCHED;
;             PG8_LDA(At, 1, 1); if (!fin) { PG8_STAGE(PG8_SB(1, 0), b3, voffB); PG8_STAGE(PG8_SB(1, 1), b3 + hstep, voffB); PG8_STAGE(PG8_SA(1, 0), a3, voffA); }
;             if (!fin) PG8_WAIT_V(8); PG8_WAIT_L(0); PG8_BAR; PG8_MMA(1, 0, At, B0); PG8_MMA(1, 1, At, B1); PG8_BAR; PG8_SCHED;
.LBB0_988:
	s_waitcnt lgkmcnt(0)
	s_barrier
	v_mfma_f32_16x16x32_f16 v[62:65], v[166:169], v[186:189], v[62:65]
	s_setprio 1
	v_mfma_f32_16x16x32_f16 v[62:65], v[170:173], v[190:193], v[62:65]
	v_mfma_f32_16x16x32_f16 v[58:61], v[162:165], v[190:193], v[58:61]
	v_mfma_f32_16x16x32_f16 v[58:61], v[158:161], v[186:189], v[58:61]
	v_mfma_f32_16x16x32_f16 v[42:45], v[158:161], v[178:181], v[42:45]
	v_mfma_f32_16x16x32_f16 v[42:45], v[162:165], v[182:185], v[42:45]
	v_mfma_f32_16x16x32_f16 v[46:49], v[170:173], v[182:185], v[46:49]
	v_mfma_f32_16x16x32_f16 v[46:49], v[166:169], v[178:181], v[46:49]
	v_mfma_f32_16x16x32_f16 v[30:33], v[166:169], v[138:141], v[30:33]
	v_mfma_f32_16x16x32_f16 v[30:33], v[170:173], v[174:177], v[30:33]
	v_mfma_f32_16x16x32_f16 v[26:29], v[162:165], v[174:177], v[26:29]
	v_mfma_f32_16x16x32_f16 v[26:29], v[158:161], v[138:141], v[26:29]
	v_mfma_f32_16x16x32_f16 v[10:13], v[158:161], v[114:117], v[10:13]
	v_mfma_f32_16x16x32_f16 v[10:13], v[162:165], v[126:129], v[10:13]
	v_mfma_f32_16x16x32_f16 v[14:17], v[170:173], v[126:129], v[14:17]
	v_mfma_f32_16x16x32_f16 v[14:17], v[166:169], v[114:117], v[14:17]
	v_mfma_f32_16x16x32_f16 v[6:9], v[90:93], v[114:117], v[6:9]
	v_mfma_f32_16x16x32_f16 v[6:9], v[102:105], v[126:129], v[6:9]
	v_mfma_f32_16x16x32_f16 v[54:57], v[102:105], v[190:193], v[54:57]
	v_mfma_f32_16x16x32_f16 v[54:57], v[90:93], v[186:189], v[54:57]
	v_mfma_f32_16x16x32_f16 v[50:53], v[66:69], v[186:189], v[50:53]
	v_mfma_f32_16x16x32_f16 v[50:53], v[78:81], v[190:193], v[50:53]
	v_mfma_f32_16x16x32_f16 v[34:37], v[78:81], v[182:185], v[34:37]
	v_mfma_f32_16x16x32_f16 v[34:37], v[66:69], v[178:181], v[34:37]
	v_mfma_f32_16x16x32_f16 v[38:41], v[90:93], v[178:181], v[38:41]
	v_mfma_f32_16x16x32_f16 v[38:41], v[102:105], v[182:185], v[38:41]
	v_mfma_f32_16x16x32_f16 v[22:25], v[102:105], v[174:177], v[22:25]
	v_mfma_f32_16x16x32_f16 v[22:25], v[90:93], v[138:141], v[22:25]
	v_mfma_f32_16x16x32_f16 v[18:21], v[66:69], v[138:141], v[18:21]
	v_mfma_f32_16x16x32_f16 v[18:21], v[78:81], v[174:177], v[18:21]
	v_mfma_f32_16x16x32_f16 v[2:5], v[78:81], v[126:129], v[2:5]
	v_mfma_f32_16x16x32_f16 v[2:5], v[66:69], v[114:117], v[2:5]
	s_barrier
	s_setprio 0
	s_add_i32 s54, s54, 2
	s_add_u32 s52, s52, 0x100
	s_addc_u32 s53, s53, 0
	s_cmp_gt_u32 s54, 41
	s_cbranch_scc1 .LBB0_999
.LBB0_989:
	ds_read_b128 v[158:161], v213
	ds_read_b128 v[162:165], v213 offset:1024
	ds_read_b128 v[166:169], v213 offset:2048
	ds_read_b128 v[170:173], v213 offset:3072
	ds_read_b128 v[66:69], v214
	ds_read_b128 v[78:81], v214 offset:1024
	ds_read_b128 v[90:93], v214 offset:2048
	ds_read_b128 v[102:105], v214 offset:3072
	s_mov_b64 s[6:7], s[50:51]
	s_add_u32 s50, s6, 0x100
	s_addc_u32 s51, s7, 0
	s_cmp_eq_u32 s54, 40
	s_cselect_b64 s[26:27], -1, 0
	s_and_b64 s[8:9], s[26:27], exec
	s_cselect_b32 s25, s47, s51
	s_cselect_b32 s24, s46, s50
	s_cselect_b32 s9, s49, s53
	s_cselect_b32 s8, s48, s52
	ds_read_b128 v[174:177], v215
	ds_read_b128 v[178:181], v215 offset:1024
	ds_read_b128 v[182:185], v215 offset:2048
	ds_read_b128 v[186:189], v215 offset:3072
	ds_read_b128 v[190:193], v215 offset:4096
	ds_read_b128 v[194:197], v215 offset:5120
	ds_read_b128 v[198:201], v215 offset:6144
	ds_read_b128 v[202:205], v215 offset:7168
	s_add_u32 s6, s6, 0xb0080
	s_addc_u32 s7, s7, 0
	s_add_u32 m0, s28, 0xc000
	s_nop 0
	global_load_lds_dwordx4 v1, s[6:7]
	s_nop 0
	s_add_u32 m0, s28, 0xe000
	s_nop 0
	global_load_lds_dwordx4 v211, s[6:7]
	s_waitcnt vmcnt(8)
	s_waitcnt lgkmcnt(0)
	s_barrier
	v_mfma_f32_16x16x32_f16 v[114:117], v[158:161], v[174:177], v[154:157]
	s_setprio 1
	v_mfma_f32_16x16x32_f16 v[114:117], v[162:165], v[178:181], v[114:117]
	v_mfma_f32_16x16x32_f16 v[126:129], v[170:173], v[178:181], v[150:153]
	v_mfma_f32_16x16x32_f16 v[126:129], v[166:169], v[174:177], v[126:129]
	v_mfma_f32_16x16x32_f16 v[130:133], v[166:169], v[182:185], v[130:133]
	v_mfma_f32_16x16x32_f16 v[130:133], v[170:173], v[186:189], v[130:133]
	v_mfma_f32_16x16x32_f16 v[134:137], v[162:165], v[186:189], v[134:137]
	v_mfma_f32_16x16x32_f16 v[134:137], v[158:161], v[182:185], v[134:137]
	v_mfma_f32_16x16x32_f16 v[110:113], v[158:161], v[190:193], v[110:113]
	v_mfma_f32_16x16x32_f16 v[110:113], v[162:165], v[194:197], v[110:113]
	v_mfma_f32_16x16x32_f16 v[106:109], v[170:173], v[194:197], v[106:109]
	v_mfma_f32_16x16x32_f16 v[106:109], v[166:169], v[190:193], v[106:109]
	v_mfma_f32_16x16x32_f16 v[82:85], v[166:169], v[198:201], v[82:85]
	v_mfma_f32_16x16x32_f16 v[82:85], v[170:173], v[202:205], v[82:85]
	v_mfma_f32_16x16x32_f16 v[86:89], v[162:165], v[202:205], v[86:89]
	v_mfma_f32_16x16x32_f16 v[86:89], v[158:161], v[198:201], v[86:89]
	v_mfma_f32_16x16x32_f16 v[74:77], v[66:69], v[198:201], v[74:77]
	v_mfma_f32_16x16x32_f16 v[74:77], v[78:81], v[202:205], v[74:77]
	v_mfma_f32_16x16x32_f16 v[138:141], v[78:81], v[178:181], v[146:149]
	v_mfma_f32_16x16x32_f16 v[138:141], v[66:69], v[174:177], v[138:141]
	v_mfma_f32_16x16x32_f16 v[142:145], v[90:93], v[174:177], v[142:145]
	v_mfma_f32_16x16x32_f16 v[142:145], v[102:105], v[178:181], v[142:145]
	v_mfma_f32_16x16x32_f16 v[118:121], v[102:105], v[186:189], v[118:121]
	v_mfma_f32_16x16x32_f16 v[118:121], v[90:93], v[182:185], v[118:121]
	v_mfma_f32_16x16x32_f16 v[122:125], v[66:69], v[182:185], v[122:125]
	v_mfma_f32_16x16x32_f16 v[122:125], v[78:81], v[186:189], v[122:125]
	v_mfma_f32_16x16x32_f16 v[98:101], v[78:81], v[194:197], v[98:101]
	v_mfma_f32_16x16x32_f16 v[98:101], v[66:69], v[190:193], v[98:101]
	v_mfma_f32_16x16x32_f16 v[94:97], v[90:93], v[190:193], v[94:97]
	v_mfma_f32_16x16x32_f16 v[94:97], v[102:105], v[194:197], v[94:97]
	v_mfma_f32_16x16x32_f16 v[70:73], v[102:105], v[202:205], v[70:73]
	v_mfma_f32_16x16x32_f16 v[70:73], v[90:93], v[198:201], v[70:73]
	s_barrier
	s_setprio 0
	ds_read_b128 v[186:189], v215 offset:16384
	ds_read_b128 v[190:193], v215 offset:17408
	ds_read_b128 v[178:181], v215 offset:18432
	ds_read_b128 v[182:185], v215 offset:19456
	ds_read_b128 v[154:157], v215 offset:20480
	ds_read_b128 v[174:177], v215 offset:21504
	ds_read_b128 v[146:149], v215 offset:22528
	ds_read_b128 v[150:153], v215 offset:23552
	s_and_b64 s[6:7], s[4:5], s[26:27]
	s_mov_b64 s[26:27], -1
	s_and_b64 vcc, exec, s[6:7]
	s_cbranch_vccnz .LBB0_991
	s_add_u32 m0, s28, 0x10000
	s_nop 0
	global_load_lds_dwordx4 v210, s[8:9]
	s_nop 0
	s_add_u32 m0, s28, 0x12000
	s_nop 0
	global_load_lds_dwordx4 v212, s[8:9]
	s_add_u32 s26, s8, 0xb0000
	s_addc_u32 s27, s9, 0
	s_add_u32 m0, s28, 0x14000
	s_nop 0
	global_load_lds_dwordx4 v210, s[26:27]
	s_nop 0
	s_add_u32 m0, s28, 0x16000
	s_nop 0
	global_load_lds_dwordx4 v212, s[26:27]
	s_mov_b64 s[26:27], 0
	s_add_u32 m0, s28, 0
	s_nop 0
	global_load_lds_dwordx4 v1, s[24:25]
	s_nop 0
	s_add_u32 m0, s28, 0x2000
	s_nop 0
	global_load_lds_dwordx4 v211, s[24:25]
	s_waitcnt vmcnt(8)

; #define PG8_STAGE(bufoff, gbase, voff) do { if constexpr (ABL & 1) break; glds16s<(bufoff)>((voff)[0], (const void*)(gbase), ldsbw); glds16s<(bufoff) + 8192>((voff)[1], (const void*)(gbase), ldsbw); } while (0)
; #define PG8_LDA(dst, b, h) do { if constexpr (ABL & 4) break; _Pragma("unroll") for (int m = 0; m < 4; ++m) _Pragma("unroll") for (int k = 0; k < 2; ++k) dst[m][k] = *(const LAS f16x8*)(lds + PG8_SA(b, h) + aoff + m * 2048 + k * 1024); } while (0)
; #define PG8_LDB(dst, b, h) do { if constexpr (ABL & 4) break; _Pragma("unroll") for (int n = 0; n < 2; ++n) _Pragma("unroll") for (int k = 0; k < 2; ++k) dst[n][k] = *(const LAS f16x8*)(lds + PG8_SB(b, h) + boff + n * 2048 + k * 1024); } while (0)
; #define PG8_MMA(ai, bj, At, Bt) do { if constexpr (ABL & 2) break; __builtin_amdgcn_s_setprio(1); _Pragma("unroll") for (int m = 0; m < 4; ++m) _Pragma("unroll") for (int n = 0; n < 2; ++n) _Pragma("unroll") for (int k = 0; k < 2; ++k) \
;         acc[ai][bj][m][n] = __builtin_amdgcn_mfma_f32_16x16x32_f16(Bt[n][k], At[m][k], acc[ai][bj][m][n], 0, 0, 0); __builtin_amdgcn_s_setprio(0); } while (0)
; #define PG8_MMAF(ai, bj, At, Bt) do { if (t == 0) PG8_MMA0(ai, bj, At, Bt); else PG8_MMA(ai, bj, At, Bt); } while (0)
; #define PG8_WAIT_V(n) asm volatile("s_waitcnt vmcnt(" #n ")" ::: "memory")
; #define PG8_WAIT_L(n) asm volatile("s_waitcnt lgkmcnt(" #n ")" ::: "memory")
; #define PG8_BAR __builtin_amdgcn_s_barrier()
; #define PG8_SCHED __builtin_amdgcn_sched_barrier(0)
;     ...
;             if (!fin) PG8_WAIT_V(8); else PG8_WAIT_V(2); PG8_WAIT_L(0); PG8_BAR; PG8_MMAF(1, 0, At, B0); PG8_MMAF(1, 1, At, B1); PG8_BAR; PG8_SCHED;
;             PG8_LDB(B0, 1, 0); PG8_LDB(B1, 1, 1); PG8_SCHED; PG8_LDA(At, 1, 0); if (!fin) PG8_STAGE(PG8_SA(0, 1), a2 + hstep, voffA);
;             if (!fin) PG8_WAIT_V(8); else PG8_WAIT_V(0); PG8_WAIT_L(0); PG8_BAR; PG8_MMA(0, 0, At, B0); PG8_MMA(0, 1, At, B1); PG8_BAR; PG8_SCHED;
.LBB0_993:
	s_waitcnt lgkmcnt(0)
	s_xor_b64 s[26:27], s[6:7], -1
	s_barrier
	v_mfma_f32_16x16x32_f16 v[62:65], v[158:161], v[186:189], v[62:65]
	s_setprio 1
	v_mfma_f32_16x16x32_f16 v[62:65], v[162:165], v[190:193], v[62:65]
	v_mfma_f32_16x16x32_f16 v[58:61], v[170:173], v[190:193], v[58:61]
	v_mfma_f32_16x16x32_f16 v[58:61], v[166:169], v[186:189], v[58:61]
	v_mfma_f32_16x16x32_f16 v[42:45], v[166:169], v[178:181], v[42:45]
	v_mfma_f32_16x16x32_f16 v[42:45], v[170:173], v[182:185], v[42:45]
	v_mfma_f32_16x16x32_f16 v[46:49], v[162:165], v[182:185], v[46:49]
	v_mfma_f32_16x16x32_f16 v[46:49], v[158:161], v[178:181], v[46:49]
	v_mfma_f32_16x16x32_f16 v[30:33], v[158:161], v[154:157], v[30:33]
	v_mfma_f32_16x16x32_f16 v[30:33], v[162:165], v[174:177], v[30:33]
	v_mfma_f32_16x16x32_f16 v[26:29], v[170:173], v[174:177], v[26:29]
	v_mfma_f32_16x16x32_f16 v[26:29], v[166:169], v[154:157], v[26:29]
	v_mfma_f32_16x16x32_f16 v[10:13], v[166:169], v[146:149], v[10:13]
	v_mfma_f32_16x16x32_f16 v[10:13], v[170:173], v[150:153], v[10:13]
	v_mfma_f32_16x16x32_f16 v[14:17], v[162:165], v[150:153], v[14:17]
	v_mfma_f32_16x16x32_f16 v[14:17], v[158:161], v[146:149], v[14:17]
	v_mfma_f32_16x16x32_f16 v[6:9], v[66:69], v[146:149], v[6:9]
	v_mfma_f32_16x16x32_f16 v[6:9], v[78:81], v[150:153], v[6:9]
	v_mfma_f32_16x16x32_f16 v[54:57], v[78:81], v[190:193], v[54:57]
	v_mfma_f32_16x16x32_f16 v[54:57], v[66:69], v[186:189], v[54:57]
	v_mfma_f32_16x16x32_f16 v[50:53], v[90:93], v[186:189], v[50:53]
	v_mfma_f32_16x16x32_f16 v[50:53], v[102:105], v[190:193], v[50:53]
	v_mfma_f32_16x16x32_f16 v[34:37], v[102:105], v[182:185], v[34:37]
	v_mfma_f32_16x16x32_f16 v[34:37], v[90:93], v[178:181], v[34:37]
	v_mfma_f32_16x16x32_f16 v[38:41], v[66:69], v[178:181], v[38:41]
	v_mfma_f32_16x16x32_f16 v[38:41], v[78:81], v[182:185], v[38:41]
	v_mfma_f32_16x16x32_f16 v[22:25], v[78:81], v[174:177], v[22:25]
	v_mfma_f32_16x16x32_f16 v[22:25], v[66:69], v[154:157], v[22:25]
	v_mfma_f32_16x16x32_f16 v[18:21], v[90:93], v[154:157], v[18:21]
	v_mfma_f32_16x16x32_f16 v[18:21], v[102:105], v[174:177], v[18:21]
	v_mfma_f32_16x16x32_f16 v[2:5], v[102:105], v[150:153], v[2:5]
	v_mfma_f32_16x16x32_f16 v[2:5], v[90:93], v[146:149], v[2:5]
	s_barrier
	s_setprio 0
	ds_read_b128 v[166:169], v216
	ds_read_b128 v[170:173], v216 offset:1024
	ds_read_b128 v[158:161], v216 offset:2048
	ds_read_b128 v[162:165], v216 offset:3072
	ds_read_b128 v[90:93], v217
	ds_read_b128 v[102:105], v217 offset:1024
	ds_read_b128 v[66:69], v217 offset:2048
	ds_read_b128 v[78:81], v217 offset:3072
	ds_read_b128 v[198:201], v215 offset:32768
	ds_read_b128 v[202:205], v215 offset:33792
	ds_read_b128 v[190:193], v215 offset:34816
	ds_read_b128 v[194:197], v215 offset:35840
	ds_read_b128 v[182:185], v215 offset:36864
	ds_read_b128 v[186:189], v215 offset:37888
	ds_read_b128 v[174:177], v215 offset:38912
	ds_read_b128 v[178:181], v215 offset:39936
	v_cndmask_b32_e64 v146, 0, 1, s[26:27]
	v_cmp_ne_u32_e64 s[6:7], 1, v146
	s_andn2_b64 vcc, exec, s[26:27]
	s_mov_b64 s[26:27], -1
	s_cbranch_vccnz .LBB0_995
	s_add_u32 s26, s24, 0xb0000
	s_addc_u32 s27, s25, 0
	s_add_u32 m0, s28, 0x4000
	s_nop 0
	global_load_lds_dwordx4 v1, s[26:27]
	s_nop 0
	s_add_u32 m0, s28, 0x6000
	s_nop 0
	global_load_lds_dwordx4 v211, s[26:27]
	s_waitcnt vmcnt(8)
	s_mov_b64 s[26:27], 0

; #define PG8_STAGE(bufoff, gbase, voff) do { if constexpr (ABL & 1) break; glds16s<(bufoff)>((voff)[0], (const void*)(gbase), ldsbw); glds16s<(bufoff) + 8192>((voff)[1], (const void*)(gbase), ldsbw); } while (0)
; #define PG8_LDA(dst, b, h) do { if constexpr (ABL & 4) break; _Pragma("unroll") for (int m = 0; m < 4; ++m) _Pragma("unroll") for (int k = 0; k < 2; ++k) dst[m][k] = *(const LAS f16x8*)(lds + PG8_SA(b, h) + aoff + m * 2048 + k * 1024); } while (0)
; #define PG8_MMA(ai, bj, At, Bt) do { if constexpr (ABL & 2) break; __builtin_amdgcn_s_setprio(1); _Pragma("unroll") for (int m = 0; m < 4; ++m) _Pragma("unroll") for (int n = 0; n < 2; ++n) _Pragma("unroll") for (int k = 0; k < 2; ++k) \
;         acc[ai][bj][m][n] = __builtin_amdgcn_mfma_f32_16x16x32_f16(Bt[n][k], At[m][k], acc[ai][bj][m][n], 0, 0, 0); __builtin_amdgcn_s_setprio(0); } while (0)
; #define PG8_WAIT_V(n) asm volatile("s_waitcnt vmcnt(" #n ")" ::: "memory")
; #define PG8_WAIT_L(n) asm volatile("s_waitcnt lgkmcnt(" #n ")" ::: "memory")
; #define PG8_BAR __builtin_amdgcn_s_barrier()
; #define PG8_SCHED __builtin_amdgcn_sched_barrier(0)
;     ...
;             if (!fin) PG8_WAIT_V(8); else PG8_WAIT_V(0); PG8_WAIT_L(0); PG8_BAR; PG8_MMA(0, 0, At, B0); PG8_MMA(0, 1, At, B1); PG8_BAR; PG8_SCHED;
;             PG8_LDA(At, 1, 1); if (!fin) { PG8_STAGE(PG8_SB(1, 0), b3, voffB); PG8_STAGE(PG8_SB(1, 1), b3 + hstep, voffB); PG8_STAGE(PG8_SA(1, 0), a3, voffA); }
.LBB0_997:
	s_waitcnt lgkmcnt(0)
	s_barrier
	v_mfma_f32_16x16x32_f16 v[114:117], v[166:169], v[198:201], v[114:117]
	s_setprio 1
	v_mfma_f32_16x16x32_f16 v[154:157], v[170:173], v[202:205], v[114:117]
	v_mfma_f32_16x16x32_f16 v[114:117], v[162:165], v[202:205], v[126:129]
	v_mfma_f32_16x16x32_f16 v[150:153], v[158:161], v[198:201], v[114:117]
	v_mfma_f32_16x16x32_f16 v[106:109], v[158:161], v[182:185], v[106:109]
	v_mfma_f32_16x16x32_f16 v[106:109], v[162:165], v[186:189], v[106:109]
	v_mfma_f32_16x16x32_f16 v[110:113], v[170:173], v[186:189], v[110:113]
	v_mfma_f32_16x16x32_f16 v[110:113], v[166:169], v[182:185], v[110:113]
	v_mfma_f32_16x16x32_f16 v[114:117], v[166:169], v[190:193], v[134:137]
	v_mfma_f32_16x16x32_f16 v[134:137], v[170:173], v[194:197], v[114:117]
	v_mfma_f32_16x16x32_f16 v[114:117], v[162:165], v[194:197], v[130:133]
	v_mfma_f32_16x16x32_f16 v[130:133], v[158:161], v[190:193], v[114:117]
	v_mfma_f32_16x16x32_f16 v[82:85], v[158:161], v[174:177], v[82:85]
	v_mfma_f32_16x16x32_f16 v[82:85], v[162:165], v[178:181], v[82:85]
	v_mfma_f32_16x16x32_f16 v[86:89], v[170:173], v[178:181], v[86:89]
	v_mfma_f32_16x16x32_f16 v[86:89], v[166:169], v[174:177], v[86:89]
	v_mfma_f32_16x16x32_f16 v[74:77], v[90:93], v[174:177], v[74:77]
	v_mfma_f32_16x16x32_f16 v[74:77], v[102:105], v[178:181], v[74:77]
	v_mfma_f32_16x16x32_f16 v[114:117], v[102:105], v[202:205], v[138:141]
	v_mfma_f32_16x16x32_f16 v[146:149], v[90:93], v[198:201], v[114:117]
	v_mfma_f32_16x16x32_f16 v[114:117], v[66:69], v[198:201], v[142:145]
	v_mfma_f32_16x16x32_f16 v[142:145], v[78:81], v[202:205], v[114:117]
	v_mfma_f32_16x16x32_f16 v[94:97], v[78:81], v[186:189], v[94:97]
	v_mfma_f32_16x16x32_f16 v[94:97], v[66:69], v[182:185], v[94:97]
	v_mfma_f32_16x16x32_f16 v[98:101], v[90:93], v[182:185], v[98:101]
	v_mfma_f32_16x16x32_f16 v[98:101], v[102:105], v[186:189], v[98:101]
	v_mfma_f32_16x16x32_f16 v[114:117], v[102:105], v[194:197], v[122:125]
	v_mfma_f32_16x16x32_f16 v[122:125], v[90:93], v[190:193], v[114:117]
	v_mfma_f32_16x16x32_f16 v[114:117], v[66:69], v[190:193], v[118:121]
	v_mfma_f32_16x16x32_f16 v[118:121], v[78:81], v[194:197], v[114:117]
	v_mfma_f32_16x16x32_f16 v[70:73], v[78:81], v[178:181], v[70:73]
	v_mfma_f32_16x16x32_f16 v[70:73], v[66:69], v[174:177], v[70:73]
	s_barrier
	s_setprio 0
	ds_read_b128 v[186:189], v215 offset:49152
	ds_read_b128 v[190:193], v215 offset:50176
	ds_read_b128 v[178:181], v215 offset:51200
	ds_read_b128 v[182:185], v215 offset:52224
	ds_read_b128 v[138:141], v215 offset:53248
	ds_read_b128 v[174:177], v215 offset:54272
	ds_read_b128 v[114:117], v215 offset:55296
	ds_read_b128 v[126:129], v215 offset:56320
	s_and_b64 vcc, exec, s[6:7]
	s_cbranch_vccnz .LBB0_988
	s_add_u32 s6, s24, 0x80
	s_addc_u32 s7, s25, 0
	s_add_u32 s24, s8, 0x80
	s_addc_u32 s25, s9, 0
	s_add_u32 m0, s28, 0x18000
	s_nop 0
	global_load_lds_dwordx4 v210, s[24:25]
	s_nop 0
	s_add_u32 m0, s28, 0x1a000
	s_nop 0
	global_load_lds_dwordx4 v212, s[24:25]
	s_add_u32 s8, s8, 0xb0080
	s_addc_u32 s9, s9, 0
	s_add_u32 m0, s28, 0x1c000
	s_nop 0
	global_load_lds_dwordx4 v210, s[8:9]
	s_nop 0
	s_add_u32 m0, s28, 0x1e000
	s_nop 0
	global_load_lds_dwordx4 v212, s[8:9]
	s_nop 0
	s_add_u32 m0, s28, 0x8000
	s_nop 0
	global_load_lds_dwordx4 v1, s[6:7]
	s_nop 0
	s_add_u32 m0, s28, 0xa000
	s_nop 0
	global_load_lds_dwordx4 v211, s[6:7]
	s_waitcnt vmcnt(8)
	s_branch .LBB0_988

;     __device__ __forceinline__ bool next(int i, Unit& u) const { if (i >= count) return false; const int L = first + i; u.pm = L / nN; u.pn = L % nN; return true; }
; #define PG8_STAGE(bufoff, gbase, voff) do { if constexpr (ABL & 1) break; glds16s<(bufoff)>((voff)[0], (const void*)(gbase), ldsbw); glds16s<(bufoff) + 8192>((voff)[1], (const void*)(gbase), ldsbw); } while (0)
; #define PG8_LDA(dst, b, h) do { if constexpr (ABL & 4) break; _Pragma("unroll") for (int m = 0; m < 4; ++m) _Pragma("unroll") for (int k = 0; k < 2; ++k) dst[m][k] = *(const LAS f16x8*)(lds + PG8_SA(b, h) + aoff + m * 2048 + k * 1024); } while (0)
; #define PG8_LDB(dst, b, h) do { if constexpr (ABL & 4) break; _Pragma("unroll") for (int n = 0; n < 2; ++n) _Pragma("unroll") for (int k = 0; k < 2; ++k) dst[n][k] = *(const LAS f16x8*)(lds + PG8_SB(b, h) + boff + n * 2048 + k * 1024); } while (0)
; #define PG8_MMAF(ai, bj, At, Bt) do { if (t == 0) PG8_MMA0(ai, bj, At, Bt); else PG8_MMA(ai, bj, At, Bt); } while (0)
; #define PG8_WAIT_V(n) asm volatile("s_waitcnt vmcnt(" #n ")" ::: "memory")
; #define PG8_BAR __builtin_amdgcn_s_barrier()
;     ...
;         const bool has_next = S.next(ui + 1, nxt);
;         const char* nA = has_next ? (const char*)g.A + (size_t)nxt.pm * tstep : cA; const char* nB = has_next ? (const char*)g.Bt + (size_t)nxt.pn * tstep : cB;
;         for (int t = 0; t < nt; t += 2) {
;             const bool last = (t == nt - 2);
;             const char* a1 = cA + (size_t)(t + 1) * kstep;
;             const char* a2 = last ? nA : cA + (size_t)(t + 2) * kstep; const char* b2 = last ? nB : cB + (size_t)(t + 2) * kstep;
;             const char* a3 = a2 + kstep; const char* b3 = b2 + kstep;
;             if (last && has_next) S.a_ready(nxt);
;             if constexpr (SP2) {
;             PG8_LDB(B0, 0, 0); PG8_LDB(B1, 0, 1); PG8_SCHED; PG8_LDA(At, 0, 0); PG8_STAGE(PG8_SA(1, 1), a1 + hstep, voffA);
;             PG8_WAIT_V(8); PG8_WAIT_L(0); PG8_BAR; PG8_MMAF(0, 0, At, B0); PG8_MMAF(0, 1, At, B1); PG8_BAR; PG8_SCHED;
;             const bool fin = last && !has_next;
;             PG8_LDA(At, 0, 1); if (!fin) { PG8_STAGE(PG8_SB(0, 0), b2, voffB); PG8_STAGE(PG8_SB(0, 1), b2 + hstep, voffB); PG8_STAGE(PG8_SA(0, 0), a2, voffA); }
;             if (!fin) PG8_WAIT_V(8); else PG8_WAIT_V(2); PG8_WAIT_L(0); PG8_BAR; PG8_MMAF(1, 0, At, B0); PG8_MMAF(1, 1, At, B1); PG8_BAR; PG8_SCHED;
.LBB0_1111:
	s_ashr_i32 s43, s42, 31
	s_lshl_b64 s[8:9], s[42:43], 19
	s_add_u32 s44, s74, s8
	s_addc_u32 s45, s75, s9
	s_and_b64 s[8:9], exec, s[4:5]
	s_waitcnt lgkmcnt(0)
	ds_read_b128 v[2:5], v201
	ds_read_b128 v[6:9], v201 offset:1024
	ds_read_b128 v[10:13], v201 offset:2048
	ds_read_b128 v[14:17], v201 offset:3072
	ds_read_b128 v[18:21], v202
	ds_read_b128 v[22:25], v202 offset:1024
	ds_read_b128 v[26:29], v202 offset:2048
	ds_read_b128 v[30:33], v202 offset:3072
	s_cselect_b32 s43, s55, s45
	s_cselect_b32 s56, s54, s44
	s_ashr_i32 s41, s40, 31
	s_lshl_b64 s[8:9], s[40:41], 19
	s_add_u32 s46, s94, s8
	s_addc_u32 s47, s95, s9
	s_and_b64 s[8:9], exec, s[4:5]
	s_cselect_b32 s41, s7, s47
	s_cselect_b32 s57, s6, s46
	s_add_u32 s52, s54, 0x100
	s_addc_u32 s53, s55, 0
	s_add_u32 s26, s6, 0x100
	s_addc_u32 s27, s7, 0
	s_add_u32 s8, s54, 0x180
	s_addc_u32 s9, s55, 0
	ds_read_b128 v[34:37], v203
	ds_read_b128 v[38:41], v203 offset:1024
	ds_read_b128 v[42:45], v203 offset:2048
	ds_read_b128 v[46:49], v203 offset:3072
	ds_read_b128 v[50:53], v203 offset:4096
	ds_read_b128 v[54:57], v203 offset:5120
	ds_read_b128 v[58:61], v203 offset:6144
	ds_read_b128 v[62:65], v203 offset:7168
	s_add_u32 s24, s6, 0x180
	s_addc_u32 s25, s7, 0
	s_add_u32 s58, s54, 0x40080
	s_addc_u32 s59, s55, 0
	s_add_u32 m0, s28, 0xc000
	s_nop 0
	global_load_lds_dwordx4 v1, s[58:59]
	s_nop 0
	s_add_u32 m0, s28, 0xe000
	s_nop 0
	global_load_lds_dwordx4 v199, s[58:59]
	s_waitcnt vmcnt(8)
	s_waitcnt lgkmcnt(0)
	s_barrier
	v_mfma_f32_16x16x32_f16 v[90:93], v[2:5], v[58:61], 0
	s_setprio 1
	v_mfma_f32_16x16x32_f16 v[98:101], v[6:9], v[62:65], v[90:93]
	v_mfma_f32_16x16x32_f16 v[66:69], v[2:5], v[34:37], 0
	v_mfma_f32_16x16x32_f16 v[66:69], v[6:9], v[38:41], v[66:69]
	v_mfma_f32_16x16x32_f16 v[70:73], v[10:13], v[34:37], 0
	v_mfma_f32_16x16x32_f16 v[70:73], v[14:17], v[38:41], v[70:73]
	v_mfma_f32_16x16x32_f16 v[74:77], v[2:5], v[42:45], 0
	v_mfma_f32_16x16x32_f16 v[74:77], v[6:9], v[46:49], v[74:77]
	v_mfma_f32_16x16x32_f16 v[78:81], v[10:13], v[42:45], 0
	v_mfma_f32_16x16x32_f16 v[78:81], v[14:17], v[46:49], v[78:81]
	v_mfma_f32_16x16x32_f16 v[82:85], v[2:5], v[50:53], 0
	v_mfma_f32_16x16x32_f16 v[82:85], v[6:9], v[54:57], v[82:85]
	v_mfma_f32_16x16x32_f16 v[86:89], v[10:13], v[50:53], 0
	v_mfma_f32_16x16x32_f16 v[86:89], v[14:17], v[54:57], v[86:89]
	v_mfma_f32_16x16x32_f16 v[90:93], v[10:13], v[58:61], 0
	v_mfma_f32_16x16x32_f16 v[102:105], v[14:17], v[62:65], v[90:93]
	v_mfma_f32_16x16x32_f16 v[90:93], v[18:21], v[34:37], 0
	v_mfma_f32_16x16x32_f16 v[114:117], v[22:25], v[38:41], v[90:93]
	v_mfma_f32_16x16x32_f16 v[34:37], v[26:29], v[34:37], 0
	v_mfma_f32_16x16x32_f16 v[34:37], v[30:33], v[38:41], v[34:37]
	v_mfma_f32_16x16x32_f16 v[38:41], v[18:21], v[42:45], 0
	v_mfma_f32_16x16x32_f16 v[38:41], v[22:25], v[46:49], v[38:41]
	v_mfma_f32_16x16x32_f16 v[42:45], v[26:29], v[42:45], 0
	v_mfma_f32_16x16x32_f16 v[42:45], v[30:33], v[46:49], v[42:45]
	v_mfma_f32_16x16x32_f16 v[46:49], v[18:21], v[50:53], 0
	v_mfma_f32_16x16x32_f16 v[46:49], v[22:25], v[54:57], v[46:49]
	v_mfma_f32_16x16x32_f16 v[50:53], v[26:29], v[50:53], 0
	v_mfma_f32_16x16x32_f16 v[50:53], v[30:33], v[54:57], v[50:53]
	v_mfma_f32_16x16x32_f16 v[54:57], v[18:21], v[58:61], 0
	v_mfma_f32_16x16x32_f16 v[54:57], v[22:25], v[62:65], v[54:57]
	v_mfma_f32_16x16x32_f16 v[58:61], v[26:29], v[58:61], 0
	v_mfma_f32_16x16x32_f16 v[58:61], v[30:33], v[62:65], v[58:61]
	s_barrier
	s_setprio 0
	ds_read_b128 v[62:65], v203 offset:16384
	ds_read_b128 v[90:93], v203 offset:17408
	ds_read_b128 v[94:97], v203 offset:18432
	ds_read_b128 v[106:109], v203 offset:19456
	ds_read_b128 v[110:113], v203 offset:20480
	ds_read_b128 v[118:121], v203 offset:21504
	ds_read_b128 v[122:125], v203 offset:22528
	ds_read_b128 v[126:129], v203 offset:23552
	s_add_u32 m0, s28, 0x10000
	s_nop 0
	global_load_lds_dwordx4 v198, s[26:27]
	s_nop 0
	s_add_u32 m0, s28, 0x12000
	s_nop 0
	global_load_lds_dwordx4 v200, s[26:27]
	s_add_u32 s26, s6, 0x40100
	s_addc_u32 s27, s7, 0
	s_add_u32 m0, s28, 0x14000
	s_nop 0
	global_load_lds_dwordx4 v198, s[26:27]
	s_nop 0
	s_add_u32 m0, s28, 0x16000
	s_nop 0
	global_load_lds_dwordx4 v200, s[26:27]
	s_nop 0
	s_add_u32 m0, s28, 0
	s_nop 0
	global_load_lds_dwordx4 v1, s[52:53]
	s_nop 0
	s_add_u32 m0, s28, 0x2000
	s_nop 0
	global_load_lds_dwordx4 v199, s[52:53]
	s_waitcnt vmcnt(8)
	s_waitcnt lgkmcnt(0)
	s_barrier
	v_mfma_f32_16x16x32_f16 v[130:133], v[2:5], v[62:65], 0
	s_setprio 1
	v_mfma_f32_16x16x32_f16 v[130:133], v[6:9], v[90:93], v[130:133]
	v_mfma_f32_16x16x32_f16 v[138:141], v[2:5], v[94:97], 0
	v_mfma_f32_16x16x32_f16 v[138:141], v[6:9], v[106:109], v[138:141]
	v_mfma_f32_16x16x32_f16 v[146:149], v[2:5], v[110:113], 0
	v_mfma_f32_16x16x32_f16 v[146:149], v[6:9], v[118:121], v[146:149]
	v_mfma_f32_16x16x32_f16 v[2:5], v[2:5], v[122:125], 0
	v_mfma_f32_16x16x32_f16 v[2:5], v[6:9], v[126:129], v[2:5]
	v_mfma_f32_16x16x32_f16 v[6:9], v[10:13], v[122:125], 0
	v_mfma_f32_16x16x32_f16 v[6:9], v[14:17], v[126:129], v[6:9]
	v_mfma_f32_16x16x32_f16 v[134:137], v[10:13], v[62:65], 0
	v_mfma_f32_16x16x32_f16 v[134:137], v[14:17], v[90:93], v[134:137]
	v_mfma_f32_16x16x32_f16 v[142:145], v[10:13], v[94:97], 0
	v_mfma_f32_16x16x32_f16 v[142:145], v[14:17], v[106:109], v[142:145]
	v_mfma_f32_16x16x32_f16 v[150:153], v[10:13], v[110:113], 0
	v_mfma_f32_16x16x32_f16 v[150:153], v[14:17], v[118:121], v[150:153]
	v_mfma_f32_16x16x32_f16 v[10:13], v[18:21], v[62:65], 0
	v_mfma_f32_16x16x32_f16 v[154:157], v[22:25], v[90:93], v[10:13]
	v_mfma_f32_16x16x32_f16 v[10:13], v[26:29], v[62:65], 0
	v_mfma_f32_16x16x32_f16 v[158:161], v[30:33], v[90:93], v[10:13]
	v_mfma_f32_16x16x32_f16 v[10:13], v[18:21], v[94:97], 0
	v_mfma_f32_16x16x32_f16 v[162:165], v[22:25], v[106:109], v[10:13]
	v_mfma_f32_16x16x32_f16 v[10:13], v[26:29], v[94:97], 0
	v_mfma_f32_16x16x32_f16 v[166:169], v[30:33], v[106:109], v[10:13]
	v_mfma_f32_16x16x32_f16 v[10:13], v[18:21], v[110:113], 0
	v_mfma_f32_16x16x32_f16 v[170:173], v[22:25], v[118:121], v[10:13]
	v_mfma_f32_16x16x32_f16 v[10:13], v[26:29], v[110:113], 0
	v_mfma_f32_16x16x32_f16 v[174:177], v[30:33], v[118:121], v[10:13]
	v_mfma_f32_16x16x32_f16 v[10:13], v[18:21], v[122:125], 0
	v_mfma_f32_16x16x32_f16 v[178:181], v[22:25], v[126:129], v[10:13]
	v_mfma_f32_16x16x32_f16 v[10:13], v[26:29], v[122:125], 0
	v_mfma_f32_16x16x32_f16 v[182:185], v[30:33], v[126:129], v[10:13]
	s_barrier
; #define PG8_STAGE(bufoff, gbase, voff) do { if constexpr (ABL & 1) break; glds16s<(bufoff)>((voff)[0], (const void*)(gbase), ldsbw); glds16s<(bufoff) + 8192>((voff)[1], (const void*)(gbase), ldsbw); } while (0)
; #define PG8_LDA(dst, b, h) do { if constexpr (ABL & 4) break; _Pragma("unroll") for (int m = 0; m < 4; ++m) _Pragma("unroll") for (int k = 0; k < 2; ++k) dst[m][k] = *(const LAS f16x8*)(lds + PG8_SA(b, h) + aoff + m * 2048 + k * 1024); } while (0)
; #define PG8_LDB(dst, b, h) do { if constexpr (ABL & 4) break; _Pragma("unroll") for (int n = 0; n < 2; ++n) _Pragma("unroll") for (int k = 0; k < 2; ++k) dst[n][k] = *(const LAS f16x8*)(lds + PG8_SB(b, h) + boff + n * 2048 + k * 1024); } while (0)
; #define PG8_MMA(ai, bj, At, Bt) do { if constexpr (ABL & 2) break; __builtin_amdgcn_s_setprio(1); _Pragma("unroll") for (int m = 0; m < 4; ++m) _Pragma("unroll") for (int n = 0; n < 2; ++n) _Pragma("unroll") for (int k = 0; k < 2; ++k) \
;         acc[ai][bj][m][n] = __builtin_amdgcn_mfma_f32_16x16x32_f16(Bt[n][k], At[m][k], acc[ai][bj][m][n], 0, 0, 0); __builtin_amdgcn_s_setprio(0); } while (0)
; #define PG8_WAIT_V(n) asm volatile("s_waitcnt vmcnt(" #n ")" ::: "memory")
; #define PG8_WAIT_L(n) asm volatile("s_waitcnt lgkmcnt(" #n ")" ::: "memory")
; #define PG8_BAR __builtin_amdgcn_s_barrier()
; #define PG8_SCHED __builtin_amdgcn_sched_barrier(0)
;     ...
;             PG8_LDB(B0, 1, 0); PG8_LDB(B1, 1, 1); PG8_SCHED; PG8_LDA(At, 1, 0); if (!fin) PG8_STAGE(PG8_SA(0, 1), a2 + hstep, voffA);
;             if (!fin) PG8_WAIT_V(8); else PG8_WAIT_V(0); PG8_WAIT_L(0); PG8_BAR; PG8_MMA(0, 0, At, B0); PG8_MMA(0, 1, At, B1); PG8_BAR; PG8_SCHED;
;             PG8_LDA(At, 1, 1); if (!fin) { PG8_STAGE(PG8_SB(1, 0), b3, voffB); PG8_STAGE(PG8_SB(1, 1), b3 + hstep, voffB); PG8_STAGE(PG8_SA(1, 0), a3, voffA); }
;             if (!fin) PG8_WAIT_V(8); PG8_WAIT_L(0); PG8_BAR; PG8_MMA(1, 0, At, B0); PG8_MMA(1, 1, At, B1); PG8_BAR; PG8_SCHED;
	s_setprio 0
	s_nop 4
	ds_read_b128 v[10:13], v204
	ds_read_b128 v[14:17], v204 offset:1024
	ds_read_b128 v[18:21], v204 offset:2048
	ds_read_b128 v[22:25], v204 offset:3072
	ds_read_b128 v[186:189], v205
	ds_read_b128 v[190:193], v205 offset:1024
	ds_read_b128 v[210:213], v205 offset:2048
	ds_read_b128 v[214:217], v205 offset:3072
	ds_read_b128 v[26:29], v203 offset:32768
	ds_read_b128 v[30:33], v203 offset:33792
	ds_read_b128 v[62:65], v203 offset:34816
	ds_read_b128 v[218:221], v203 offset:35840
	ds_read_b128 v[222:225], v203 offset:36864
	ds_read_b128 v[226:229], v203 offset:37888
	ds_read_b128 v[230:233], v203 offset:38912
	ds_read_b128 v[234:237], v203 offset:39936
	s_add_u32 s26, s54, 0x40100
	s_addc_u32 s27, s55, 0
	s_add_u32 m0, s28, 0x4000
	s_nop 0
	global_load_lds_dwordx4 v1, s[26:27]
	s_nop 0
	s_add_u32 m0, s28, 0x6000
	s_nop 0
	global_load_lds_dwordx4 v199, s[26:27]
	s_waitcnt vmcnt(8)
	s_waitcnt lgkmcnt(0)
	s_barrier
	v_mfma_f32_16x16x32_f16 v[66:69], v[10:13], v[26:29], v[66:69]
	s_setprio 1
	v_mfma_f32_16x16x32_f16 v[126:129], v[14:17], v[30:33], v[66:69]
	v_mfma_f32_16x16x32_f16 v[66:69], v[18:21], v[26:29], v[70:73]
	v_mfma_f32_16x16x32_f16 v[122:125], v[22:25], v[30:33], v[66:69]
	v_mfma_f32_16x16x32_f16 v[66:69], v[10:13], v[62:65], v[74:77]
	v_mfma_f32_16x16x32_f16 v[110:113], v[14:17], v[218:221], v[66:69]
	v_mfma_f32_16x16x32_f16 v[66:69], v[18:21], v[62:65], v[78:81]
	v_mfma_f32_16x16x32_f16 v[106:109], v[22:25], v[218:221], v[66:69]
	v_mfma_f32_16x16x32_f16 v[66:69], v[10:13], v[222:225], v[82:85]
	v_mfma_f32_16x16x32_f16 v[94:97], v[14:17], v[226:229], v[66:69]
	v_mfma_f32_16x16x32_f16 v[66:69], v[18:21], v[222:225], v[86:89]
	v_mfma_f32_16x16x32_f16 v[90:93], v[22:25], v[226:229], v[66:69]
	v_mfma_f32_16x16x32_f16 v[66:69], v[10:13], v[230:233], v[98:101]
	v_mfma_f32_16x16x32_f16 v[78:81], v[14:17], v[234:237], v[66:69]
	v_mfma_f32_16x16x32_f16 v[66:69], v[18:21], v[230:233], v[102:105]
	v_mfma_f32_16x16x32_f16 v[74:77], v[22:25], v[234:237], v[66:69]
	v_mfma_f32_16x16x32_f16 v[66:69], v[186:189], v[26:29], v[114:117]
	v_mfma_f32_16x16x32_f16 v[118:121], v[190:193], v[30:33], v[66:69]
	v_mfma_f32_16x16x32_f16 v[26:29], v[210:213], v[26:29], v[34:37]
	v_mfma_f32_16x16x32_f16 v[114:117], v[214:217], v[30:33], v[26:29]
	v_mfma_f32_16x16x32_f16 v[26:29], v[186:189], v[62:65], v[38:41]
	v_mfma_f32_16x16x32_f16 v[102:105], v[190:193], v[218:221], v[26:29]
	v_mfma_f32_16x16x32_f16 v[26:29], v[210:213], v[62:65], v[42:45]
	v_mfma_f32_16x16x32_f16 v[98:101], v[214:217], v[218:221], v[26:29]
	v_mfma_f32_16x16x32_f16 v[26:29], v[186:189], v[222:225], v[46:49]
	v_mfma_f32_16x16x32_f16 v[86:89], v[190:193], v[226:229], v[26:29]
	v_mfma_f32_16x16x32_f16 v[26:29], v[210:213], v[222:225], v[50:53]
	v_mfma_f32_16x16x32_f16 v[82:85], v[214:217], v[226:229], v[26:29]
	v_mfma_f32_16x16x32_f16 v[26:29], v[186:189], v[230:233], v[54:57]
	v_mfma_f32_16x16x32_f16 v[70:73], v[190:193], v[234:237], v[26:29]
	v_mfma_f32_16x16x32_f16 v[26:29], v[210:213], v[230:233], v[58:61]
	v_mfma_f32_16x16x32_f16 v[66:69], v[214:217], v[234:237], v[26:29]
	s_barrier
	s_setprio 0
	ds_read_b128 v[34:37], v203 offset:49152
	ds_read_b128 v[38:41], v203 offset:50176
	ds_read_b128 v[218:221], v203 offset:51200
	ds_read_b128 v[222:225], v203 offset:52224
	ds_read_b128 v[226:229], v203 offset:53248
	ds_read_b128 v[230:233], v203 offset:54272
	ds_read_b128 v[234:237], v203 offset:55296
	ds_read_b128 v[238:241], v203 offset:56320
	s_add_u32 m0, s28, 0x18000
	s_nop 0
	global_load_lds_dwordx4 v198, s[24:25]
	s_nop 0
	s_add_u32 m0, s28, 0x1a000
	s_nop 0
	global_load_lds_dwordx4 v200, s[24:25]
	s_add_u32 s24, s6, 0x40180
	s_addc_u32 s25, s7, 0
	s_add_u32 m0, s28, 0x1c000
	s_nop 0
	global_load_lds_dwordx4 v198, s[24:25]
	s_nop 0
	s_add_u32 m0, s28, 0x1e000
	s_nop 0
	global_load_lds_dwordx4 v200, s[24:25]
	s_nop 0
	s_add_u32 m0, s28, 0x8000
	s_nop 0
	global_load_lds_dwordx4 v1, s[8:9]
	s_nop 0
	s_add_u32 m0, s28, 0xa000
	s_nop 0
	global_load_lds_dwordx4 v199, s[8:9]
	s_waitcnt vmcnt(8)
	s_waitcnt lgkmcnt(0)
	s_barrier
	v_mfma_f32_16x16x32_f16 v[26:29], v[10:13], v[34:37], v[130:133]
	s_setprio 1
	v_mfma_f32_16x16x32_f16 v[62:65], v[14:17], v[38:41], v[26:29]
	v_mfma_f32_16x16x32_f16 v[26:29], v[22:25], v[38:41], v[134:137]
	v_mfma_f32_16x16x32_f16 v[58:61], v[18:21], v[34:37], v[26:29]
	v_mfma_f32_16x16x32_f16 v[26:29], v[10:13], v[218:221], v[138:141]
	v_mfma_f32_16x16x32_f16 v[46:49], v[14:17], v[222:225], v[26:29]
	v_mfma_f32_16x16x32_f16 v[26:29], v[22:25], v[222:225], v[142:145]
	v_mfma_f32_16x16x32_f16 v[42:45], v[18:21], v[218:221], v[26:29]
	v_mfma_f32_16x16x32_f16 v[26:29], v[10:13], v[226:229], v[146:149]
	v_mfma_f32_16x16x32_f16 v[30:33], v[14:17], v[230:233], v[26:29]
	v_mfma_f32_16x16x32_f16 v[2:5], v[14:17], v[238:241], v[2:5]
	v_mfma_f32_16x16x32_f16 v[14:17], v[10:13], v[234:237], v[2:5]
	v_mfma_f32_16x16x32_f16 v[2:5], v[18:21], v[234:237], v[6:9]
	v_mfma_f32_16x16x32_f16 v[10:13], v[22:25], v[238:241], v[2:5]
	v_mfma_f32_16x16x32_f16 v[26:29], v[22:25], v[230:233], v[150:153]
	v_mfma_f32_16x16x32_f16 v[26:29], v[18:21], v[226:229], v[26:29]
	v_mfma_f32_16x16x32_f16 v[2:5], v[186:189], v[34:37], v[154:157]
	v_mfma_f32_16x16x32_f16 v[54:57], v[190:193], v[38:41], v[2:5]
	v_mfma_f32_16x16x32_f16 v[2:5], v[214:217], v[38:41], v[158:161]
	v_mfma_f32_16x16x32_f16 v[50:53], v[210:213], v[34:37], v[2:5]
	v_mfma_f32_16x16x32_f16 v[2:5], v[186:189], v[218:221], v[162:165]
	v_mfma_f32_16x16x32_f16 v[38:41], v[190:193], v[222:225], v[2:5]
	v_mfma_f32_16x16x32_f16 v[2:5], v[214:217], v[222:225], v[166:169]
	v_mfma_f32_16x16x32_f16 v[34:37], v[210:213], v[218:221], v[2:5]
	v_mfma_f32_16x16x32_f16 v[2:5], v[186:189], v[226:229], v[170:173]
	v_mfma_f32_16x16x32_f16 v[22:25], v[190:193], v[230:233], v[2:5]
	v_mfma_f32_16x16x32_f16 v[2:5], v[214:217], v[230:233], v[174:177]
	v_mfma_f32_16x16x32_f16 v[18:21], v[210:213], v[226:229], v[2:5]
	v_mfma_f32_16x16x32_f16 v[2:5], v[186:189], v[234:237], v[178:181]
	v_mfma_f32_16x16x32_f16 v[6:9], v[190:193], v[238:241], v[2:5]
	v_mfma_f32_16x16x32_f16 v[2:5], v[214:217], v[238:241], v[182:185]
	v_mfma_f32_16x16x32_f16 v[2:5], v[210:213], v[234:237], v[2:5]
	s_barrier
	s_setprio 0
	s_add_u32 s54, s6, 0x200
	s_addc_u32 s55, s7, 0
	s_mov_b32 s58, 0
	s_branch .LBB0_1113
; #define PG8_STAGE(bufoff, gbase, voff) do { if constexpr (ABL & 1) break; glds16s<(bufoff)>((voff)[0], (const void*)(gbase), ldsbw); glds16s<(bufoff) + 8192>((voff)[1], (const void*)(gbase), ldsbw); } while (0)
; #define PG8_LDA(dst, b, h) do { if constexpr (ABL & 4) break; _Pragma("unroll") for (int m = 0; m < 4; ++m) _Pragma("unroll") for (int k = 0; k < 2; ++k) dst[m][k] = *(const LAS f16x8*)(lds + PG8_SA(b, h) + aoff + m * 2048 + k * 1024); } while (0)
; #define PG8_LDB(dst, b, h) do { if constexpr (ABL & 4) break; _Pragma("unroll") for (int n = 0; n < 2; ++n) _Pragma("unroll") for (int k = 0; k < 2; ++k) dst[n][k] = *(const LAS f16x8*)(lds + PG8_SB(b, h) + boff + n * 2048 + k * 1024); } while (0)
; #define PG8_BAR __builtin_amdgcn_s_barrier()
;     ...
;         for (int t = 0; t < nt; t += 2) {
;             const bool last = (t == nt - 2);
;             const char* a1 = cA + (size_t)(t + 1) * kstep;
;             const char* a2 = last ? nA : cA + (size_t)(t + 2) * kstep; const char* b2 = last ? nB : cB + (size_t)(t + 2) * kstep;
;             const char* a3 = a2 + kstep; const char* b3 = b2 + kstep;
;             if (last && has_next) S.a_ready(nxt);
;             if constexpr (SP2) {
;             PG8_LDB(B0, 0, 0); PG8_LDB(B1, 0, 1); PG8_SCHED; PG8_LDA(At, 0, 0); PG8_STAGE(PG8_SA(1, 1), a1 + hstep, voffA);
;             PG8_WAIT_V(8); PG8_WAIT_L(0); PG8_BAR; PG8_MMAF(0, 0, At, B0); PG8_MMAF(0, 1, At, B1); PG8_BAR; PG8_SCHED;
;             const bool fin = last && !has_next;
;             PG8_LDA(At, 0, 1); if (!fin) { PG8_STAGE(PG8_SB(0, 0), b2, voffB); PG8_STAGE(PG8_SB(0, 1), b2 + hstep, voffB); PG8_STAGE(PG8_SA(0, 0), a2, voffA); }
;             if (!fin) PG8_WAIT_V(8); else PG8_WAIT_V(2); PG8_WAIT_L(0); PG8_BAR; PG8_MMAF(1, 0, At, B0); PG8_MMAF(1, 1, At, B1); PG8_BAR; PG8_SCHED;
;             PG8_LDB(B0, 1, 0); PG8_LDB(B1, 1, 1); PG8_SCHED; PG8_LDA(At, 1, 0); if (!fin) PG8_STAGE(PG8_SA(0, 1), a2 + hstep, voffA);
;             if (!fin) PG8_WAIT_V(8); else PG8_WAIT_V(0); PG8_WAIT_L(0); PG8_BAR; PG8_MMA(0, 0, At, B0); PG8_MMA(0, 1, At, B1); PG8_BAR; PG8_SCHED;
;             PG8_LDA(At, 1, 1); if (!fin) { PG8_STAGE(PG8_SB(1, 0), b3, voffB); PG8_STAGE(PG8_SB(1, 1), b3 + hstep, voffB); PG8_STAGE(PG8_SA(1, 0), a3, voffA); }
;             if (!fin) PG8_WAIT_V(8); PG8_WAIT_L(0); PG8_BAR; PG8_MMA(1, 0, At, B0); PG8_MMA(1, 1, At, B1); PG8_BAR; PG8_SCHED;
.LBB0_1112:
	s_waitcnt lgkmcnt(0)
	s_barrier
	v_mfma_f32_16x16x32_f16 v[62:65], v[146:149], v[186:189], v[62:65]
	s_setprio 1
	v_mfma_f32_16x16x32_f16 v[62:65], v[150:153], v[190:193], v[62:65]
	v_mfma_f32_16x16x32_f16 v[58:61], v[158:161], v[190:193], v[58:61]
	v_mfma_f32_16x16x32_f16 v[58:61], v[154:157], v[186:189], v[58:61]
	v_mfma_f32_16x16x32_f16 v[42:45], v[154:157], v[178:181], v[42:45]
	v_mfma_f32_16x16x32_f16 v[42:45], v[158:161], v[182:185], v[42:45]
	v_mfma_f32_16x16x32_f16 v[46:49], v[150:153], v[182:185], v[46:49]
	v_mfma_f32_16x16x32_f16 v[46:49], v[146:149], v[178:181], v[46:49]
	v_mfma_f32_16x16x32_f16 v[30:33], v[146:149], v[170:173], v[30:33]
	v_mfma_f32_16x16x32_f16 v[30:33], v[150:153], v[174:177], v[30:33]
	v_mfma_f32_16x16x32_f16 v[26:29], v[158:161], v[174:177], v[26:29]
	v_mfma_f32_16x16x32_f16 v[26:29], v[154:157], v[170:173], v[26:29]
	v_mfma_f32_16x16x32_f16 v[10:13], v[154:157], v[162:165], v[10:13]
	v_mfma_f32_16x16x32_f16 v[10:13], v[158:161], v[166:169], v[10:13]
	v_mfma_f32_16x16x32_f16 v[14:17], v[150:153], v[166:169], v[14:17]
	v_mfma_f32_16x16x32_f16 v[14:17], v[146:149], v[162:165], v[14:17]
	v_mfma_f32_16x16x32_f16 v[6:9], v[130:133], v[162:165], v[6:9]
	v_mfma_f32_16x16x32_f16 v[6:9], v[134:137], v[166:169], v[6:9]
	v_mfma_f32_16x16x32_f16 v[54:57], v[134:137], v[190:193], v[54:57]
	v_mfma_f32_16x16x32_f16 v[54:57], v[130:133], v[186:189], v[54:57]
	v_mfma_f32_16x16x32_f16 v[50:53], v[138:141], v[186:189], v[50:53]
	v_mfma_f32_16x16x32_f16 v[50:53], v[142:145], v[190:193], v[50:53]
	v_mfma_f32_16x16x32_f16 v[34:37], v[142:145], v[182:185], v[34:37]
	v_mfma_f32_16x16x32_f16 v[34:37], v[138:141], v[178:181], v[34:37]
	v_mfma_f32_16x16x32_f16 v[38:41], v[130:133], v[178:181], v[38:41]
	v_mfma_f32_16x16x32_f16 v[38:41], v[134:137], v[182:185], v[38:41]
	v_mfma_f32_16x16x32_f16 v[22:25], v[134:137], v[174:177], v[22:25]
	v_mfma_f32_16x16x32_f16 v[22:25], v[130:133], v[170:173], v[22:25]
	v_mfma_f32_16x16x32_f16 v[18:21], v[138:141], v[170:173], v[18:21]
	v_mfma_f32_16x16x32_f16 v[18:21], v[142:145], v[174:177], v[18:21]
	v_mfma_f32_16x16x32_f16 v[2:5], v[142:145], v[166:169], v[2:5]
	v_mfma_f32_16x16x32_f16 v[2:5], v[138:141], v[162:165], v[2:5]
	s_barrier
	s_setprio 0
	s_add_i32 s58, s58, 2
	s_add_u32 s54, s54, 0x100
	s_addc_u32 s55, s55, 0
	s_cmp_gt_u32 s58, 13
	s_cbranch_scc1 .LBB0_1123
.LBB0_1113:
	ds_read_b128 v[146:149], v201
	ds_read_b128 v[150:153], v201 offset:1024
	ds_read_b128 v[154:157], v201 offset:2048
	ds_read_b128 v[158:161], v201 offset:3072
	ds_read_b128 v[130:133], v202
	ds_read_b128 v[134:137], v202 offset:1024
	ds_read_b128 v[138:141], v202 offset:2048
	ds_read_b128 v[142:145], v202 offset:3072
	s_mov_b64 s[6:7], s[52:53]
	s_add_u32 s52, s6, 0x100
	s_addc_u32 s53, s7, 0
	s_cmp_eq_u32 s58, 12
	s_cselect_b64 s[26:27], -1, 0
	s_and_b64 s[8:9], s[26:27], exec
	s_cselect_b32 s25, s43, s53
	s_cselect_b32 s24, s56, s52
	s_cselect_b32 s9, s41, s55
	s_cselect_b32 s8, s57, s54
	ds_read_b128 v[162:165], v203
	ds_read_b128 v[166:169], v203 offset:1024
	ds_read_b128 v[170:173], v203 offset:2048
	ds_read_b128 v[174:177], v203 offset:3072
	ds_read_b128 v[178:181], v203 offset:4096
	ds_read_b128 v[182:185], v203 offset:5120
	ds_read_b128 v[186:189], v203 offset:6144
	ds_read_b128 v[190:193], v203 offset:7168
	s_add_u32 s6, s6, 0x40080
	s_addc_u32 s7, s7, 0
	s_add_u32 m0, s28, 0xc000
	s_nop 0
	global_load_lds_dwordx4 v1, s[6:7]
	s_nop 0
	s_add_u32 m0, s28, 0xe000
	s_nop 0
	global_load_lds_dwordx4 v199, s[6:7]
	s_waitcnt vmcnt(8)
	s_waitcnt lgkmcnt(0)
	s_barrier
	v_mfma_f32_16x16x32_f16 v[126:129], v[146:149], v[162:165], v[126:129]
	s_setprio 1
	v_mfma_f32_16x16x32_f16 v[126:129], v[150:153], v[166:169], v[126:129]
	v_mfma_f32_16x16x32_f16 v[122:125], v[158:161], v[166:169], v[122:125]
	v_mfma_f32_16x16x32_f16 v[122:125], v[154:157], v[162:165], v[122:125]
	v_mfma_f32_16x16x32_f16 v[106:109], v[154:157], v[170:173], v[106:109]
	v_mfma_f32_16x16x32_f16 v[106:109], v[158:161], v[174:177], v[106:109]
	v_mfma_f32_16x16x32_f16 v[110:113], v[150:153], v[174:177], v[110:113]
	v_mfma_f32_16x16x32_f16 v[110:113], v[146:149], v[170:173], v[110:113]
	v_mfma_f32_16x16x32_f16 v[94:97], v[146:149], v[178:181], v[94:97]
	v_mfma_f32_16x16x32_f16 v[94:97], v[150:153], v[182:185], v[94:97]
	v_mfma_f32_16x16x32_f16 v[90:93], v[158:161], v[182:185], v[90:93]
	v_mfma_f32_16x16x32_f16 v[90:93], v[154:157], v[178:181], v[90:93]
	v_mfma_f32_16x16x32_f16 v[74:77], v[154:157], v[186:189], v[74:77]
	v_mfma_f32_16x16x32_f16 v[74:77], v[158:161], v[190:193], v[74:77]
	v_mfma_f32_16x16x32_f16 v[78:81], v[150:153], v[190:193], v[78:81]
	v_mfma_f32_16x16x32_f16 v[78:81], v[146:149], v[186:189], v[78:81]
	v_mfma_f32_16x16x32_f16 v[70:73], v[130:133], v[186:189], v[70:73]
	v_mfma_f32_16x16x32_f16 v[70:73], v[134:137], v[190:193], v[70:73]
	v_mfma_f32_16x16x32_f16 v[118:121], v[134:137], v[166:169], v[118:121]
	v_mfma_f32_16x16x32_f16 v[118:121], v[130:133], v[162:165], v[118:121]
	v_mfma_f32_16x16x32_f16 v[114:117], v[138:141], v[162:165], v[114:117]
	v_mfma_f32_16x16x32_f16 v[114:117], v[142:145], v[166:169], v[114:117]
	v_mfma_f32_16x16x32_f16 v[98:101], v[142:145], v[174:177], v[98:101]
	v_mfma_f32_16x16x32_f16 v[98:101], v[138:141], v[170:173], v[98:101]
	v_mfma_f32_16x16x32_f16 v[102:105], v[130:133], v[170:173], v[102:105]
	v_mfma_f32_16x16x32_f16 v[102:105], v[134:137], v[174:177], v[102:105]
	v_mfma_f32_16x16x32_f16 v[86:89], v[134:137], v[182:185], v[86:89]
	v_mfma_f32_16x16x32_f16 v[86:89], v[130:133], v[178:181], v[86:89]
	v_mfma_f32_16x16x32_f16 v[82:85], v[138:141], v[178:181], v[82:85]
	v_mfma_f32_16x16x32_f16 v[82:85], v[142:145], v[182:185], v[82:85]
	v_mfma_f32_16x16x32_f16 v[66:69], v[142:145], v[190:193], v[66:69]
	v_mfma_f32_16x16x32_f16 v[66:69], v[138:141], v[186:189], v[66:69]
	s_barrier
	s_setprio 0
	ds_read_b128 v[186:189], v203 offset:16384
	ds_read_b128 v[190:193], v203 offset:17408
	ds_read_b128 v[178:181], v203 offset:18432
	ds_read_b128 v[182:185], v203 offset:19456
	ds_read_b128 v[170:173], v203 offset:20480
	ds_read_b128 v[174:177], v203 offset:21504
	ds_read_b128 v[162:165], v203 offset:22528
	ds_read_b128 v[166:169], v203 offset:23552
	s_and_b64 s[6:7], s[4:5], s[26:27]
	s_mov_b64 s[26:27], -1
	s_and_b64 vcc, exec, s[6:7]
	s_cbranch_vccnz .LBB0_1115
	s_add_u32 m0, s28, 0x10000
	s_nop 0
	global_load_lds_dwordx4 v198, s[8:9]
	s_nop 0
	s_add_u32 m0, s28, 0x12000
	s_nop 0
	global_load_lds_dwordx4 v200, s[8:9]
	s_add_u32 s26, s8, 0x40000
	s_addc_u32 s27, s9, 0
	s_add_u32 m0, s28, 0x14000
	s_nop 0
	global_load_lds_dwordx4 v198, s[26:27]
	s_nop 0
	s_add_u32 m0, s28, 0x16000
	s_nop 0
	global_load_lds_dwordx4 v200, s[26:27]
	s_mov_b64 s[26:27], 0
	s_add_u32 m0, s28, 0
	s_nop 0
	global_load_lds_dwordx4 v1, s[24:25]
	s_nop 0
	s_add_u32 m0, s28, 0x2000
	s_nop 0
	global_load_lds_dwordx4 v199, s[24:25]
	s_waitcnt vmcnt(8)

; #define PG8_STAGE(bufoff, gbase, voff) do { if constexpr (ABL & 1) break; glds16s<(bufoff)>((voff)[0], (const void*)(gbase), ldsbw); glds16s<(bufoff) + 8192>((voff)[1], (const void*)(gbase), ldsbw); } while (0)
; #define PG8_LDA(dst, b, h) do { if constexpr (ABL & 4) break; _Pragma("unroll") for (int m = 0; m < 4; ++m) _Pragma("unroll") for (int k = 0; k < 2; ++k) dst[m][k] = *(const LAS f16x8*)(lds + PG8_SA(b, h) + aoff + m * 2048 + k * 1024); } while (0)
; #define PG8_LDB(dst, b, h) do { if constexpr (ABL & 4) break; _Pragma("unroll") for (int n = 0; n < 2; ++n) _Pragma("unroll") for (int k = 0; k < 2; ++k) dst[n][k] = *(const LAS f16x8*)(lds + PG8_SB(b, h) + boff + n * 2048 + k * 1024); } while (0)
; #define PG8_MMA(ai, bj, At, Bt) do { if constexpr (ABL & 2) break; __builtin_amdgcn_s_setprio(1); _Pragma("unroll") for (int m = 0; m < 4; ++m) _Pragma("unroll") for (int n = 0; n < 2; ++n) _Pragma("unroll") for (int k = 0; k < 2; ++k) \
;         acc[ai][bj][m][n] = __builtin_amdgcn_mfma_f32_16x16x32_f16(Bt[n][k], At[m][k], acc[ai][bj][m][n], 0, 0, 0); __builtin_amdgcn_s_setprio(0); } while (0)
; #define PG8_MMAF(ai, bj, At, Bt) do { if (t == 0) PG8_MMA0(ai, bj, At, Bt); else PG8_MMA(ai, bj, At, Bt); } while (0)
; #define PG8_WAIT_V(n) asm volatile("s_waitcnt vmcnt(" #n ")" ::: "memory")
; #define PG8_WAIT_L(n) asm volatile("s_waitcnt lgkmcnt(" #n ")" ::: "memory")
; #define PG8_BAR __builtin_amdgcn_s_barrier()
; #define PG8_SCHED __builtin_amdgcn_sched_barrier(0)
;     ...
;             if (!fin) PG8_WAIT_V(8); else PG8_WAIT_V(2); PG8_WAIT_L(0); PG8_BAR; PG8_MMAF(1, 0, At, B0); PG8_MMAF(1, 1, At, B1); PG8_BAR; PG8_SCHED;
;             PG8_LDB(B0, 1, 0); PG8_LDB(B1, 1, 1); PG8_SCHED; PG8_LDA(At, 1, 0); if (!fin) PG8_STAGE(PG8_SA(0, 1), a2 + hstep, voffA);
;             if (!fin) PG8_WAIT_V(8); else PG8_WAIT_V(0); PG8_WAIT_L(0); PG8_BAR; PG8_MMA(0, 0, At, B0); PG8_MMA(0, 1, At, B1); PG8_BAR; PG8_SCHED;
.LBB0_1117:
	s_waitcnt lgkmcnt(0)
	s_xor_b64 s[26:27], s[6:7], -1
	s_barrier
	v_mfma_f32_16x16x32_f16 v[62:65], v[146:149], v[186:189], v[62:65]
	s_setprio 1
	v_mfma_f32_16x16x32_f16 v[62:65], v[150:153], v[190:193], v[62:65]
	v_mfma_f32_16x16x32_f16 v[58:61], v[158:161], v[190:193], v[58:61]
	v_mfma_f32_16x16x32_f16 v[58:61], v[154:157], v[186:189], v[58:61]
	v_mfma_f32_16x16x32_f16 v[42:45], v[154:157], v[178:181], v[42:45]
	v_mfma_f32_16x16x32_f16 v[42:45], v[158:161], v[182:185], v[42:45]
	v_mfma_f32_16x16x32_f16 v[46:49], v[150:153], v[182:185], v[46:49]
	v_mfma_f32_16x16x32_f16 v[46:49], v[146:149], v[178:181], v[46:49]
	v_mfma_f32_16x16x32_f16 v[30:33], v[146:149], v[170:173], v[30:33]
	v_mfma_f32_16x16x32_f16 v[30:33], v[150:153], v[174:177], v[30:33]
	v_mfma_f32_16x16x32_f16 v[26:29], v[158:161], v[174:177], v[26:29]
	v_mfma_f32_16x16x32_f16 v[26:29], v[154:157], v[170:173], v[26:29]
	v_mfma_f32_16x16x32_f16 v[10:13], v[154:157], v[162:165], v[10:13]
	v_mfma_f32_16x16x32_f16 v[10:13], v[158:161], v[166:169], v[10:13]
	v_mfma_f32_16x16x32_f16 v[14:17], v[150:153], v[166:169], v[14:17]
	v_mfma_f32_16x16x32_f16 v[14:17], v[146:149], v[162:165], v[14:17]
	v_mfma_f32_16x16x32_f16 v[6:9], v[130:133], v[162:165], v[6:9]
	v_mfma_f32_16x16x32_f16 v[6:9], v[134:137], v[166:169], v[6:9]
	v_mfma_f32_16x16x32_f16 v[54:57], v[134:137], v[190:193], v[54:57]
	v_mfma_f32_16x16x32_f16 v[54:57], v[130:133], v[186:189], v[54:57]
	v_mfma_f32_16x16x32_f16 v[50:53], v[138:141], v[186:189], v[50:53]
	v_mfma_f32_16x16x32_f16 v[50:53], v[142:145], v[190:193], v[50:53]
	v_mfma_f32_16x16x32_f16 v[34:37], v[142:145], v[182:185], v[34:37]
	v_mfma_f32_16x16x32_f16 v[34:37], v[138:141], v[178:181], v[34:37]
	v_mfma_f32_16x16x32_f16 v[38:41], v[130:133], v[178:181], v[38:41]
	v_mfma_f32_16x16x32_f16 v[38:41], v[134:137], v[182:185], v[38:41]
	v_mfma_f32_16x16x32_f16 v[22:25], v[134:137], v[174:177], v[22:25]
	v_mfma_f32_16x16x32_f16 v[22:25], v[130:133], v[170:173], v[22:25]
	v_mfma_f32_16x16x32_f16 v[18:21], v[138:141], v[170:173], v[18:21]
	v_mfma_f32_16x16x32_f16 v[18:21], v[142:145], v[174:177], v[18:21]
	v_mfma_f32_16x16x32_f16 v[2:5], v[142:145], v[166:169], v[2:5]
	v_mfma_f32_16x16x32_f16 v[2:5], v[138:141], v[162:165], v[2:5]
	s_barrier
	s_setprio 0
	ds_read_b128 v[146:149], v204
	ds_read_b128 v[150:153], v204 offset:1024
	ds_read_b128 v[154:157], v204 offset:2048
	ds_read_b128 v[158:161], v204 offset:3072
	ds_read_b128 v[130:133], v205
	ds_read_b128 v[134:137], v205 offset:1024
	ds_read_b128 v[138:141], v205 offset:2048
	ds_read_b128 v[142:145], v205 offset:3072
	ds_read_b128 v[186:189], v203 offset:32768
	ds_read_b128 v[190:193], v203 offset:33792
	ds_read_b128 v[178:181], v203 offset:34816
	ds_read_b128 v[182:185], v203 offset:35840
	ds_read_b128 v[170:173], v203 offset:36864
	ds_read_b128 v[174:177], v203 offset:37888
	ds_read_b128 v[162:165], v203 offset:38912
	ds_read_b128 v[166:169], v203 offset:39936
	v_cndmask_b32_e64 v209, 0, 1, s[26:27]
	v_cmp_ne_u32_e64 s[6:7], 1, v209
	s_andn2_b64 vcc, exec, s[26:27]
	s_mov_b64 s[26:27], -1
	s_cbranch_vccnz .LBB0_1119
	s_add_u32 s26, s24, 0x40000
	s_addc_u32 s27, s25, 0
	s_add_u32 m0, s28, 0x4000
	s_nop 0
	global_load_lds_dwordx4 v1, s[26:27]
	s_nop 0
	s_add_u32 m0, s28, 0x6000
	s_nop 0
	global_load_lds_dwordx4 v199, s[26:27]
	s_waitcnt vmcnt(8)
	s_mov_b64 s[26:27], 0

; #define PG8_STAGE(bufoff, gbase, voff) do { if constexpr (ABL & 1) break; glds16s<(bufoff)>((voff)[0], (const void*)(gbase), ldsbw); glds16s<(bufoff) + 8192>((voff)[1], (const void*)(gbase), ldsbw); } while (0)
; #define PG8_LDA(dst, b, h) do { if constexpr (ABL & 4) break; _Pragma("unroll") for (int m = 0; m < 4; ++m) _Pragma("unroll") for (int k = 0; k < 2; ++k) dst[m][k] = *(const LAS f16x8*)(lds + PG8_SA(b, h) + aoff + m * 2048 + k * 1024); } while (0)
; #define PG8_MMA(ai, bj, At, Bt) do { if constexpr (ABL & 2) break; __builtin_amdgcn_s_setprio(1); _Pragma("unroll") for (int m = 0; m < 4; ++m) _Pragma("unroll") for (int n = 0; n < 2; ++n) _Pragma("unroll") for (int k = 0; k < 2; ++k) \
;         acc[ai][bj][m][n] = __builtin_amdgcn_mfma_f32_16x16x32_f16(Bt[n][k], At[m][k], acc[ai][bj][m][n], 0, 0, 0); __builtin_amdgcn_s_setprio(0); } while (0)
; #define PG8_WAIT_V(n) asm volatile("s_waitcnt vmcnt(" #n ")" ::: "memory")
; #define PG8_WAIT_L(n) asm volatile("s_waitcnt lgkmcnt(" #n ")" ::: "memory")
; #define PG8_BAR __builtin_amdgcn_s_barrier()
; #define PG8_SCHED __builtin_amdgcn_sched_barrier(0)
;     ...
;             if (!fin) PG8_WAIT_V(8); else PG8_WAIT_V(0); PG8_WAIT_L(0); PG8_BAR; PG8_MMA(0, 0, At, B0); PG8_MMA(0, 1, At, B1); PG8_BAR; PG8_SCHED;
;             PG8_LDA(At, 1, 1); if (!fin) { PG8_STAGE(PG8_SB(1, 0), b3, voffB); PG8_STAGE(PG8_SB(1, 1), b3 + hstep, voffB); PG8_STAGE(PG8_SA(1, 0), a3, voffA); }
;             if (!fin) PG8_WAIT_V(8); PG8_WAIT_L(0); PG8_BAR; PG8_MMA(1, 0, At, B0); PG8_MMA(1, 1, At, B1); PG8_BAR; PG8_SCHED;
.LBB0_1121:
	s_waitcnt lgkmcnt(0)
	s_barrier
	v_mfma_f32_16x16x32_f16 v[126:129], v[146:149], v[186:189], v[126:129]
	s_setprio 1
	v_mfma_f32_16x16x32_f16 v[126:129], v[150:153], v[190:193], v[126:129]
	v_mfma_f32_16x16x32_f16 v[122:125], v[158:161], v[190:193], v[122:125]
	v_mfma_f32_16x16x32_f16 v[122:125], v[154:157], v[186:189], v[122:125]
	v_mfma_f32_16x16x32_f16 v[106:109], v[154:157], v[178:181], v[106:109]
	v_mfma_f32_16x16x32_f16 v[106:109], v[158:161], v[182:185], v[106:109]
	v_mfma_f32_16x16x32_f16 v[110:113], v[150:153], v[182:185], v[110:113]
	v_mfma_f32_16x16x32_f16 v[110:113], v[146:149], v[178:181], v[110:113]
	v_mfma_f32_16x16x32_f16 v[94:97], v[146:149], v[170:173], v[94:97]
	v_mfma_f32_16x16x32_f16 v[94:97], v[150:153], v[174:177], v[94:97]
	v_mfma_f32_16x16x32_f16 v[90:93], v[158:161], v[174:177], v[90:93]
	v_mfma_f32_16x16x32_f16 v[90:93], v[154:157], v[170:173], v[90:93]
	v_mfma_f32_16x16x32_f16 v[74:77], v[154:157], v[162:165], v[74:77]
	v_mfma_f32_16x16x32_f16 v[74:77], v[158:161], v[166:169], v[74:77]
	v_mfma_f32_16x16x32_f16 v[78:81], v[150:153], v[166:169], v[78:81]
	v_mfma_f32_16x16x32_f16 v[78:81], v[146:149], v[162:165], v[78:81]
	v_mfma_f32_16x16x32_f16 v[70:73], v[130:133], v[162:165], v[70:73]
	v_mfma_f32_16x16x32_f16 v[70:73], v[134:137], v[166:169], v[70:73]
	v_mfma_f32_16x16x32_f16 v[118:121], v[134:137], v[190:193], v[118:121]
	v_mfma_f32_16x16x32_f16 v[118:121], v[130:133], v[186:189], v[118:121]
	v_mfma_f32_16x16x32_f16 v[114:117], v[138:141], v[186:189], v[114:117]
	v_mfma_f32_16x16x32_f16 v[114:117], v[142:145], v[190:193], v[114:117]
	v_mfma_f32_16x16x32_f16 v[98:101], v[142:145], v[182:185], v[98:101]
	v_mfma_f32_16x16x32_f16 v[98:101], v[138:141], v[178:181], v[98:101]
	v_mfma_f32_16x16x32_f16 v[102:105], v[130:133], v[178:181], v[102:105]
	v_mfma_f32_16x16x32_f16 v[102:105], v[134:137], v[182:185], v[102:105]
	v_mfma_f32_16x16x32_f16 v[86:89], v[134:137], v[174:177], v[86:89]
	v_mfma_f32_16x16x32_f16 v[86:89], v[130:133], v[170:173], v[86:89]
	v_mfma_f32_16x16x32_f16 v[82:85], v[138:141], v[170:173], v[82:85]
	v_mfma_f32_16x16x32_f16 v[82:85], v[142:145], v[174:177], v[82:85]
	v_mfma_f32_16x16x32_f16 v[66:69], v[142:145], v[166:169], v[66:69]
	v_mfma_f32_16x16x32_f16 v[66:69], v[138:141], v[162:165], v[66:69]
	s_barrier
	s_setprio 0
	ds_read_b128 v[186:189], v203 offset:49152
	ds_read_b128 v[190:193], v203 offset:50176
	ds_read_b128 v[178:181], v203 offset:51200
	ds_read_b128 v[182:185], v203 offset:52224
	ds_read_b128 v[170:173], v203 offset:53248
	ds_read_b128 v[174:177], v203 offset:54272
	ds_read_b128 v[162:165], v203 offset:55296
	ds_read_b128 v[166:169], v203 offset:56320
	s_and_b64 vcc, exec, s[6:7]
	s_cbranch_vccnz .LBB0_1112
	s_add_u32 s6, s24, 0x80
	s_addc_u32 s7, s25, 0
	s_add_u32 s24, s8, 0x80
	s_addc_u32 s25, s9, 0
	s_add_u32 m0, s28, 0x18000
	s_nop 0
	global_load_lds_dwordx4 v198, s[24:25]
	s_nop 0
	s_add_u32 m0, s28, 0x1a000
	s_nop 0
	global_load_lds_dwordx4 v200, s[24:25]
	s_add_u32 s8, s8, 0x40080
	s_addc_u32 s9, s9, 0
	s_add_u32 m0, s28, 0x1c000
	s_nop 0
	global_load_lds_dwordx4 v198, s[8:9]
	s_nop 0
	s_add_u32 m0, s28, 0x1e000
	s_nop 0
	global_load_lds_dwordx4 v200, s[8:9]
	s_nop 0
	s_add_u32 m0, s28, 0x8000
	s_nop 0
	global_load_lds_dwordx4 v1, s[6:7]
	s_nop 0
	s_add_u32 m0, s28, 0xa000
	s_nop 0
	global_load_lds_dwordx4 v199, s[6:7]
	s_waitcnt vmcnt(8)
	s_branch .LBB0_1112

;     __device__ __forceinline__ bool next(int i, Unit& u) const { if (i >= count) return false; const int L = first + i; u.pm = L / nN; u.pn = L % nN; return true; }
; #define PG8_STAGE(bufoff, gbase, voff) do { if constexpr (ABL & 1) break; glds16s<(bufoff)>((voff)[0], (const void*)(gbase), ldsbw); glds16s<(bufoff) + 8192>((voff)[1], (const void*)(gbase), ldsbw); } while (0)
; #define PG8_LDA(dst, b, h) do { if constexpr (ABL & 4) break; _Pragma("unroll") for (int m = 0; m < 4; ++m) _Pragma("unroll") for (int k = 0; k < 2; ++k) dst[m][k] = *(const LAS f16x8*)(lds + PG8_SA(b, h) + aoff + m * 2048 + k * 1024); } while (0)
; #define PG8_LDB(dst, b, h) do { if constexpr (ABL & 4) break; _Pragma("unroll") for (int n = 0; n < 2; ++n) _Pragma("unroll") for (int k = 0; k < 2; ++k) dst[n][k] = *(const LAS f16x8*)(lds + PG8_SB(b, h) + boff + n * 2048 + k * 1024); } while (0)
; #define PG8_MMAF(ai, bj, At, Bt) do { if (t == 0) PG8_MMA0(ai, bj, At, Bt); else PG8_MMA(ai, bj, At, Bt); } while (0)
; #define PG8_WAIT_V(n) asm volatile("s_waitcnt vmcnt(" #n ")" ::: "memory")
; #define PG8_BAR __builtin_amdgcn_s_barrier()
;     ...
;         const bool has_next = S.next(ui + 1, nxt);
;         const char* nA = has_next ? (const char*)g.A + (size_t)nxt.pm * tstep : cA; const char* nB = has_next ? (const char*)g.Bt + (size_t)nxt.pn * tstep : cB;
;         for (int t = 0; t < nt; t += 2) {
;             const bool last = (t == nt - 2);
;             const char* a1 = cA + (size_t)(t + 1) * kstep;
;             const char* a2 = last ? nA : cA + (size_t)(t + 2) * kstep; const char* b2 = last ? nB : cB + (size_t)(t + 2) * kstep;
;             const char* a3 = a2 + kstep; const char* b3 = b2 + kstep;
;             if (last && has_next) S.a_ready(nxt);
;             if constexpr (SP2) {
;             PG8_LDB(B0, 0, 0); PG8_LDB(B1, 0, 1); PG8_SCHED; PG8_LDA(At, 0, 0); PG8_STAGE(PG8_SA(1, 1), a1 + hstep, voffA);
;             PG8_WAIT_V(8); PG8_WAIT_L(0); PG8_BAR; PG8_MMAF(0, 0, At, B0); PG8_MMAF(0, 1, At, B1); PG8_BAR; PG8_SCHED;
;             const bool fin = last && !has_next;
;             PG8_LDA(At, 0, 1); if (!fin) { PG8_STAGE(PG8_SB(0, 0), b2, voffB); PG8_STAGE(PG8_SB(0, 1), b2 + hstep, voffB); PG8_STAGE(PG8_SA(0, 0), a2, voffA); }
;             if (!fin) PG8_WAIT_V(8); else PG8_WAIT_V(2); PG8_WAIT_L(0); PG8_BAR; PG8_MMAF(1, 0, At, B0); PG8_MMAF(1, 1, At, B1); PG8_BAR; PG8_SCHED;
.LBB0_1163:
	s_ashr_i32 s49, s48, 31
	s_lshl_b64 s[6:7], s[48:49], 19
	s_add_u32 s50, s74, s6
	s_addc_u32 s51, s75, s7
	s_and_b64 s[6:7], exec, s[2:3]
	ds_read_b128 v[2:5], v213
	ds_read_b128 v[6:9], v213 offset:1024
	ds_read_b128 v[10:13], v213 offset:2048
	ds_read_b128 v[14:17], v213 offset:3072
	ds_read_b128 v[18:21], v214
	ds_read_b128 v[22:25], v214 offset:1024
	ds_read_b128 v[26:29], v214 offset:2048
	ds_read_b128 v[30:33], v214 offset:3072
	s_cselect_b32 s45, s37, s51
	s_cselect_b32 s49, s36, s50
	s_ashr_i32 s47, s46, 31
	s_lshl_b64 s[6:7], s[46:47], 19
	s_add_u32 s52, s94, s6
	s_addc_u32 s53, s95, s7
	s_and_b64 s[6:7], exec, s[2:3]
	s_cselect_b32 s47, s39, s53
	s_cselect_b32 s57, s38, s52
	s_add_u32 s24, s36, 0x100
	s_addc_u32 s25, s37, 0
	s_add_u32 s26, s38, 0x100
	s_addc_u32 s27, s39, 0
	s_add_u32 s6, s36, 0x180
	s_addc_u32 s7, s37, 0
	ds_read_b128 v[34:37], v215
	ds_read_b128 v[38:41], v215 offset:1024
	ds_read_b128 v[42:45], v215 offset:2048
	ds_read_b128 v[46:49], v215 offset:3072
	ds_read_b128 v[50:53], v215 offset:4096
	ds_read_b128 v[54:57], v215 offset:5120
	ds_read_b128 v[58:61], v215 offset:6144
	ds_read_b128 v[62:65], v215 offset:7168
	s_add_u32 s8, s38, 0x180
	s_addc_u32 s9, s39, 0
	s_add_u32 s54, s36, 0x40080
	s_addc_u32 s55, s37, 0
	s_add_u32 m0, s35, 0xc000
	s_nop 0
	global_load_lds_dwordx4 v1, s[54:55]
	s_nop 0
	s_add_u32 m0, s35, 0xe000
	s_nop 0
	global_load_lds_dwordx4 v211, s[54:55]
	s_waitcnt vmcnt(8)
	s_waitcnt lgkmcnt(0)
	s_barrier
	v_mfma_f32_16x16x32_f16 v[90:93], v[2:5], v[58:61], 0
	s_setprio 1
	v_mfma_f32_16x16x32_f16 v[98:101], v[6:9], v[62:65], v[90:93]
	v_mfma_f32_16x16x32_f16 v[66:69], v[2:5], v[34:37], 0
	v_mfma_f32_16x16x32_f16 v[66:69], v[6:9], v[38:41], v[66:69]
	v_mfma_f32_16x16x32_f16 v[70:73], v[10:13], v[34:37], 0
	v_mfma_f32_16x16x32_f16 v[70:73], v[14:17], v[38:41], v[70:73]
	v_mfma_f32_16x16x32_f16 v[74:77], v[2:5], v[42:45], 0
	v_mfma_f32_16x16x32_f16 v[74:77], v[6:9], v[46:49], v[74:77]
	v_mfma_f32_16x16x32_f16 v[78:81], v[10:13], v[42:45], 0
	v_mfma_f32_16x16x32_f16 v[78:81], v[14:17], v[46:49], v[78:81]
	v_mfma_f32_16x16x32_f16 v[82:85], v[2:5], v[50:53], 0
	v_mfma_f32_16x16x32_f16 v[82:85], v[6:9], v[54:57], v[82:85]
	v_mfma_f32_16x16x32_f16 v[86:89], v[10:13], v[50:53], 0
	v_mfma_f32_16x16x32_f16 v[86:89], v[14:17], v[54:57], v[86:89]
	v_mfma_f32_16x16x32_f16 v[90:93], v[10:13], v[58:61], 0
	v_mfma_f32_16x16x32_f16 v[102:105], v[14:17], v[62:65], v[90:93]
	v_mfma_f32_16x16x32_f16 v[90:93], v[18:21], v[34:37], 0
	v_mfma_f32_16x16x32_f16 v[114:117], v[22:25], v[38:41], v[90:93]
	v_mfma_f32_16x16x32_f16 v[34:37], v[26:29], v[34:37], 0
	v_mfma_f32_16x16x32_f16 v[34:37], v[30:33], v[38:41], v[34:37]
	v_mfma_f32_16x16x32_f16 v[38:41], v[18:21], v[42:45], 0
	v_mfma_f32_16x16x32_f16 v[38:41], v[22:25], v[46:49], v[38:41]
	v_mfma_f32_16x16x32_f16 v[42:45], v[26:29], v[42:45], 0
	v_mfma_f32_16x16x32_f16 v[42:45], v[30:33], v[46:49], v[42:45]
	v_mfma_f32_16x16x32_f16 v[46:49], v[18:21], v[50:53], 0
	v_mfma_f32_16x16x32_f16 v[46:49], v[22:25], v[54:57], v[46:49]
	v_mfma_f32_16x16x32_f16 v[50:53], v[26:29], v[50:53], 0
	v_mfma_f32_16x16x32_f16 v[50:53], v[30:33], v[54:57], v[50:53]
	v_mfma_f32_16x16x32_f16 v[54:57], v[18:21], v[58:61], 0
	v_mfma_f32_16x16x32_f16 v[54:57], v[22:25], v[62:65], v[54:57]
	v_mfma_f32_16x16x32_f16 v[58:61], v[26:29], v[58:61], 0
	v_mfma_f32_16x16x32_f16 v[58:61], v[30:33], v[62:65], v[58:61]
	s_barrier
	s_setprio 0
	ds_read_b128 v[62:65], v215 offset:16384
	ds_read_b128 v[90:93], v215 offset:17408
	ds_read_b128 v[94:97], v215 offset:18432
	ds_read_b128 v[106:109], v215 offset:19456
	ds_read_b128 v[110:113], v215 offset:20480
	ds_read_b128 v[118:121], v215 offset:21504
	ds_read_b128 v[122:125], v215 offset:22528
	ds_read_b128 v[126:129], v215 offset:23552
	s_add_u32 m0, s35, 0x10000
	s_nop 0
	global_load_lds_dwordx4 v210, s[26:27]
	s_nop 0
	s_add_u32 m0, s35, 0x12000
	s_nop 0
	global_load_lds_dwordx4 v212, s[26:27]
	s_add_u32 s26, s38, 0x40100
	s_addc_u32 s27, s39, 0
	s_add_u32 m0, s35, 0x14000
	s_nop 0
	global_load_lds_dwordx4 v210, s[26:27]
	s_nop 0
	s_add_u32 m0, s35, 0x16000
	s_nop 0
	global_load_lds_dwordx4 v212, s[26:27]
	s_nop 0
	s_add_u32 m0, s35, 0
	s_nop 0
	global_load_lds_dwordx4 v1, s[24:25]
	s_nop 0
	s_add_u32 m0, s35, 0x2000
	s_nop 0
	global_load_lds_dwordx4 v211, s[24:25]
	s_waitcnt vmcnt(8)
	s_waitcnt lgkmcnt(0)
	s_barrier
	v_mfma_f32_16x16x32_f16 v[134:137], v[10:13], v[62:65], 0
	s_setprio 1
	v_mfma_f32_16x16x32_f16 v[146:149], v[14:17], v[90:93], v[134:137]
	v_mfma_f32_16x16x32_f16 v[134:137], v[2:5], v[94:97], 0
	v_mfma_f32_16x16x32_f16 v[150:153], v[6:9], v[106:109], v[134:137]
	v_mfma_f32_16x16x32_f16 v[134:137], v[10:13], v[94:97], 0
	v_mfma_f32_16x16x32_f16 v[154:157], v[14:17], v[106:109], v[134:137]
	v_mfma_f32_16x16x32_f16 v[130:133], v[2:5], v[62:65], 0
	v_mfma_f32_16x16x32_f16 v[130:133], v[6:9], v[90:93], v[130:133]
	v_mfma_f32_16x16x32_f16 v[134:137], v[2:5], v[110:113], 0
	v_mfma_f32_16x16x32_f16 v[158:161], v[6:9], v[118:121], v[134:137]
	v_mfma_f32_16x16x32_f16 v[2:5], v[2:5], v[122:125], 0
	v_mfma_f32_16x16x32_f16 v[2:5], v[6:9], v[126:129], v[2:5]
	v_mfma_f32_16x16x32_f16 v[6:9], v[10:13], v[122:125], 0
	v_mfma_f32_16x16x32_f16 v[6:9], v[14:17], v[126:129], v[6:9]
	v_mfma_f32_16x16x32_f16 v[134:137], v[10:13], v[110:113], 0
	v_mfma_f32_16x16x32_f16 v[162:165], v[14:17], v[118:121], v[134:137]
	v_mfma_f32_16x16x32_f16 v[10:13], v[18:21], v[62:65], 0
	v_mfma_f32_16x16x32_f16 v[166:169], v[22:25], v[90:93], v[10:13]
	v_mfma_f32_16x16x32_f16 v[10:13], v[26:29], v[62:65], 0
	v_mfma_f32_16x16x32_f16 v[170:173], v[30:33], v[90:93], v[10:13]
	v_mfma_f32_16x16x32_f16 v[10:13], v[18:21], v[94:97], 0
	v_mfma_f32_16x16x32_f16 v[174:177], v[22:25], v[106:109], v[10:13]
	v_mfma_f32_16x16x32_f16 v[10:13], v[26:29], v[94:97], 0
	v_mfma_f32_16x16x32_f16 v[178:181], v[30:33], v[106:109], v[10:13]
	v_mfma_f32_16x16x32_f16 v[10:13], v[18:21], v[110:113], 0
	v_mfma_f32_16x16x32_f16 v[182:185], v[22:25], v[118:121], v[10:13]
	v_mfma_f32_16x16x32_f16 v[10:13], v[26:29], v[110:113], 0
	v_mfma_f32_16x16x32_f16 v[118:121], v[30:33], v[118:121], v[10:13]
	v_mfma_f32_16x16x32_f16 v[10:13], v[18:21], v[122:125], 0
	v_mfma_f32_16x16x32_f16 v[186:189], v[22:25], v[126:129], v[10:13]
	v_mfma_f32_16x16x32_f16 v[10:13], v[26:29], v[122:125], 0
	v_mfma_f32_16x16x32_f16 v[122:125], v[30:33], v[126:129], v[10:13]
	s_barrier
; #define PG8_STAGE(bufoff, gbase, voff) do { if constexpr (ABL & 1) break; glds16s<(bufoff)>((voff)[0], (const void*)(gbase), ldsbw); glds16s<(bufoff) + 8192>((voff)[1], (const void*)(gbase), ldsbw); } while (0)
; #define PG8_LDA(dst, b, h) do { if constexpr (ABL & 4) break; _Pragma("unroll") for (int m = 0; m < 4; ++m) _Pragma("unroll") for (int k = 0; k < 2; ++k) dst[m][k] = *(const LAS f16x8*)(lds + PG8_SA(b, h) + aoff + m * 2048 + k * 1024); } while (0)
; #define PG8_LDB(dst, b, h) do { if constexpr (ABL & 4) break; _Pragma("unroll") for (int n = 0; n < 2; ++n) _Pragma("unroll") for (int k = 0; k < 2; ++k) dst[n][k] = *(const LAS f16x8*)(lds + PG8_SB(b, h) + boff + n * 2048 + k * 1024); } while (0)
; #define PG8_MMA(ai, bj, At, Bt) do { if constexpr (ABL & 2) break; __builtin_amdgcn_s_setprio(1); _Pragma("unroll") for (int m = 0; m < 4; ++m) _Pragma("unroll") for (int n = 0; n < 2; ++n) _Pragma("unroll") for (int k = 0; k < 2; ++k) \
;         acc[ai][bj][m][n] = __builtin_amdgcn_mfma_f32_16x16x32_f16(Bt[n][k], At[m][k], acc[ai][bj][m][n], 0, 0, 0); __builtin_amdgcn_s_setprio(0); } while (0)
; #define PG8_WAIT_V(n) asm volatile("s_waitcnt vmcnt(" #n ")" ::: "memory")
; #define PG8_WAIT_L(n) asm volatile("s_waitcnt lgkmcnt(" #n ")" ::: "memory")
; #define PG8_BAR __builtin_amdgcn_s_barrier()
; #define PG8_SCHED __builtin_amdgcn_sched_barrier(0)
;     ...
;             PG8_LDB(B0, 1, 0); PG8_LDB(B1, 1, 1); PG8_SCHED; PG8_LDA(At, 1, 0); if (!fin) PG8_STAGE(PG8_SA(0, 1), a2 + hstep, voffA);
;             if (!fin) PG8_WAIT_V(8); else PG8_WAIT_V(0); PG8_WAIT_L(0); PG8_BAR; PG8_MMA(0, 0, At, B0); PG8_MMA(0, 1, At, B1); PG8_BAR; PG8_SCHED;
;             PG8_LDA(At, 1, 1); if (!fin) { PG8_STAGE(PG8_SB(1, 0), b3, voffB); PG8_STAGE(PG8_SB(1, 1), b3 + hstep, voffB); PG8_STAGE(PG8_SA(1, 0), a3, voffA); }
;             if (!fin) PG8_WAIT_V(8); PG8_WAIT_L(0); PG8_BAR; PG8_MMA(1, 0, At, B0); PG8_MMA(1, 1, At, B1); PG8_BAR; PG8_SCHED;
	s_setprio 0
	s_nop 4
	ds_read_b128 v[10:13], v216
	ds_read_b128 v[14:17], v216 offset:1024
	ds_read_b128 v[18:21], v216 offset:2048
	ds_read_b128 v[22:25], v216 offset:3072
	ds_read_b128 v[190:193], v217
	ds_read_b128 v[194:197], v217 offset:1024
	ds_read_b128 v[198:201], v217 offset:2048
	ds_read_b128 v[202:205], v217 offset:3072
	ds_read_b128 v[26:29], v215 offset:32768
	ds_read_b128 v[30:33], v215 offset:33792
	ds_read_b128 v[62:65], v215 offset:34816
	ds_read_b128 v[218:221], v215 offset:35840
	ds_read_b128 v[222:225], v215 offset:36864
	ds_read_b128 v[226:229], v215 offset:37888
	ds_read_b128 v[230:233], v215 offset:38912
	ds_read_b128 v[234:237], v215 offset:39936
	s_add_u32 s24, s36, 0x40100
	s_addc_u32 s25, s37, 0
	s_add_u32 m0, s35, 0x4000
	s_nop 0
	global_load_lds_dwordx4 v1, s[24:25]
	s_nop 0
	s_add_u32 m0, s35, 0x6000
	s_nop 0
	global_load_lds_dwordx4 v211, s[24:25]
	s_waitcnt vmcnt(8)
	s_waitcnt lgkmcnt(0)
	s_barrier
	v_mfma_f32_16x16x32_f16 v[66:69], v[10:13], v[26:29], v[66:69]
	s_setprio 1
	v_mfma_f32_16x16x32_f16 v[142:145], v[14:17], v[30:33], v[66:69]
	v_mfma_f32_16x16x32_f16 v[66:69], v[18:21], v[26:29], v[70:73]
	v_mfma_f32_16x16x32_f16 v[138:141], v[22:25], v[30:33], v[66:69]
	v_mfma_f32_16x16x32_f16 v[66:69], v[10:13], v[62:65], v[74:77]
	v_mfma_f32_16x16x32_f16 v[110:113], v[14:17], v[218:221], v[66:69]
	v_mfma_f32_16x16x32_f16 v[66:69], v[18:21], v[62:65], v[78:81]
	v_mfma_f32_16x16x32_f16 v[106:109], v[22:25], v[218:221], v[66:69]
	v_mfma_f32_16x16x32_f16 v[66:69], v[10:13], v[222:225], v[82:85]
	v_mfma_f32_16x16x32_f16 v[94:97], v[14:17], v[226:229], v[66:69]
	v_mfma_f32_16x16x32_f16 v[66:69], v[18:21], v[222:225], v[86:89]
	v_mfma_f32_16x16x32_f16 v[90:93], v[22:25], v[226:229], v[66:69]
	v_mfma_f32_16x16x32_f16 v[66:69], v[10:13], v[230:233], v[98:101]
	v_mfma_f32_16x16x32_f16 v[78:81], v[14:17], v[234:237], v[66:69]
	v_mfma_f32_16x16x32_f16 v[66:69], v[18:21], v[230:233], v[102:105]
	v_mfma_f32_16x16x32_f16 v[74:77], v[22:25], v[234:237], v[66:69]
	v_mfma_f32_16x16x32_f16 v[66:69], v[190:193], v[26:29], v[114:117]
	v_mfma_f32_16x16x32_f16 v[134:137], v[194:197], v[30:33], v[66:69]
	v_mfma_f32_16x16x32_f16 v[26:29], v[198:201], v[26:29], v[34:37]
	v_mfma_f32_16x16x32_f16 v[126:129], v[202:205], v[30:33], v[26:29]
	v_mfma_f32_16x16x32_f16 v[26:29], v[190:193], v[62:65], v[38:41]
	v_mfma_f32_16x16x32_f16 v[102:105], v[194:197], v[218:221], v[26:29]
	v_mfma_f32_16x16x32_f16 v[26:29], v[198:201], v[62:65], v[42:45]
	v_mfma_f32_16x16x32_f16 v[98:101], v[202:205], v[218:221], v[26:29]
	v_mfma_f32_16x16x32_f16 v[26:29], v[190:193], v[222:225], v[46:49]
	v_mfma_f32_16x16x32_f16 v[86:89], v[194:197], v[226:229], v[26:29]
	v_mfma_f32_16x16x32_f16 v[26:29], v[198:201], v[222:225], v[50:53]
	v_mfma_f32_16x16x32_f16 v[82:85], v[202:205], v[226:229], v[26:29]
	v_mfma_f32_16x16x32_f16 v[26:29], v[190:193], v[230:233], v[54:57]
	v_mfma_f32_16x16x32_f16 v[70:73], v[194:197], v[234:237], v[26:29]
	v_mfma_f32_16x16x32_f16 v[26:29], v[198:201], v[230:233], v[58:61]
	v_mfma_f32_16x16x32_f16 v[66:69], v[202:205], v[234:237], v[26:29]
	s_barrier
	s_setprio 0
	ds_read_b128 v[34:37], v215 offset:49152
	ds_read_b128 v[38:41], v215 offset:50176
	ds_read_b128 v[114:117], v215 offset:51200
	ds_read_b128 v[218:221], v215 offset:52224
	ds_read_b128 v[222:225], v215 offset:53248
	ds_read_b128 v[226:229], v215 offset:54272
	ds_read_b128 v[230:233], v215 offset:55296
	ds_read_b128 v[234:237], v215 offset:56320
	s_add_u32 m0, s35, 0x18000
	s_nop 0
	global_load_lds_dwordx4 v210, s[8:9]
	s_nop 0
	s_add_u32 m0, s35, 0x1a000
	s_nop 0
	global_load_lds_dwordx4 v212, s[8:9]
	s_add_u32 s8, s38, 0x40180
	s_addc_u32 s9, s39, 0
	s_add_u32 m0, s35, 0x1c000
	s_nop 0
	global_load_lds_dwordx4 v210, s[8:9]
	s_nop 0
	s_add_u32 m0, s35, 0x1e000
	s_nop 0
	global_load_lds_dwordx4 v212, s[8:9]
	s_nop 0
	s_add_u32 m0, s35, 0x8000
	s_nop 0
	global_load_lds_dwordx4 v1, s[6:7]
	s_nop 0
	s_add_u32 m0, s35, 0xa000
	s_nop 0
	global_load_lds_dwordx4 v211, s[6:7]
	s_waitcnt vmcnt(8)
	s_waitcnt lgkmcnt(0)
	s_barrier
	v_mfma_f32_16x16x32_f16 v[26:29], v[10:13], v[34:37], v[130:133]
	s_setprio 1
	v_mfma_f32_16x16x32_f16 v[62:65], v[14:17], v[38:41], v[26:29]
	v_mfma_f32_16x16x32_f16 v[26:29], v[22:25], v[38:41], v[146:149]
	v_mfma_f32_16x16x32_f16 v[58:61], v[18:21], v[34:37], v[26:29]
	v_mfma_f32_16x16x32_f16 v[26:29], v[10:13], v[114:117], v[150:153]
	v_mfma_f32_16x16x32_f16 v[46:49], v[14:17], v[218:221], v[26:29]
	v_mfma_f32_16x16x32_f16 v[26:29], v[22:25], v[218:221], v[154:157]
	v_mfma_f32_16x16x32_f16 v[42:45], v[18:21], v[114:117], v[26:29]
	v_mfma_f32_16x16x32_f16 v[26:29], v[10:13], v[222:225], v[158:161]
	v_mfma_f32_16x16x32_f16 v[30:33], v[14:17], v[226:229], v[26:29]
	v_mfma_f32_16x16x32_f16 v[2:5], v[14:17], v[234:237], v[2:5]
	v_mfma_f32_16x16x32_f16 v[14:17], v[10:13], v[230:233], v[2:5]
	v_mfma_f32_16x16x32_f16 v[2:5], v[18:21], v[230:233], v[6:9]
	v_mfma_f32_16x16x32_f16 v[10:13], v[22:25], v[234:237], v[2:5]
	v_mfma_f32_16x16x32_f16 v[26:29], v[22:25], v[226:229], v[162:165]
	v_mfma_f32_16x16x32_f16 v[26:29], v[18:21], v[222:225], v[26:29]
	v_mfma_f32_16x16x32_f16 v[2:5], v[190:193], v[34:37], v[166:169]
	v_mfma_f32_16x16x32_f16 v[54:57], v[194:197], v[38:41], v[2:5]
	v_mfma_f32_16x16x32_f16 v[2:5], v[202:205], v[38:41], v[170:173]
	v_mfma_f32_16x16x32_f16 v[50:53], v[198:201], v[34:37], v[2:5]
	v_mfma_f32_16x16x32_f16 v[2:5], v[190:193], v[114:117], v[174:177]
	v_mfma_f32_16x16x32_f16 v[38:41], v[194:197], v[218:221], v[2:5]
	v_mfma_f32_16x16x32_f16 v[2:5], v[202:205], v[218:221], v[178:181]
	v_mfma_f32_16x16x32_f16 v[34:37], v[198:201], v[114:117], v[2:5]
	v_mfma_f32_16x16x32_f16 v[2:5], v[190:193], v[222:225], v[182:185]
	v_mfma_f32_16x16x32_f16 v[22:25], v[194:197], v[226:229], v[2:5]
	v_mfma_f32_16x16x32_f16 v[2:5], v[202:205], v[226:229], v[118:121]
	v_mfma_f32_16x16x32_f16 v[18:21], v[198:201], v[222:225], v[2:5]
	v_mfma_f32_16x16x32_f16 v[2:5], v[190:193], v[230:233], v[186:189]
	v_mfma_f32_16x16x32_f16 v[6:9], v[194:197], v[234:237], v[2:5]
	v_mfma_f32_16x16x32_f16 v[2:5], v[202:205], v[234:237], v[122:125]
	v_mfma_f32_16x16x32_f16 v[2:5], v[198:201], v[230:233], v[2:5]
	s_barrier
	s_setprio 0
	s_mov_b32 s58, 0
	s_mov_b64 s[54:55], 0
	s_branch .LBB0_1165
; #define PG8_STAGE(bufoff, gbase, voff) do { if constexpr (ABL & 1) break; glds16s<(bufoff)>((voff)[0], (const void*)(gbase), ldsbw); glds16s<(bufoff) + 8192>((voff)[1], (const void*)(gbase), ldsbw); } while (0)
; #define PG8_LDA(dst, b, h) do { if constexpr (ABL & 4) break; _Pragma("unroll") for (int m = 0; m < 4; ++m) _Pragma("unroll") for (int k = 0; k < 2; ++k) dst[m][k] = *(const LAS f16x8*)(lds + PG8_SA(b, h) + aoff + m * 2048 + k * 1024); } while (0)
; #define PG8_LDB(dst, b, h) do { if constexpr (ABL & 4) break; _Pragma("unroll") for (int n = 0; n < 2; ++n) _Pragma("unroll") for (int k = 0; k < 2; ++k) dst[n][k] = *(const LAS f16x8*)(lds + PG8_SB(b, h) + boff + n * 2048 + k * 1024); } while (0)
; #define PG8_BAR __builtin_amdgcn_s_barrier()
;     ...
;         for (int t = 0; t < nt; t += 2) {
;             const bool last = (t == nt - 2);
;             const char* a1 = cA + (size_t)(t + 1) * kstep;
;             const char* a2 = last ? nA : cA + (size_t)(t + 2) * kstep; const char* b2 = last ? nB : cB + (size_t)(t + 2) * kstep;
;             const char* a3 = a2 + kstep; const char* b3 = b2 + kstep;
;             if (last && has_next) S.a_ready(nxt);
;             if constexpr (SP2) {
;             PG8_LDB(B0, 0, 0); PG8_LDB(B1, 0, 1); PG8_SCHED; PG8_LDA(At, 0, 0); PG8_STAGE(PG8_SA(1, 1), a1 + hstep, voffA);
;             PG8_WAIT_V(8); PG8_WAIT_L(0); PG8_BAR; PG8_MMAF(0, 0, At, B0); PG8_MMAF(0, 1, At, B1); PG8_BAR; PG8_SCHED;
;             const bool fin = last && !has_next;
;             PG8_LDA(At, 0, 1); if (!fin) { PG8_STAGE(PG8_SB(0, 0), b2, voffB); PG8_STAGE(PG8_SB(0, 1), b2 + hstep, voffB); PG8_STAGE(PG8_SA(0, 0), a2, voffA); }
;             if (!fin) PG8_WAIT_V(8); else PG8_WAIT_V(2); PG8_WAIT_L(0); PG8_BAR; PG8_MMAF(1, 0, At, B0); PG8_MMAF(1, 1, At, B1); PG8_BAR; PG8_SCHED;
;             PG8_LDB(B0, 1, 0); PG8_LDB(B1, 1, 1); PG8_SCHED; PG8_LDA(At, 1, 0); if (!fin) PG8_STAGE(PG8_SA(0, 1), a2 + hstep, voffA);
;             if (!fin) PG8_WAIT_V(8); else PG8_WAIT_V(0); PG8_WAIT_L(0); PG8_BAR; PG8_MMA(0, 0, At, B0); PG8_MMA(0, 1, At, B1); PG8_BAR; PG8_SCHED;
;             PG8_LDA(At, 1, 1); if (!fin) { PG8_STAGE(PG8_SB(1, 0), b3, voffB); PG8_STAGE(PG8_SB(1, 1), b3 + hstep, voffB); PG8_STAGE(PG8_SA(1, 0), a3, voffA); }
;             if (!fin) PG8_WAIT_V(8); PG8_WAIT_L(0); PG8_BAR; PG8_MMA(1, 0, At, B0); PG8_MMA(1, 1, At, B1); PG8_BAR; PG8_SCHED;
.LBB0_1164:
	s_waitcnt lgkmcnt(0)
	s_barrier
	v_mfma_f32_16x16x32_f16 v[62:65], v[158:161], v[186:189], v[62:65]
	s_setprio 1
	v_mfma_f32_16x16x32_f16 v[62:65], v[162:165], v[190:193], v[62:65]
	v_mfma_f32_16x16x32_f16 v[58:61], v[170:173], v[190:193], v[58:61]
	v_mfma_f32_16x16x32_f16 v[58:61], v[166:169], v[186:189], v[58:61]
	v_mfma_f32_16x16x32_f16 v[42:45], v[166:169], v[178:181], v[42:45]
	v_mfma_f32_16x16x32_f16 v[42:45], v[170:173], v[182:185], v[42:45]
	v_mfma_f32_16x16x32_f16 v[46:49], v[162:165], v[182:185], v[46:49]
	v_mfma_f32_16x16x32_f16 v[46:49], v[158:161], v[178:181], v[46:49]
	v_mfma_f32_16x16x32_f16 v[30:33], v[158:161], v[122:125], v[30:33]
	v_mfma_f32_16x16x32_f16 v[30:33], v[162:165], v[174:177], v[30:33]
	v_mfma_f32_16x16x32_f16 v[26:29], v[170:173], v[174:177], v[26:29]
	v_mfma_f32_16x16x32_f16 v[26:29], v[166:169], v[122:125], v[26:29]
	v_mfma_f32_16x16x32_f16 v[10:13], v[166:169], v[114:117], v[10:13]
	v_mfma_f32_16x16x32_f16 v[10:13], v[170:173], v[118:121], v[10:13]
	v_mfma_f32_16x16x32_f16 v[14:17], v[162:165], v[118:121], v[14:17]
	v_mfma_f32_16x16x32_f16 v[14:17], v[158:161], v[114:117], v[14:17]
	v_mfma_f32_16x16x32_f16 v[6:9], v[130:133], v[114:117], v[6:9]
	v_mfma_f32_16x16x32_f16 v[6:9], v[146:149], v[118:121], v[6:9]
	v_mfma_f32_16x16x32_f16 v[54:57], v[146:149], v[190:193], v[54:57]
	v_mfma_f32_16x16x32_f16 v[54:57], v[130:133], v[186:189], v[54:57]
	v_mfma_f32_16x16x32_f16 v[50:53], v[150:153], v[186:189], v[50:53]
	v_mfma_f32_16x16x32_f16 v[50:53], v[154:157], v[190:193], v[50:53]
	v_mfma_f32_16x16x32_f16 v[34:37], v[154:157], v[182:185], v[34:37]
	v_mfma_f32_16x16x32_f16 v[34:37], v[150:153], v[178:181], v[34:37]
	v_mfma_f32_16x16x32_f16 v[38:41], v[130:133], v[178:181], v[38:41]
	v_mfma_f32_16x16x32_f16 v[38:41], v[146:149], v[182:185], v[38:41]
	v_mfma_f32_16x16x32_f16 v[22:25], v[146:149], v[174:177], v[22:25]
	v_mfma_f32_16x16x32_f16 v[22:25], v[130:133], v[122:125], v[22:25]
	v_mfma_f32_16x16x32_f16 v[18:21], v[150:153], v[122:125], v[18:21]
	v_mfma_f32_16x16x32_f16 v[18:21], v[154:157], v[174:177], v[18:21]
	v_mfma_f32_16x16x32_f16 v[2:5], v[154:157], v[118:121], v[2:5]
	v_mfma_f32_16x16x32_f16 v[2:5], v[150:153], v[114:117], v[2:5]
	s_barrier
	s_setprio 0
	s_add_i32 s58, s58, 2
	s_add_u32 s54, s54, 0x100
	s_addc_u32 s55, s55, 0
	s_cmp_gt_u32 s58, 13
	s_cbranch_scc1 .LBB0_1175
.LBB0_1165:
	s_add_u32 s26, s36, s54
	s_addc_u32 s27, s37, s55
	ds_read_b128 v[158:161], v213
	ds_read_b128 v[162:165], v213 offset:1024
	ds_read_b128 v[166:169], v213 offset:2048
	ds_read_b128 v[170:173], v213 offset:3072
	ds_read_b128 v[130:133], v214
	ds_read_b128 v[146:149], v214 offset:1024
	ds_read_b128 v[150:153], v214 offset:2048
	ds_read_b128 v[154:157], v214 offset:3072
	s_add_u32 s24, s26, 0x200
	s_addc_u32 s25, s27, 0
	s_add_u32 s6, s38, s54
	s_addc_u32 s7, s39, s55
	s_add_u32 s59, s6, 0x200
	s_addc_u32 s60, s7, 0
	s_cmp_eq_u32 s58, 12
	s_cselect_b64 s[6:7], -1, 0
	s_and_b64 s[8:9], s[6:7], exec
	s_cselect_b32 s25, s45, s25
	s_cselect_b32 s24, s49, s24
	s_cselect_b32 s9, s47, s60
	s_cselect_b32 s8, s57, s59
	ds_read_b128 v[174:177], v215
	ds_read_b128 v[178:181], v215 offset:1024
	ds_read_b128 v[182:185], v215 offset:2048
	ds_read_b128 v[186:189], v215 offset:3072
	ds_read_b128 v[190:193], v215 offset:4096
	ds_read_b128 v[194:197], v215 offset:5120
	ds_read_b128 v[198:201], v215 offset:6144
	ds_read_b128 v[202:205], v215 offset:7168
	s_add_u32 s26, s26, 0x40180
	s_addc_u32 s27, s27, 0
	s_add_u32 m0, s35, 0xc000
	s_nop 0
	global_load_lds_dwordx4 v1, s[26:27]
	s_nop 0
	s_add_u32 m0, s35, 0xe000
	s_nop 0
	global_load_lds_dwordx4 v211, s[26:27]
	s_waitcnt vmcnt(8)
	s_waitcnt lgkmcnt(0)
	s_barrier
	v_mfma_f32_16x16x32_f16 v[114:117], v[158:161], v[174:177], v[142:145]
	s_setprio 1
	v_mfma_f32_16x16x32_f16 v[114:117], v[162:165], v[178:181], v[114:117]
	v_mfma_f32_16x16x32_f16 v[118:121], v[170:173], v[178:181], v[138:141]
	v_mfma_f32_16x16x32_f16 v[118:121], v[166:169], v[174:177], v[118:121]
	v_mfma_f32_16x16x32_f16 v[106:109], v[166:169], v[182:185], v[106:109]
	v_mfma_f32_16x16x32_f16 v[106:109], v[170:173], v[186:189], v[106:109]
	v_mfma_f32_16x16x32_f16 v[110:113], v[162:165], v[186:189], v[110:113]
	v_mfma_f32_16x16x32_f16 v[110:113], v[158:161], v[182:185], v[110:113]
	v_mfma_f32_16x16x32_f16 v[94:97], v[158:161], v[190:193], v[94:97]
	v_mfma_f32_16x16x32_f16 v[94:97], v[162:165], v[194:197], v[94:97]
	v_mfma_f32_16x16x32_f16 v[90:93], v[170:173], v[194:197], v[90:93]
	v_mfma_f32_16x16x32_f16 v[90:93], v[166:169], v[190:193], v[90:93]
	v_mfma_f32_16x16x32_f16 v[74:77], v[166:169], v[198:201], v[74:77]
	v_mfma_f32_16x16x32_f16 v[74:77], v[170:173], v[202:205], v[74:77]
	v_mfma_f32_16x16x32_f16 v[78:81], v[162:165], v[202:205], v[78:81]
	v_mfma_f32_16x16x32_f16 v[78:81], v[158:161], v[198:201], v[78:81]
	v_mfma_f32_16x16x32_f16 v[70:73], v[130:133], v[198:201], v[70:73]
	v_mfma_f32_16x16x32_f16 v[70:73], v[146:149], v[202:205], v[70:73]
	v_mfma_f32_16x16x32_f16 v[122:125], v[146:149], v[178:181], v[134:137]
	v_mfma_f32_16x16x32_f16 v[122:125], v[130:133], v[174:177], v[122:125]
	v_mfma_f32_16x16x32_f16 v[126:129], v[150:153], v[174:177], v[126:129]
	v_mfma_f32_16x16x32_f16 v[126:129], v[154:157], v[178:181], v[126:129]
	v_mfma_f32_16x16x32_f16 v[98:101], v[154:157], v[186:189], v[98:101]
	v_mfma_f32_16x16x32_f16 v[98:101], v[150:153], v[182:185], v[98:101]
	v_mfma_f32_16x16x32_f16 v[102:105], v[130:133], v[182:185], v[102:105]
	v_mfma_f32_16x16x32_f16 v[102:105], v[146:149], v[186:189], v[102:105]
	v_mfma_f32_16x16x32_f16 v[86:89], v[146:149], v[194:197], v[86:89]
	v_mfma_f32_16x16x32_f16 v[86:89], v[130:133], v[190:193], v[86:89]
	v_mfma_f32_16x16x32_f16 v[82:85], v[150:153], v[190:193], v[82:85]
	v_mfma_f32_16x16x32_f16 v[82:85], v[154:157], v[194:197], v[82:85]
	v_mfma_f32_16x16x32_f16 v[66:69], v[154:157], v[202:205], v[66:69]
	v_mfma_f32_16x16x32_f16 v[66:69], v[150:153], v[198:201], v[66:69]
	s_barrier
	s_setprio 0
	ds_read_b128 v[186:189], v215 offset:16384
	ds_read_b128 v[190:193], v215 offset:17408
	ds_read_b128 v[178:181], v215 offset:18432
	ds_read_b128 v[182:185], v215 offset:19456
	ds_read_b128 v[142:145], v215 offset:20480
	ds_read_b128 v[174:177], v215 offset:21504
	ds_read_b128 v[134:137], v215 offset:22528
	ds_read_b128 v[138:141], v215 offset:23552
	s_and_b64 s[6:7], s[2:3], s[6:7]
	s_mov_b64 s[26:27], -1
	s_and_b64 vcc, exec, s[6:7]
	s_cbranch_vccnz .LBB0_1167
	s_add_u32 m0, s35, 0x10000
	s_nop 0
	global_load_lds_dwordx4 v210, s[8:9]
	s_nop 0
	s_add_u32 m0, s35, 0x12000
	s_nop 0
	global_load_lds_dwordx4 v212, s[8:9]
	s_add_u32 s26, s8, 0x40000
	s_addc_u32 s27, s9, 0
	s_add_u32 m0, s35, 0x14000
	s_nop 0
	global_load_lds_dwordx4 v210, s[26:27]
	s_nop 0
	s_add_u32 m0, s35, 0x16000
	s_nop 0
	global_load_lds_dwordx4 v212, s[26:27]
	s_mov_b64 s[26:27], 0
	s_add_u32 m0, s35, 0
	s_nop 0
	global_load_lds_dwordx4 v1, s[24:25]
	s_nop 0
	s_add_u32 m0, s35, 0x2000
	s_nop 0
	global_load_lds_dwordx4 v211, s[24:25]
	s_waitcnt vmcnt(8)

; #define PG8_STAGE(bufoff, gbase, voff) do { if constexpr (ABL & 1) break; glds16s<(bufoff)>((voff)[0], (const void*)(gbase), ldsbw); glds16s<(bufoff) + 8192>((voff)[1], (const void*)(gbase), ldsbw); } while (0)
; #define PG8_LDA(dst, b, h) do { if constexpr (ABL & 4) break; _Pragma("unroll") for (int m = 0; m < 4; ++m) _Pragma("unroll") for (int k = 0; k < 2; ++k) dst[m][k] = *(const LAS f16x8*)(lds + PG8_SA(b, h) + aoff + m * 2048 + k * 1024); } while (0)
; #define PG8_LDB(dst, b, h) do { if constexpr (ABL & 4) break; _Pragma("unroll") for (int n = 0; n < 2; ++n) _Pragma("unroll") for (int k = 0; k < 2; ++k) dst[n][k] = *(const LAS f16x8*)(lds + PG8_SB(b, h) + boff + n * 2048 + k * 1024); } while (0)
; #define PG8_MMA(ai, bj, At, Bt) do { if constexpr (ABL & 2) break; __builtin_amdgcn_s_setprio(1); _Pragma("unroll") for (int m = 0; m < 4; ++m) _Pragma("unroll") for (int n = 0; n < 2; ++n) _Pragma("unroll") for (int k = 0; k < 2; ++k) \
;         acc[ai][bj][m][n] = __builtin_amdgcn_mfma_f32_16x16x32_f16(Bt[n][k], At[m][k], acc[ai][bj][m][n], 0, 0, 0); __builtin_amdgcn_s_setprio(0); } while (0)
; #define PG8_MMAF(ai, bj, At, Bt) do { if (t == 0) PG8_MMA0(ai, bj, At, Bt); else PG8_MMA(ai, bj, At, Bt); } while (0)
; #define PG8_WAIT_V(n) asm volatile("s_waitcnt vmcnt(" #n ")" ::: "memory")
; #define PG8_WAIT_L(n) asm volatile("s_waitcnt lgkmcnt(" #n ")" ::: "memory")
; #define PG8_BAR __builtin_amdgcn_s_barrier()
; #define PG8_SCHED __builtin_amdgcn_sched_barrier(0)
;     ...
;             if (!fin) PG8_WAIT_V(8); else PG8_WAIT_V(2); PG8_WAIT_L(0); PG8_BAR; PG8_MMAF(1, 0, At, B0); PG8_MMAF(1, 1, At, B1); PG8_BAR; PG8_SCHED;
;             PG8_LDB(B0, 1, 0); PG8_LDB(B1, 1, 1); PG8_SCHED; PG8_LDA(At, 1, 0); if (!fin) PG8_STAGE(PG8_SA(0, 1), a2 + hstep, voffA);
;             if (!fin) PG8_WAIT_V(8); else PG8_WAIT_V(0); PG8_WAIT_L(0); PG8_BAR; PG8_MMA(0, 0, At, B0); PG8_MMA(0, 1, At, B1); PG8_BAR; PG8_SCHED;
.LBB0_1169:
	s_waitcnt lgkmcnt(0)
	s_xor_b64 s[26:27], s[6:7], -1
	s_barrier
	v_mfma_f32_16x16x32_f16 v[62:65], v[158:161], v[186:189], v[62:65]
	s_setprio 1
	v_mfma_f32_16x16x32_f16 v[62:65], v[162:165], v[190:193], v[62:65]
	v_mfma_f32_16x16x32_f16 v[58:61], v[170:173], v[190:193], v[58:61]
	v_mfma_f32_16x16x32_f16 v[58:61], v[166:169], v[186:189], v[58:61]
	v_mfma_f32_16x16x32_f16 v[42:45], v[166:169], v[178:181], v[42:45]
	v_mfma_f32_16x16x32_f16 v[42:45], v[170:173], v[182:185], v[42:45]
	v_mfma_f32_16x16x32_f16 v[46:49], v[162:165], v[182:185], v[46:49]
	v_mfma_f32_16x16x32_f16 v[46:49], v[158:161], v[178:181], v[46:49]
	v_mfma_f32_16x16x32_f16 v[30:33], v[158:161], v[142:145], v[30:33]
	v_mfma_f32_16x16x32_f16 v[30:33], v[162:165], v[174:177], v[30:33]
	v_mfma_f32_16x16x32_f16 v[26:29], v[170:173], v[174:177], v[26:29]
	v_mfma_f32_16x16x32_f16 v[26:29], v[166:169], v[142:145], v[26:29]
	v_mfma_f32_16x16x32_f16 v[10:13], v[166:169], v[134:137], v[10:13]
	v_mfma_f32_16x16x32_f16 v[10:13], v[170:173], v[138:141], v[10:13]
	v_mfma_f32_16x16x32_f16 v[14:17], v[162:165], v[138:141], v[14:17]
	v_mfma_f32_16x16x32_f16 v[14:17], v[158:161], v[134:137], v[14:17]
	v_mfma_f32_16x16x32_f16 v[6:9], v[130:133], v[134:137], v[6:9]
	v_mfma_f32_16x16x32_f16 v[6:9], v[146:149], v[138:141], v[6:9]
	v_mfma_f32_16x16x32_f16 v[54:57], v[146:149], v[190:193], v[54:57]
	v_mfma_f32_16x16x32_f16 v[54:57], v[130:133], v[186:189], v[54:57]
	v_mfma_f32_16x16x32_f16 v[50:53], v[150:153], v[186:189], v[50:53]
	v_mfma_f32_16x16x32_f16 v[50:53], v[154:157], v[190:193], v[50:53]
	v_mfma_f32_16x16x32_f16 v[34:37], v[154:157], v[182:185], v[34:37]
	v_mfma_f32_16x16x32_f16 v[34:37], v[150:153], v[178:181], v[34:37]
	v_mfma_f32_16x16x32_f16 v[38:41], v[130:133], v[178:181], v[38:41]
	v_mfma_f32_16x16x32_f16 v[38:41], v[146:149], v[182:185], v[38:41]
	v_mfma_f32_16x16x32_f16 v[22:25], v[146:149], v[174:177], v[22:25]
	v_mfma_f32_16x16x32_f16 v[22:25], v[130:133], v[142:145], v[22:25]
	v_mfma_f32_16x16x32_f16 v[18:21], v[150:153], v[142:145], v[18:21]
	v_mfma_f32_16x16x32_f16 v[18:21], v[154:157], v[174:177], v[18:21]
	v_mfma_f32_16x16x32_f16 v[2:5], v[154:157], v[138:141], v[2:5]
	v_mfma_f32_16x16x32_f16 v[2:5], v[150:153], v[134:137], v[2:5]
	s_barrier
	s_setprio 0
	ds_read_b128 v[158:161], v216
	ds_read_b128 v[162:165], v216 offset:1024
	ds_read_b128 v[166:169], v216 offset:2048
	ds_read_b128 v[170:173], v216 offset:3072
	ds_read_b128 v[130:133], v217
	ds_read_b128 v[146:149], v217 offset:1024
	ds_read_b128 v[150:153], v217 offset:2048
	ds_read_b128 v[154:157], v217 offset:3072
	ds_read_b128 v[198:201], v215 offset:32768
	ds_read_b128 v[202:205], v215 offset:33792
	ds_read_b128 v[190:193], v215 offset:34816
	ds_read_b128 v[194:197], v215 offset:35840
	ds_read_b128 v[182:185], v215 offset:36864
	ds_read_b128 v[186:189], v215 offset:37888
	ds_read_b128 v[174:177], v215 offset:38912
	ds_read_b128 v[178:181], v215 offset:39936
	v_cndmask_b32_e64 v134, 0, 1, s[26:27]
	v_cmp_ne_u32_e64 s[6:7], 1, v134
	s_andn2_b64 vcc, exec, s[26:27]
	s_mov_b64 s[26:27], -1
	s_cbranch_vccnz .LBB0_1171
	s_add_u32 s26, s24, 0x40000
	s_addc_u32 s27, s25, 0
	s_add_u32 m0, s35, 0x4000
	s_nop 0
	global_load_lds_dwordx4 v1, s[26:27]
	s_nop 0
	s_add_u32 m0, s35, 0x6000
	s_nop 0
	global_load_lds_dwordx4 v211, s[26:27]
	s_waitcnt vmcnt(8)
	s_mov_b64 s[26:27], 0

; #define PG8_STAGE(bufoff, gbase, voff) do { if constexpr (ABL & 1) break; glds16s<(bufoff)>((voff)[0], (const void*)(gbase), ldsbw); glds16s<(bufoff) + 8192>((voff)[1], (const void*)(gbase), ldsbw); } while (0)
; #define PG8_LDA(dst, b, h) do { if constexpr (ABL & 4) break; _Pragma("unroll") for (int m = 0; m < 4; ++m) _Pragma("unroll") for (int k = 0; k < 2; ++k) dst[m][k] = *(const LAS f16x8*)(lds + PG8_SA(b, h) + aoff + m * 2048 + k * 1024); } while (0)
; #define PG8_MMA(ai, bj, At, Bt) do { if constexpr (ABL & 2) break; __builtin_amdgcn_s_setprio(1); _Pragma("unroll") for (int m = 0; m < 4; ++m) _Pragma("unroll") for (int n = 0; n < 2; ++n) _Pragma("unroll") for (int k = 0; k < 2; ++k) \
;         acc[ai][bj][m][n] = __builtin_amdgcn_mfma_f32_16x16x32_f16(Bt[n][k], At[m][k], acc[ai][bj][m][n], 0, 0, 0); __builtin_amdgcn_s_setprio(0); } while (0)
; #define PG8_WAIT_V(n) asm volatile("s_waitcnt vmcnt(" #n ")" ::: "memory")
; #define PG8_WAIT_L(n) asm volatile("s_waitcnt lgkmcnt(" #n ")" ::: "memory")
; #define PG8_BAR __builtin_amdgcn_s_barrier()
; #define PG8_SCHED __builtin_amdgcn_sched_barrier(0)
;     ...
;             if (!fin) PG8_WAIT_V(8); else PG8_WAIT_V(0); PG8_WAIT_L(0); PG8_BAR; PG8_MMA(0, 0, At, B0); PG8_MMA(0, 1, At, B1); PG8_BAR; PG8_SCHED;
;             PG8_LDA(At, 1, 1); if (!fin) { PG8_STAGE(PG8_SB(1, 0), b3, voffB); PG8_STAGE(PG8_SB(1, 1), b3 + hstep, voffB); PG8_STAGE(PG8_SA(1, 0), a3, voffA); }
;             if (!fin) PG8_WAIT_V(8); PG8_WAIT_L(0); PG8_BAR; PG8_MMA(1, 0, At, B0); PG8_MMA(1, 1, At, B1); PG8_BAR; PG8_SCHED;
.LBB0_1173:
	s_waitcnt lgkmcnt(0)
	s_barrier
	v_mfma_f32_16x16x32_f16 v[114:117], v[158:161], v[198:201], v[114:117]
	s_setprio 1
	v_mfma_f32_16x16x32_f16 v[142:145], v[162:165], v[202:205], v[114:117]
	v_mfma_f32_16x16x32_f16 v[114:117], v[170:173], v[202:205], v[118:121]
	v_mfma_f32_16x16x32_f16 v[138:141], v[166:169], v[198:201], v[114:117]
	v_mfma_f32_16x16x32_f16 v[106:109], v[166:169], v[190:193], v[106:109]
	v_mfma_f32_16x16x32_f16 v[106:109], v[170:173], v[194:197], v[106:109]
	v_mfma_f32_16x16x32_f16 v[110:113], v[162:165], v[194:197], v[110:113]
	v_mfma_f32_16x16x32_f16 v[110:113], v[158:161], v[190:193], v[110:113]
	v_mfma_f32_16x16x32_f16 v[94:97], v[158:161], v[182:185], v[94:97]
	v_mfma_f32_16x16x32_f16 v[94:97], v[162:165], v[186:189], v[94:97]
	v_mfma_f32_16x16x32_f16 v[90:93], v[170:173], v[186:189], v[90:93]
	v_mfma_f32_16x16x32_f16 v[90:93], v[166:169], v[182:185], v[90:93]
	v_mfma_f32_16x16x32_f16 v[74:77], v[166:169], v[174:177], v[74:77]
	v_mfma_f32_16x16x32_f16 v[74:77], v[170:173], v[178:181], v[74:77]
	v_mfma_f32_16x16x32_f16 v[78:81], v[162:165], v[178:181], v[78:81]
	v_mfma_f32_16x16x32_f16 v[78:81], v[158:161], v[174:177], v[78:81]
	v_mfma_f32_16x16x32_f16 v[70:73], v[130:133], v[174:177], v[70:73]
	v_mfma_f32_16x16x32_f16 v[70:73], v[146:149], v[178:181], v[70:73]
	v_mfma_f32_16x16x32_f16 v[114:117], v[146:149], v[202:205], v[122:125]
	v_mfma_f32_16x16x32_f16 v[134:137], v[130:133], v[198:201], v[114:117]
	v_mfma_f32_16x16x32_f16 v[114:117], v[150:153], v[198:201], v[126:129]
	v_mfma_f32_16x16x32_f16 v[126:129], v[154:157], v[202:205], v[114:117]
	v_mfma_f32_16x16x32_f16 v[98:101], v[154:157], v[194:197], v[98:101]
	v_mfma_f32_16x16x32_f16 v[98:101], v[150:153], v[190:193], v[98:101]
	v_mfma_f32_16x16x32_f16 v[102:105], v[130:133], v[190:193], v[102:105]
	v_mfma_f32_16x16x32_f16 v[102:105], v[146:149], v[194:197], v[102:105]
	v_mfma_f32_16x16x32_f16 v[86:89], v[146:149], v[186:189], v[86:89]
	v_mfma_f32_16x16x32_f16 v[86:89], v[130:133], v[182:185], v[86:89]
	v_mfma_f32_16x16x32_f16 v[82:85], v[150:153], v[182:185], v[82:85]
	v_mfma_f32_16x16x32_f16 v[82:85], v[154:157], v[186:189], v[82:85]
	v_mfma_f32_16x16x32_f16 v[66:69], v[154:157], v[178:181], v[66:69]
	v_mfma_f32_16x16x32_f16 v[66:69], v[150:153], v[174:177], v[66:69]
	s_barrier
	s_setprio 0
	ds_read_b128 v[186:189], v215 offset:49152
	ds_read_b128 v[190:193], v215 offset:50176
	ds_read_b128 v[178:181], v215 offset:51200
	ds_read_b128 v[182:185], v215 offset:52224
	ds_read_b128 v[122:125], v215 offset:53248
	ds_read_b128 v[174:177], v215 offset:54272
	ds_read_b128 v[114:117], v215 offset:55296
	ds_read_b128 v[118:121], v215 offset:56320
	s_and_b64 vcc, exec, s[6:7]
	s_cbranch_vccnz .LBB0_1164
	s_add_u32 s6, s24, 0x80
	s_addc_u32 s7, s25, 0
	s_add_u32 s24, s8, 0x80
	s_addc_u32 s25, s9, 0
	s_add_u32 m0, s35, 0x18000
	s_nop 0
	global_load_lds_dwordx4 v210, s[24:25]
	s_nop 0
	s_add_u32 m0, s35, 0x1a000
	s_nop 0
	global_load_lds_dwordx4 v212, s[24:25]
	s_add_u32 s8, s8, 0x40080
	s_addc_u32 s9, s9, 0
	s_add_u32 m0, s35, 0x1c000
	s_nop 0
	global_load_lds_dwordx4 v210, s[8:9]
	s_nop 0
	s_add_u32 m0, s35, 0x1e000
	s_nop 0
	global_load_lds_dwordx4 v212, s[8:9]
	s_nop 0
	s_add_u32 m0, s35, 0x8000
	s_nop 0
	global_load_lds_dwordx4 v1, s[6:7]
	s_nop 0
	s_add_u32 m0, s35, 0xa000
	s_nop 0
	global_load_lds_dwordx4 v211, s[6:7]
	s_waitcnt vmcnt(8)
	s_branch .LBB0_1164
